# MFMA/LDS interleave: next tile's Q/K fragment ds_reads issued right after the barrier, under the five tail PV MFMAs of the attention-A loop
# baseline (speedup 1.0000x reference)
; DI float bflo(unsigned u) { return __uint_as_float(u << 16); }
; DI float bfhi(unsigned u) { return __uint_as_float(u & 0xffff0000u); }
; __device__ __forceinline__ void attn_item_A(const Params& p, int layer, int head, int q0u, char* lds) {
;     ...
;   {
;     const u16* qg = P + (size_t)(q0u + wid * 32 + r) * LDP + qcol + 8 * h;
;     float nA = 0.f, nB = 0.f;
; #pragma unroll
;     for (int s = 0; s < 8; ++s) {
;       const u32x4 q = *(const u32x4*)(qg + 16 * s);
;       *(u32x4*)(Qs + s * 1024) = q;
;       float ss = 0.f;
; #pragma unroll
;       for (int j = 0; j < 4; ++j) { const float a = bflo(q[j]), b = bfhi(q[j]); ss += a * a + b * b; }
;       if (s < 4) nA += ss; else nB += ss;
;     }
;     nA += __shfl_xor(nA, 32); nB += __shfl_xor(nB, 32);
;     const float* km = (const float*)(p.ws + OFF_LAM) + 8 + layer * 24 + head * 2;
;     bA = sqrtf(nA) * km[0] * CS; bB = sqrtf(nB) * km[1] * CS;
;   }
.LBB0_1570:
	v_mov_b32_e32 v34, v211
	s_lshl_b32 s0, s36, 7
	v_ashrrev_i32_e32 v2, 6, v34
	v_and_b32_e32 v12, 31, v34
	v_lshl_add_u32 v191, v2, 5, s82
	v_add_u32_e32 v0, v191, v12
	v_mov_b64_e32 v[8:9], s[12:13]
	v_mad_i64_i32 v[0:1], s[4:5], v0, s63, v[8:9]
	s_ashr_i32 s1, s0, 31
	v_lshrrev_b32_e32 v3, 2, v34
	s_lshl_b64 s[4:5], s[0:1], 1
	v_and_b32_e32 v13, 8, v3
	v_lshl_add_u64 v[0:1], v[0:1], 0, s[4:5]
	v_lshlrev_b32_e32 v164, 1, v13
	v_lshl_add_u64 v[10:11], v[0:1], 0, v[164:165]
	global_load_dwordx4 v[14:17], v[10:11], off
	global_load_dwordx4 v[18:21], v[10:11], off offset:32
	global_load_dwordx4 v[22:25], v[10:11], off offset:64
	global_load_dwordx4 v[26:29], v[10:11], off offset:96
	v_lshlrev_b32_e32 v193, 13, v2
	global_load_dwordx4 v[30:33], v[10:11], off offset:128
	global_load_dwordx4 v[0:3], v[10:11], off offset:160
	global_load_dwordx4 v[4:7], v[10:11], off offset:192
	v_and_b32_e32 v167, 63, v34
	v_lshlrev_b32_e32 v194, 4, v167
	v_or_b32_e32 v36, v193, v194
	s_lshl_b32 s6, s36, 1
	s_ashr_i32 s7, s6, 31
	s_lshl_b64 s[6:7], s[6:7], 2
	s_add_u32 s6, s19, s6
	s_addc_u32 s7, s29, s7
	v_ashrrev_i32_e32 v195, 3, v34
	v_cmp_lt_i32_e32 vcc, v186, v188
	s_cmpk_lt_u32 s82, 0x100
	v_mad_u32_u24 v196, v12, s65, v164
	s_mov_b32 s8, 0
	s_waitcnt vmcnt(6)
	ds_write_b128 v36, v[14:17] offset:37888
	v_lshlrev_b32_e32 v35, 16, v14
	v_and_b32_e32 v14, 0xffff0000, v14
	v_lshlrev_b32_e32 v37, 16, v15
	v_and_b32_e32 v15, 0xffff0000, v15
	s_waitcnt vmcnt(5)
	ds_write_b128 v36, v[18:21] offset:38912
	v_lshlrev_b32_e32 v40, 16, v18
	v_and_b32_e32 v18, 0xffff0000, v18
	v_lshlrev_b32_e32 v41, 16, v19
	v_and_b32_e32 v19, 0xffff0000, v19
	v_lshlrev_b32_e32 v38, 16, v16
	v_and_b32_e32 v16, 0xffff0000, v16
	v_lshlrev_b32_e32 v42, 16, v20
	v_and_b32_e32 v20, 0xffff0000, v20
	v_mul_f32_e32 v14, v14, v14
	v_mul_f32_e32 v15, v15, v15
	v_mul_f32_e32 v18, v18, v18
	v_mul_f32_e32 v19, v19, v19
	v_lshlrev_b32_e32 v39, 16, v17
	v_and_b32_e32 v17, 0xffff0000, v17
	v_lshlrev_b32_e32 v43, 16, v21
	v_and_b32_e32 v21, 0xffff0000, v21
	s_waitcnt vmcnt(4)
	ds_write_b128 v36, v[22:25] offset:39936
	v_lshlrev_b32_e32 v44, 16, v22
	v_and_b32_e32 v22, 0xffff0000, v22
	v_lshlrev_b32_e32 v45, 16, v23
	v_and_b32_e32 v23, 0xffff0000, v23
	v_mul_f32_e32 v16, v16, v16
	v_mul_f32_e32 v20, v20, v20
	v_fmac_f32_e32 v14, v35, v35
	v_fmac_f32_e32 v15, v37, v37
	v_fmac_f32_e32 v18, v40, v40
	v_fmac_f32_e32 v19, v41, v41
	v_lshlrev_b32_e32 v46, 16, v24
	v_and_b32_e32 v24, 0xffff0000, v24
	v_mul_f32_e32 v17, v17, v17
	v_mul_f32_e32 v21, v21, v21
	v_mul_f32_e32 v22, v22, v22
	v_mul_f32_e32 v23, v23, v23
	v_fmac_f32_e32 v16, v38, v38
	v_fmac_f32_e32 v20, v42, v42
	v_add_f32_e32 v14, v14, v15
	v_add_f32_e32 v15, v18, v19
	v_lshlrev_b32_e32 v47, 16, v25
	v_and_b32_e32 v25, 0xffff0000, v25
	v_mul_f32_e32 v24, v24, v24
	v_fmac_f32_e32 v17, v39, v39
	v_fmac_f32_e32 v21, v43, v43
	v_fmac_f32_e32 v22, v44, v44
	v_fmac_f32_e32 v23, v45, v45
	v_add_f32_e32 v14, v16, v14
	v_add_f32_e32 v15, v20, v15
	v_mul_f32_e32 v25, v25, v25
	v_fmac_f32_e32 v24, v46, v46
	v_add_f32_e32 v18, v22, v23
	v_add_f32_e32 v14, v17, v14
	v_add_f32_e32 v15, v21, v15
	s_waitcnt vmcnt(3)
	ds_write_b128 v36, v[26:29] offset:40960
	v_lshlrev_b32_e32 v48, 16, v26
	v_and_b32_e32 v26, 0xffff0000, v26
	v_fmac_f32_e32 v25, v47, v47
	v_add_f32_e32 v16, v24, v18
	v_add_f32_e32 v14, v14, v15
	v_and_b32_e32 v15, 0xffff0000, v27
	v_lshlrev_b32_e32 v49, 16, v27
	v_mul_f32_e32 v26, v26, v26
	v_add_f32_e32 v16, v25, v16
	v_mul_f32_e32 v15, v15, v15
	v_and_b32_e32 v17, 0xffff0000, v28
	v_fmac_f32_e32 v26, v48, v48
	v_add_f32_e32 v14, v14, v16
	v_fmac_f32_e32 v15, v49, v49
	v_lshlrev_b32_e32 v16, 16, v28
	v_mul_f32_e32 v17, v17, v17
	v_add_f32_e32 v15, v26, v15
	v_fmac_f32_e32 v17, v16, v16
	v_add_f32_e32 v15, v17, v15
	v_and_b32_e32 v17, 0xffff0000, v29
	v_lshlrev_b32_e32 v16, 16, v29
	v_mul_f32_e32 v17, v17, v17
	v_fmac_f32_e32 v17, v16, v16
	v_add_f32_e32 v15, v17, v15
	v_add_f32_e32 v37, v14, v15
	s_waitcnt vmcnt(2)
	v_and_b32_e32 v15, 0xffff0000, v30
	v_lshlrev_b32_e32 v14, 16, v30
	v_mul_f32_e32 v18, v15, v15
	v_fmac_f32_e32 v18, v14, v14
	global_load_dwordx4 v[14:17], v[10:11], off offset:224
	v_and_b32_e32 v20, 0xffff0000, v31
	ds_write_b128 v36, v[30:33] offset:41984
	v_lshlrev_b32_e32 v19, 16, v31
	global_load_dwordx2 v[30:31], v165, s[6:7]
	v_mul_f32_e32 v10, v20, v20
	v_fmac_f32_e32 v10, v19, v19
	v_add_f32_e32 v10, v18, v10
	v_and_b32_e32 v18, 0xffff0000, v32
	v_lshlrev_b32_e32 v11, 16, v32
	v_mul_f32_e32 v18, v18, v18
	v_fmac_f32_e32 v18, v11, v11
	v_add_f32_e32 v10, v18, v10
	v_and_b32_e32 v18, 0xffff0000, v33
	v_lshlrev_b32_e32 v11, 16, v33
	v_mul_f32_e32 v18, v18, v18
	v_fmac_f32_e32 v18, v11, v11
	v_add_f32_e32 v10, v18, v10
	s_waitcnt vmcnt(3)
	v_and_b32_e32 v18, 0xffff0000, v0
	v_lshlrev_b32_e32 v11, 16, v0
	v_mul_f32_e32 v18, v18, v18
	v_and_b32_e32 v19, 0xffff0000, v1
	v_fmac_f32_e32 v18, v11, v11
	v_lshlrev_b32_e32 v11, 16, v1
	v_mul_f32_e32 v19, v19, v19
	v_fmac_f32_e32 v19, v11, v11
	v_add_f32_e32 v11, v18, v19
	v_and_b32_e32 v19, 0xffff0000, v2
	v_lshlrev_b32_e32 v18, 16, v2
	v_mul_f32_e32 v19, v19, v19
	v_fmac_f32_e32 v19, v18, v18
	v_add_f32_e32 v11, v19, v11
	v_and_b32_e32 v19, 0xffff0000, v3
	v_lshlrev_b32_e32 v18, 16, v3
	v_mul_f32_e32 v19, v19, v19
	v_fmac_f32_e32 v19, v18, v18
	v_add_f32_e32 v11, v19, v11
	v_add_f32_e32 v38, v10, v11
	s_waitcnt vmcnt(2)
; __device__ __forceinline__ void attn_item_A(const Params& p, int layer, int head, int q0u, char* lds) {
;     ...
;     nA += __shfl_xor(nA, 32); nB += __shfl_xor(nB, 32);
;     const float* km = (const float*)(p.ws + OFF_LAM) + 8 + layer * 24 + head * 2;
;     bA = sqrtf(nA) * km[0] * CS; bB = sqrtf(nB) * km[1] * CS;
;   }
;   const int srow = tid >> 3, sseg = (tid & 7) * 16;
;   const u16* VTg = (const u16*)(p.ws + OFF_VT) + (size_t)(head * 128 + (tid >> 1)) * LDVT + (tid & 1) * 16;
;   float lA = 0.f, lB = 0.f;
;   f32x16 o1[4], o2[4];
; #pragma unroll
;   for (int d = 0; d < 4; ++d)
; #pragma unroll
;     for (int e = 0; e < 16; ++e) { o1[d][e] = 0.f; o2[d][e] = 0.f; }
;   u32x4 rk0, rk1, rv0, rv1;
;   const u16* gnext;
;   ATT_LOADK(0); ATT_LOADV(0);
;   ATT_STOREK(0); ATT_STOREV(0);
;   __syncthreads();
	v_and_b32_e32 v11, 0xffff0000, v4
	v_lshlrev_b32_e32 v10, 16, v4
	v_mul_f32_e32 v11, v11, v11
	v_and_b32_e32 v18, 0xffff0000, v5
	v_fmac_f32_e32 v11, v10, v10
	v_lshlrev_b32_e32 v10, 16, v5
	v_mul_f32_e32 v18, v18, v18
	v_fmac_f32_e32 v18, v10, v10
	v_add_f32_e32 v10, v11, v18
	v_and_b32_e32 v18, 0xffff0000, v6
	v_lshlrev_b32_e32 v11, 16, v6
	v_mul_f32_e32 v18, v18, v18
	v_fmac_f32_e32 v18, v11, v11
	v_ashrrev_i32_e32 v42, 1, v34
	v_lshlrev_b32_e32 v24, 5, v34
	v_add_f32_e32 v39, v18, v10
	v_add_u32_e32 v18, s0, v42
	v_mov_b64_e32 v[10:11], s[14:15]
	v_mad_i64_i32 v[8:9], s[0:1], v195, s63, v[8:9]
	v_and_b32_e32 v32, 0xe0, v24
	v_mov_b32_e32 v33, v165
	v_mad_i64_i32 v[22:23], s[0:1], v18, s64, v[10:11]
	v_lshl_add_u64 v[8:9], v[8:9], 0, v[32:33]
	v_and_b32_e32 v34, 32, v24
	v_mov_b32_e32 v35, v165
	v_lshl_add_u64 v[18:19], v[8:9], 0, s[4:5]
	v_lshl_add_u64 v[170:171], v[22:23], 0, v[34:35]
	global_load_dwordx4 v[8:11], v[18:19], off offset:1040
	s_nop 0
	global_load_dwordx4 v[18:21], v[18:19], off offset:1024
	s_nop 0
	global_load_dwordx4 v[22:25], v[170:171], off offset:16
	global_load_dwordx4 v[26:29], v[170:171], off
	v_and_b32_e32 v41, 0xffff0000, v7
	v_lshlrev_b32_e32 v40, 16, v7
	v_mul_f32_e32 v35, v41, v41
	v_fmac_f32_e32 v35, v40, v40
	v_add_f32_e32 v35, v35, v39
	v_add_f32_e32 v35, v38, v35
	ds_write_b128 v36, v[0:3] offset:43008
	ds_write_b128 v36, v[4:7] offset:44032
	s_waitcnt vmcnt(5)
	ds_write_b128 v36, v[14:17] offset:45056
	s_mov_b32 s6, 32
	v_and_b32_e32 v39, 0xffff0000, v14
	v_lshlrev_b32_e32 v38, 16, v14
	v_mul_f32_e32 v39, v39, v39
	v_and_b32_e32 v40, 0xffff0000, v15
	v_fmac_f32_e32 v39, v38, v38
	v_lshlrev_b32_e32 v38, 16, v15
	v_mul_f32_e32 v40, v40, v40
	v_fmac_f32_e32 v40, v38, v38
	v_add_f32_e32 v38, v39, v40
	v_and_b32_e32 v40, 0xffff0000, v16
	v_lshlrev_b32_e32 v39, 16, v16
	v_mul_f32_e32 v40, v40, v40
	v_fmac_f32_e32 v40, v39, v39
	v_add_f32_e32 v38, v40, v38
	v_and_b32_e32 v40, 0xffff0000, v17
	v_lshlrev_b32_e32 v39, 16, v17
	v_mul_f32_e32 v40, v40, v40
	v_fmac_f32_e32 v40, v39, v39
	v_add_f32_e32 v38, v40, v38
	v_add_f32_e32 v35, v35, v38
	v_cndmask_b32_e32 v38, v214, v186, vcc
	v_lshlrev_b32_e32 v192, 2, v38
	ds_bpermute_b32 v38, v192, v35
	ds_bpermute_b32 v3, v192, v37
	s_waitcnt lgkmcnt(1)
	v_add_f32_e32 v0, v35, v38
	v_mul_f32_e32 v1, 0x4f800000, v0
	v_cmp_gt_f32_e32 vcc, s70, v0
	s_waitcnt lgkmcnt(0)
	v_add_f32_e32 v3, v37, v3
	v_cndmask_b32_e32 v1, v0, v1, vcc
	v_sqrt_f32_e32 v2, v1
	v_mov_b32_e32 v0, 0
	v_mov_b32_e32 v6, v0
	v_mov_b32_e32 v7, v0
	v_add_u32_e32 v4, -1, v2
	v_fma_f32 v5, -v4, v2, v1
	v_cmp_ge_f32_e64 s[0:1], 0, v5
	v_add_u32_e32 v5, 1, v2
	v_mov_b32_e32 v14, v0
	v_cndmask_b32_e64 v4, v2, v4, s[0:1]
	v_fma_f32 v2, -v5, v2, v1
	v_cmp_lt_f32_e64 s[0:1], 0, v2
	v_mov_b32_e32 v15, v0
	v_mov_b32_e32 v16, v0
	v_cndmask_b32_e64 v2, v4, v5, s[0:1]
	v_mul_f32_e32 v4, 0x37800000, v2
	v_cndmask_b32_e32 v2, v2, v4, vcc
	v_mul_f32_e32 v4, 0x4f800000, v3
	v_cmp_gt_f32_e32 vcc, s70, v3
	v_cmp_class_f32_e64 s[0:1], v1, v183
	v_mov_b32_e32 v17, v0
	v_cndmask_b32_e32 v3, v3, v4, vcc
	v_sqrt_f32_e32 v4, v3
	v_cndmask_b32_e64 v1, v2, v1, s[0:1]
	s_waitcnt vmcnt(4)
	v_mul_f32_e32 v1, v31, v1
	v_mul_f32_e32 v164, 0xbe38aa3b, v1
	v_add_u32_e32 v2, -1, v4
	v_fma_f32 v5, -v2, v4, v3
	v_cmp_ge_f32_e64 s[0:1], 0, v5
	v_add_u32_e32 v5, 1, v4
	v_mul_i32_i24_e32 v1, 0xffffff38, v12
	v_cndmask_b32_e64 v2, v4, v2, s[0:1]
	v_fma_f32 v4, -v5, v4, v3
	v_cmp_lt_f32_e64 s[0:1], 0, v4
	v_mov_b32_e32 v31, v0
	v_mov_b32_e32 v36, v0
	v_cndmask_b32_e64 v2, v2, v5, s[0:1]
	v_mul_f32_e32 v4, 0x37800000, v2
	v_cndmask_b32_e32 v2, v2, v4, vcc
	v_cmp_class_f32_e32 vcc, v3, v183
	v_mad_u64_u32 v[174:175], s[0:1], v42, s66, v[34:35]
	s_nop 0
	v_cndmask_b32_e32 v2, v2, v3, vcc
	v_mul_f32_e32 v4, v30, v2
	v_mad_u64_u32 v[172:173], s[0:1], v195, s65, v[32:33]
	v_add_u32_e32 v2, 0x4400, v174
	s_waitcnt vmcnt(2)
	ds_write_b128 v172, v[18:21]
	ds_write_b128 v172, v[8:11] offset:16
	s_waitcnt vmcnt(0)
	ds_write2_b64 v2, v[26:27], v[28:29] offset1:1
	v_add_u32_e32 v2, 0x4410, v174
	ds_write2_b64 v2, v[22:23], v[24:25] offset1:1
	v_lshl_add_u64 v[2:3], s[12:13], 0, v[32:33]
	v_lshl_add_u64 v[176:177], v[2:3], 0, s[4:5]
	v_mul_u32_u24_e32 v2, 0x110, v12
	v_mul_f32_e32 v173, 0xbe38aa3b, v4
	v_add3_u32 v175, v2, v1, v13
	s_cselect_b32 s0, 7, 0x207
	v_mov_b32_e32 v1, v0
	v_mov_b32_e32 v2, v0
	v_mov_b32_e32 v3, v0
	v_mov_b32_e32 v4, v0
	v_mov_b32_e32 v5, v0
	v_mov_b32_e32 v8, v0
	v_mov_b32_e32 v9, v0
	v_mov_b32_e32 v10, v0
	v_mov_b32_e32 v11, v0
	v_mov_b32_e32 v12, v0
	v_mov_b32_e32 v13, v0
	v_mov_b32_e32 v18, v0
	v_mov_b32_e32 v19, v0
	v_mov_b32_e32 v20, v0
	v_mov_b32_e32 v21, v0
	v_mov_b32_e32 v22, v0
	v_mov_b32_e32 v23, v0
	v_mov_b32_e32 v24, v0
	v_mov_b32_e32 v25, v0
	v_mov_b32_e32 v26, v0
	v_mov_b32_e32 v27, v0
	v_mov_b32_e32 v28, v0
	v_mov_b32_e32 v29, v0
	v_mov_b32_e32 v30, v0
	v_mov_b32_e32 v32, v0
	v_mov_b32_e32 v33, v0
	v_mov_b32_e32 v34, v0
	v_mov_b32_e32 v35, v0
	v_mov_b32_e32 v37, v0
	v_mov_b32_e32 v38, v0
	v_mov_b32_e32 v39, v0
	v_mov_b32_e32 v40, v0
	v_mov_b32_e32 v41, v0
	v_mov_b32_e32 v42, v0
	v_mov_b32_e32 v43, v0
	v_mov_b32_e32 v44, v0
	v_mov_b32_e32 v45, v0
	v_mov_b32_e32 v46, v0
	v_mov_b32_e32 v47, v0
	v_mov_b32_e32 v48, v0
	v_mov_b32_e32 v49, v0
	v_mov_b32_e32 v50, v0
	v_mov_b32_e32 v51, v0
	v_mov_b32_e32 v52, v0
	v_mov_b32_e32 v53, v0
	v_mov_b32_e32 v54, v0
	v_mov_b32_e32 v55, v0
	v_mov_b32_e32 v56, v0
	v_mov_b32_e32 v57, v0
	v_mov_b32_e32 v58, v0
	v_mov_b32_e32 v59, v0
	v_mov_b32_e32 v60, v0
	v_mov_b32_e32 v61, v0
	v_mov_b32_e32 v62, v0
	v_mov_b32_e32 v63, v0
	v_mov_b32_e32 v64, v0
	v_mov_b32_e32 v65, v0
	v_mov_b32_e32 v66, v0
; #define MFMA32(a, b, c) __builtin_amdgcn_mfma_f32_32x32x16_bf16((a), (b), (c), 0, 0, 0)
; __device__ __forceinline__ void attn_item_A(const Params& p, int layer, int head, int q0u, char* lds) {
;     ...
; #pragma unroll
;   for (int d = 0; d < 4; ++d)
; #pragma unroll
;     for (int e = 0; e < 16; ++e) { o1[d][e] = 0.f; o2[d][e] = 0.f; }
;     ...
;   for (int t = 0; t < ntiles; ++t) {
;     const int buf = t & 1;
;     const bool more = (t + 1 < ntiles);
;     if (more) { ATT_LOADK(t + 1); ATT_LOADV(t + 1); }
;     const u16* kt_ = Ks + buf * 32 * KLD + r * KLD + 8 * h;
;     bf16x8 a0, a1, b0, b1;
;     {
;       f32x16 sx, sy;
; #pragma unroll
;       for (int e = 0; e < 16; ++e) { sx[e] = 0.f; sy[e] = 0.f; }
; #pragma unroll
;       for (int s = 0; s < 4; ++s) {
;         const bf16x8 kf = *(const bf16x8*)(kt_ + 16 * s);
;         const bf16x8 qf = *(const bf16x8*)(Qs + s * 1024);
;         sx = MFMA32(kf, qf, sx);
;       }
; #pragma unroll
;       for (int s = 4; s < 8; ++s) {
;         const bf16x8 kf = *(const bf16x8*)(kt_ + 16 * s);
;         const bf16x8 qf = *(const bf16x8*)(Qs + s * 1024);
;         sy = MFMA32(kf, qf, sy);
;       }
	v_mov_b32_e32 v67, v0
	v_mov_b32_e32 v68, v0
	v_mov_b32_e32 v69, v0
	v_mov_b32_e32 v70, v0
	v_mov_b32_e32 v71, v0
	v_mov_b32_e32 v72, v0
	v_mov_b32_e32 v73, v0
	v_mov_b32_e32 v74, v0
	v_mov_b32_e32 v75, v0
	v_mov_b32_e32 v76, v0
	v_mov_b32_e32 v77, v0
	v_mov_b32_e32 v78, v0
	v_mov_b32_e32 v79, v0
	v_mov_b32_e32 v80, v0
	v_mov_b32_e32 v81, v0
	v_mov_b32_e32 v82, v0
	v_mov_b32_e32 v83, v0
	v_mov_b32_e32 v84, v0
	v_mov_b32_e32 v85, v0
	v_mov_b32_e32 v86, v0
	v_mov_b32_e32 v87, v0
	v_mov_b32_e32 v88, v0
	v_mov_b32_e32 v89, v0
	v_mov_b32_e32 v90, v0
	v_mov_b32_e32 v91, v0
	v_mov_b32_e32 v92, v0
	v_mov_b32_e32 v93, v0
	v_mov_b32_e32 v94, v0
	v_mov_b32_e32 v95, v0
	v_mov_b32_e32 v96, v0
	v_mov_b32_e32 v97, v0
	v_mov_b32_e32 v98, v0
	v_mov_b32_e32 v99, v0
	v_mov_b32_e32 v100, v0
	v_mov_b32_e32 v101, v0
	v_mov_b32_e32 v102, v0
	v_mov_b32_e32 v103, v0
	v_mov_b32_e32 v104, v0
	v_mov_b32_e32 v105, v0
	v_mov_b32_e32 v106, v0
	v_mov_b32_e32 v107, v0
	v_mov_b32_e32 v108, v0
	v_mov_b32_e32 v109, v0
	v_mov_b32_e32 v110, v0
	v_mov_b32_e32 v111, v0
	v_mov_b32_e32 v112, v0
	v_mov_b32_e32 v113, v0
	v_mov_b32_e32 v114, v0
	v_mov_b32_e32 v115, v0
	v_mov_b32_e32 v116, v0
	v_mov_b32_e32 v117, v0
	v_mov_b32_e32 v118, v0
	v_mov_b32_e32 v119, v0
	v_mov_b32_e32 v120, v0
	v_mov_b32_e32 v121, v0
	v_mov_b32_e32 v122, v0
	v_mov_b32_e32 v123, v0
	v_mov_b32_e32 v124, v0
	v_mov_b32_e32 v125, v0
	v_mov_b32_e32 v126, v0
	v_mov_b32_e32 v127, v0
	v_mov_b32_e32 v168, v0
	v_mov_b32_e32 v169, v0
	v_add_u32_e32 v197, v193, v194
	ds_read_b128 v[240:243], v197 offset:39936
	ds_read_b128 v[244:247], v197 offset:40960
	ds_read_b128 v[248:251], v197 offset:44032
	ds_read_b128 v[252:255], v197 offset:45056
	s_and_b32 s1, s8, 1
	s_mul_i32 s7, s1, 0x2200
	v_add_u32_e32 v210, s7, v196
	s_waitcnt lgkmcnt(0)
	s_barrier
	ds_read_b128 v[128:131], v197 offset:37888
	ds_read_b128 v[160:163], v197 offset:38912
	ds_read_b128 v[144:147], v197 offset:41984
	ds_read_b128 v[178:181], v197 offset:43008
	ds_read_b128 v[132:135], v210
	ds_read_b128 v[148:151], v210 offset:128
	ds_read_b128 v[206:209], v210 offset:64
	ds_read_b128 v[220:223], v210 offset:192
	ds_read_b128 v[224:227], v210 offset:224
.LBB0_1571:
	s_setprio 1
	s_and_b32 s1, s8, 1
	s_mul_i32 s7, s1, 0x2200
	ds_read_b128 v[198:201], v210 offset:32
	ds_read_b128 v[202:205], v210 offset:160
	ds_read_b128 v[216:219], v210 offset:96
	s_waitcnt lgkmcnt(7)
	v_mfma_f32_32x32x16_bf16 v[128:143], v[132:135], v[128:131], 0
	s_ashr_i32 s7, s6, 31
	s_add_i32 s8, s8, 1
	s_waitcnt lgkmcnt(6)
	v_mfma_f32_32x32x16_bf16 v[144:159], v[148:151], v[144:147], 0
	s_waitcnt lgkmcnt(2)
	v_mfma_f32_32x32x16_bf16 v[128:143], v[198:201], v[160:163], v[128:143]
	s_waitcnt lgkmcnt(1)
	v_mfma_f32_32x32x16_bf16 v[144:159], v[202:205], v[178:181], v[144:159]
	s_waitcnt lgkmcnt(1)
	v_mfma_f32_32x32x16_bf16 v[128:143], v[206:209], v[240:243], v[128:143]
	v_lshl_add_u64 v[178:179], s[6:7], 1, v[170:171]
	s_mul_i32 s7, s1, 0x2400
	v_add_u32_e32 v210, s7, v175
	v_add_u32_e32 v212, 0x4000, v210
	v_add_u32_e32 v215, 0x4800, v210
	v_add_u32_e32 v238, 0x5000, v210
	s_waitcnt lgkmcnt(1)
	v_mfma_f32_32x32x16_bf16 v[144:159], v[220:223], v[248:251], v[144:159]
	v_add_u32_e32 v160, s6, v195
	v_mad_i64_i32 v[180:181], s[10:11], v160, s63, v[176:177]
	global_load_dwordx4 v[160:163], v[180:181], off offset:1040
	v_add_u32_e32 v210, 0x5800, v210
	s_xor_b32 s1, s1, 1
	s_add_i32 s6, s6, 32
	s_waitcnt lgkmcnt(0)
	v_mfma_f32_32x32x16_bf16 v[128:143], v[216:219], v[244:247], v[128:143]
	ds_read2_b64 v[198:201], v212 offset0:128 offset1:130
	s_mul_i32 s7, s1, 0x2200
	s_mulk_i32 s1, 0x2400
	s_cmp_eq_u32 s0, s8
	s_waitcnt lgkmcnt(1)
	v_mfma_f32_32x32x16_bf16 v[144:159], v[224:227], v[252:255], v[144:159]
	s_setprio 0
	s_nop 5
	v_fmamk_f32 v128, v128, 0x3e38aa3b, v173
	v_fmamk_f32 v129, v129, 0x3e38aa3b, v173
	v_fmamk_f32 v130, v130, 0x3e38aa3b, v173
	v_fmamk_f32 v131, v131, 0x3e38aa3b, v173
	v_fmamk_f32 v132, v132, 0x3e38aa3b, v173
	v_fmamk_f32 v133, v133, 0x3e38aa3b, v173
	v_fmamk_f32 v202, v134, 0x3e38aa3b, v173
	v_fmamk_f32 v135, v135, 0x3e38aa3b, v173
	v_fmamk_f32 v203, v144, 0x3e38aa3b, v164
	v_fmamk_f32 v145, v145, 0x3e38aa3b, v164
	v_fmamk_f32 v204, v146, 0x3e38aa3b, v164
	v_fmamk_f32 v205, v147, 0x3e38aa3b, v164
	v_fmamk_f32 v206, v148, 0x3e38aa3b, v164
	v_fmamk_f32 v207, v149, 0x3e38aa3b, v164
	v_fmamk_f32 v208, v150, 0x3e38aa3b, v164
	v_fmamk_f32 v209, v151, 0x3e38aa3b, v164
	v_exp_f32_e32 v150, v128
	v_exp_f32_e32 v148, v129
	v_exp_f32_e32 v146, v130
	v_exp_f32_e32 v144, v131
	v_exp_f32_e32 v134, v132
	v_exp_f32_e32 v130, v133
	v_exp_f32_e32 v132, v202
	v_exp_f32_e32 v128, v135
	v_exp_f32_e32 v151, v203
	v_exp_f32_e32 v149, v145
	v_exp_f32_e32 v147, v204
	v_exp_f32_e32 v145, v205
	v_exp_f32_e32 v135, v206
	v_exp_f32_e32 v131, v207
	v_exp_f32_e32 v133, v208
	v_exp_f32_e32 v129, v209
	v_cvt_pk_bf16_f32 v202, v150, v148
	v_cvt_pk_bf16_f32 v203, v146, v144
	v_cvt_pk_bf16_f32 v204, v134, v130
	v_cvt_pk_bf16_f32 v205, v132, v128
	v_cvt_pk_bf16_f32 v206, v151, v149
	v_cvt_pk_bf16_f32 v207, v147, v145
	v_cvt_pk_bf16_f32 v208, v135, v131
	v_cvt_pk_bf16_f32 v209, v133, v129
	s_setprio 1
	s_waitcnt lgkmcnt(0)
	v_mfma_f32_32x32x16_bf16 v[64:79], v[202:205], v[198:201], v[64:79]
	v_fmamk_f32 v152, v152, 0x3e38aa3b, v164
	v_fmamk_f32 v153, v153, 0x3e38aa3b, v164
	v_fmamk_f32 v154, v154, 0x3e38aa3b, v164
	v_fmamk_f32 v155, v155, 0x3e38aa3b, v164
	v_fmamk_f32 v156, v156, 0x3e38aa3b, v164
	v_fmamk_f32 v157, v157, 0x3e38aa3b, v164
	v_fmamk_f32 v158, v158, 0x3e38aa3b, v164
	v_mfma_f32_32x32x16_bf16 v[48:63], v[206:209], v[198:201], v[48:63]
	ds_read2_b64 v[198:201], v215 offset0:160 offset1:162
	ds_read2_b64 v[216:219], v212 offset0:132 offset1:134
	ds_read2_b64 v[220:223], v238 offset0:192 offset1:194
	ds_read2_b64 v[224:227], v210 offset0:224 offset1:226
	v_fmamk_f32 v159, v159, 0x3e38aa3b, v164
	v_exp_f32_e32 v213, v152
	v_exp_f32_e32 v229, v153
	v_exp_f32_e32 v231, v154
	v_exp_f32_e32 v233, v157
	s_waitcnt lgkmcnt(1)
; __device__ __forceinline__ void attn_item_A(const Params& p, int layer, int head, int q0u, char* lds) {
;     ...
;         float w[16];
; #pragma unroll
;         for (int e = 0; e < 16; ++e) { w[e] = __builtin_amdgcn_exp2f(fmaf(sx[e], CS, -bA)); lA += w[e]; }
;         const u32x4 p0 = {pk2(w[0], w[1]), pk2(w[2], w[3]), pk2(w[4], w[5]), pk2(w[6], w[7])};
;         const u32x4 p1 = {pk2(w[8], w[9]), pk2(w[10], w[11]), pk2(w[12], w[13]), pk2(w[14], w[15])};
;         a0 = __builtin_bit_cast(bf16x8, p0); a1 = __builtin_bit_cast(bf16x8, p1);
;       }
;       {
;         float w[16];
; #pragma unroll
;         for (int e = 0; e < 16; ++e) { w[e] = __builtin_amdgcn_exp2f(fmaf(sy[e], CS, -bB)); lB += w[e]; }
;         const u32x4 p0 = {pk2(w[0], w[1]), pk2(w[2], w[3]), pk2(w[4], w[5]), pk2(w[6], w[7])};
;         const u32x4 p1 = {pk2(w[8], w[9]), pk2(w[10], w[11]), pk2(w[12], w[13]), pk2(w[14], w[15])};
;         b0 = __builtin_bit_cast(bf16x8, p0); b1 = __builtin_bit_cast(bf16x8, p1);
;       }
;     }
;     const u16* vt = Vt + buf * 128 * VLD + r * VLD + 4 * h;
; #pragma unroll
;     for (int d = 0; d < 4; d += 2) {
;       const s16x4 l0 = *(const s16x4*)(vt + d * 32 * VLD), h0 = *(const s16x4*)(vt + d * 32 * VLD + 8);
;       const s16x4 l1 = *(const s16x4*)(vt + d * 32 * VLD + 16), h1 = *(const s16x4*)(vt + d * 32 * VLD + 24);
;       const s16x4 m0 = *(const s16x4*)(vt + (d + 1) * 32 * VLD), n0 = *(const s16x4*)(vt + (d + 1) * 32 * VLD + 8);
;       const s16x4 m1 = *(const s16x4*)(vt + (d + 1) * 32 * VLD + 16), n1 = *(const s16x4*)(vt + (d + 1) * 32 * VLD + 24);
;       const bf16x8 v0 = {l0[0], l0[1], l0[2], l0[3], h0[0], h0[1], h0[2], h0[3]};
;       const bf16x8 v1 = {l1[0], l1[1], l1[2], l1[3], h1[0], h1[1], h1[2], h1[3]};
;       const bf16x8 u0 = {m0[0], m0[1], m0[2], m0[3], n0[0], n0[1], n0[2], n0[3]};
;       const bf16x8 u1 = {m1[0], m1[1], m1[2], m1[3], n1[0], n1[1], n1[2], n1[3]};
;       o1[d] = MFMA32(a0, v0, o1[d]);
;       o2[d] = MFMA32(b0, v0, o2[d]);
;       o1[d + 1] = MFMA32(a0, u0, o1[d + 1]);
;       o2[d + 1] = MFMA32(b0, u0, o2[d + 1]);
;       o1[d] = MFMA32(a1, v1, o1[d]);
;       o2[d] = MFMA32(b1, v1, o2[d]);
;       o1[d + 1] = MFMA32(a1, u1, o1[d + 1]);
;       o2[d + 1] = MFMA32(b1, u1, o2[d + 1]);
;     }
;     if (more) { ATT_STOREK(buf ^ 1); ATT_STOREV(buf ^ 1); }
;     __syncthreads();
	v_mfma_f32_32x32x16_bf16 v[96:111], v[202:205], v[220:223], v[96:111]
	v_exp_f32_e32 v235, v158
	v_exp_f32_e32 v237, v159
	v_fmamk_f32 v136, v136, 0x3e38aa3b, v173
	v_fmamk_f32 v137, v137, 0x3e38aa3b, v173
	v_fmamk_f32 v138, v138, 0x3e38aa3b, v173
	v_fmamk_f32 v139, v139, 0x3e38aa3b, v173
	v_fmamk_f32 v140, v140, 0x3e38aa3b, v173
	v_mfma_f32_32x32x16_bf16 v[16:31], v[206:209], v[220:223], v[16:31]
	v_exp_f32_e32 v221, v155
	v_exp_f32_e32 v223, v156
	global_load_dwordx4 v[152:155], v[180:181], off offset:1024
	global_load_dwordx4 v[156:159], v[178:179], off
	v_fmamk_f32 v141, v141, 0x3e38aa3b, v173
	global_load_dwordx4 v[178:181], v[178:179], off offset:16
	v_fmamk_f32 v142, v142, 0x3e38aa3b, v173
	v_fmamk_f32 v143, v143, 0x3e38aa3b, v173
	v_exp_f32_e32 v212, v136
	v_exp_f32_e32 v228, v137
	v_exp_f32_e32 v230, v138
	v_exp_f32_e32 v220, v139
	v_exp_f32_e32 v222, v140
	v_exp_f32_e32 v232, v141
	v_exp_f32_e32 v234, v142
	v_exp_f32_e32 v236, v143
	v_mfma_f32_32x32x16_bf16 v[80:95], v[202:205], v[198:201], v[80:95]
	v_cvt_pk_bf16_f32 v136, v212, v228
	v_cvt_pk_bf16_f32 v137, v230, v220
	v_cvt_pk_bf16_f32 v138, v222, v232
	v_cvt_pk_bf16_f32 v139, v234, v236
	v_cvt_pk_bf16_f32 v140, v213, v229
	v_cvt_pk_bf16_f32 v141, v231, v221
	v_cvt_pk_bf16_f32 v142, v223, v233
	v_mfma_f32_32x32x16_bf16 v[32:47], v[206:209], v[198:201], v[32:47]
	v_cvt_pk_bf16_f32 v143, v235, v237
	ds_read2_b64 v[198:201], v215 offset0:164 offset1:166
	v_add_f32_e64 v150, v168, v150
	v_add_f32_e64 v151, v169, v151
	v_add_f32_e64 v148, v148, v150
	v_add_f32_e64 v149, v149, v151
	v_pk_add_f32 v[146:147], v[146:147], v[148:149]
	s_waitcnt lgkmcnt(1)
	v_mfma_f32_32x32x16_bf16 v[112:127], v[202:205], v[224:227], v[112:127]
	ds_read2_b64 v[202:205], v210 offset0:228 offset1:230
	v_add_f32_e64 v144, v144, v146
	v_add_f32_e64 v145, v145, v147
	v_add_f32_e64 v134, v134, v144
	v_add_f32_e64 v135, v135, v145
	v_pk_add_f32 v[130:131], v[130:131], v[134:135]
	v_mfma_f32_32x32x16_bf16 v[0:15], v[206:209], v[224:227], v[0:15]
	v_add_f32_e64 v130, v132, v130
	v_add_f32_e64 v131, v133, v131
	v_add_u32_e32 v206, s7, v172
	v_add_f32_e64 v128, v128, v130
	v_add_f32_e64 v129, v129, v131
	v_add_u32_e32 v207, s1, v174
	v_pk_add_f32 v[128:129], v[212:213], v[128:129]
	v_add_u32_e32 v208, 0x4400, v207
	v_pk_add_f32 v[128:129], v[228:229], v[128:129]
	s_waitcnt lgkmcnt(1)
	v_mfma_f32_32x32x16_bf16 v[80:95], v[136:139], v[198:201], v[80:95]
	v_add_f32_e64 v128, v230, v128
	v_add_f32_e64 v129, v231, v129
	v_add_u32_e32 v207, 0x4410, v207
	v_add_f32_e64 v128, v220, v128
	v_add_f32_e64 v129, v221, v129
	v_pk_add_f32 v[128:129], v[222:223], v[128:129]
	s_nop 0
	v_pk_add_f32 v[128:129], v[232:233], v[128:129]
	v_mfma_f32_32x32x16_bf16 v[32:47], v[140:143], v[198:201], v[32:47]
	ds_read2_b64 v[198:201], v238 offset0:196 offset1:198
	v_add_f32_e64 v128, v234, v128
	v_add_f32_e64 v129, v235, v129
	s_setprio 0
	s_waitcnt vmcnt(2)
	ds_write_b128 v206, v[152:155]
	ds_write_b128 v206, v[160:163] offset:16
	s_waitcnt vmcnt(1)
	ds_write2_b64 v208, v[156:157], v[158:159] offset1:1
	s_waitcnt vmcnt(0)
	ds_write2_b64 v207, v[178:179], v[180:181] offset1:1
	v_mfma_f32_32x32x16_bf16 v[64:79], v[136:139], v[216:219], v[64:79]
	v_add_f32_e64 v168, v236, v128
	v_add_f32_e64 v169, v237, v129
	v_add_u32_e32 v210, s7, v196
	s_waitcnt lgkmcnt(0)
	s_barrier
	ds_read_b128 v[128:131], v197 offset:37888
	ds_read_b128 v[160:163], v197 offset:38912
	ds_read_b128 v[144:147], v197 offset:41984
	ds_read_b128 v[178:181], v197 offset:43008
	ds_read_b128 v[132:135], v210
	ds_read_b128 v[148:151], v210 offset:128
	ds_read_b128 v[206:209], v210 offset:64
	ds_read_b128 v[220:223], v210 offset:192
	ds_read_b128 v[224:227], v210 offset:224
	v_mfma_f32_32x32x16_bf16 v[48:63], v[140:143], v[216:219], v[48:63]
	v_mfma_f32_32x32x16_bf16 v[96:111], v[136:139], v[198:201], v[96:111]
	v_mfma_f32_32x32x16_bf16 v[16:31], v[140:143], v[198:201], v[16:31]
	v_mfma_f32_32x32x16_bf16 v[112:127], v[136:139], v[202:205], v[112:127]
	v_mfma_f32_32x32x16_bf16 v[0:15], v[140:143], v[202:205], v[0:15]
	s_cbranch_scc0 .LBB0_1571
	s_and_b32 s0, s0, 1
	s_mul_i32 s1, s0, 0x2200
	v_add_u32_e32 v170, s1, v196
	ds_read_b128 v[128:131], v170
	ds_read_b128 v[132:135], v197 offset:37888
	ds_read_b128 v[136:139], v197 offset:38912
	ds_read_b128 v[140:143], v170 offset:32
	s_mulk_i32 s0, 0x2400
	s_waitcnt lgkmcnt(2)
	v_mfma_f32_32x32x16_bf16 v[144:159], v[128:131], v[132:135], 0
	ds_read_b128 v[128:131], v170 offset:64
	ds_read_b128 v[132:135], v197 offset:39936
	ds_read_b128 v[160:163], v197 offset:40960
	ds_read_b128 v[176:179], v170 offset:96
	s_waitcnt lgkmcnt(4)
	v_mfma_f32_32x32x16_bf16 v[144:159], v[140:143], v[136:139], v[144:159]
	s_waitcnt lgkmcnt(2)
	v_mfma_f32_32x32x16_bf16 v[144:159], v[128:131], v[132:135], v[144:159]
	ds_read_b128 v[128:131], v170 offset:128
	ds_read_b128 v[132:135], v197 offset:41984
	ds_read_b128 v[198:201], v197 offset:43008
	ds_read_b128 v[202:205], v170 offset:160
	ds_read_b128 v[206:209], v197 offset:44032
	ds_read_b128 v[194:197], v197 offset:45056
	ds_read_b128 v[216:219], v170 offset:192
	ds_read_b128 v[220:223], v170 offset:224
	s_waitcnt lgkmcnt(6)
	v_mfma_f32_32x32x16_bf16 v[128:143], v[128:131], v[132:135], 0
	s_waitcnt lgkmcnt(4)
	v_mfma_f32_32x32x16_bf16 v[128:143], v[202:205], v[198:201], v[128:143]
	s_waitcnt lgkmcnt(1)
	v_mfma_f32_32x32x16_bf16 v[128:143], v[216:219], v[206:209], v[128:143]
	s_waitcnt lgkmcnt(0)
; #define MFMA32(a, b, c) __builtin_amdgcn_mfma_f32_32x32x16_bf16((a), (b), (c), 0, 0, 0)
; __device__ __forceinline__ void attn_item_A(const Params& p, int layer, int head, int q0u, char* lds) {
;     ...
;         float w[16];
; #pragma unroll
;         for (int e = 0; e < 16; ++e) { w[e] = __builtin_amdgcn_exp2f(fmaf(sx[e], CS, -bA)); lA += w[e]; }
;         const u32x4 p0 = {pk2(w[0], w[1]), pk2(w[2], w[3]), pk2(w[4], w[5]), pk2(w[6], w[7])};
;         const u32x4 p1 = {pk2(w[8], w[9]), pk2(w[10], w[11]), pk2(w[12], w[13]), pk2(w[14], w[15])};
;         a0 = __builtin_bit_cast(bf16x8, p0); a1 = __builtin_bit_cast(bf16x8, p1);
;       }
;       {
;         float w[16];
; #pragma unroll
;         for (int e = 0; e < 16; ++e) { w[e] = __builtin_amdgcn_exp2f(fmaf(sy[e], CS, -bB)); lB += w[e]; }
;         const u32x4 p0 = {pk2(w[0], w[1]), pk2(w[2], w[3]), pk2(w[4], w[5]), pk2(w[6], w[7])};
;         const u32x4 p1 = {pk2(w[8], w[9]), pk2(w[10], w[11]), pk2(w[12], w[13]), pk2(w[14], w[15])};
;         b0 = __builtin_bit_cast(bf16x8, p0); b1 = __builtin_bit_cast(bf16x8, p1);
;       }
;     }
;     const u16* vt = Vt + buf * 128 * VLD + r * VLD + 4 * h;
; #pragma unroll
;     for (int d = 0; d < 4; d += 2) {
;       const s16x4 l0 = *(const s16x4*)(vt + d * 32 * VLD), h0 = *(const s16x4*)(vt + d * 32 * VLD + 8);
;       const s16x4 l1 = *(const s16x4*)(vt + d * 32 * VLD + 16), h1 = *(const s16x4*)(vt + d * 32 * VLD + 24);
;       const s16x4 m0 = *(const s16x4*)(vt + (d + 1) * 32 * VLD), n0 = *(const s16x4*)(vt + (d + 1) * 32 * VLD + 8);
;       const s16x4 m1 = *(const s16x4*)(vt + (d + 1) * 32 * VLD + 16), n1 = *(const s16x4*)(vt + (d + 1) * 32 * VLD + 24);
;       const bf16x8 v0 = {l0[0], l0[1], l0[2], l0[3], h0[0], h0[1], h0[2], h0[3]};
;       const bf16x8 v1 = {l1[0], l1[1], l1[2], l1[3], h1[0], h1[1], h1[2], h1[3]};
;       const bf16x8 u0 = {m0[0], m0[1], m0[2], m0[3], n0[0], n0[1], n0[2], n0[3]};
;       const bf16x8 u1 = {m1[0], m1[1], m1[2], m1[3], n1[0], n1[1], n1[2], n1[3]};
;       o1[d] = MFMA32(a0, v0, o1[d]);
;       o2[d] = MFMA32(b0, v0, o2[d]);
;       o1[d + 1] = MFMA32(a0, u0, o1[d + 1]);
;       o2[d + 1] = MFMA32(b0, u0, o2[d + 1]);
;       o1[d] = MFMA32(a1, v1, o1[d]);
;       o2[d] = MFMA32(b1, v1, o2[d]);
;       o1[d + 1] = MFMA32(a1, u1, o1[d + 1]);
;       o2[d + 1] = MFMA32(b1, u1, o2[d + 1]);
;     }
	v_mfma_f32_32x32x16_bf16 v[128:143], v[220:223], v[194:197], v[128:143]
	v_mfma_f32_32x32x16_bf16 v[144:159], v[176:179], v[160:163], v[144:159]
	s_nop 10
	v_fmamk_f32 v128, v128, 0x3e38aa3b, v164
	v_exp_f32_e32 v194, v128
	v_fmamk_f32 v128, v129, 0x3e38aa3b, v164
	v_exp_f32_e32 v195, v128
	v_fmamk_f32 v128, v130, 0x3e38aa3b, v164
	v_exp_f32_e32 v196, v128
	v_fmamk_f32 v128, v131, 0x3e38aa3b, v164
	v_fmamk_f32 v144, v144, 0x3e38aa3b, v173
	v_exp_f32_e32 v160, v144
	v_fmamk_f32 v144, v155, 0x3e38aa3b, v173
	v_exp_f32_e32 v197, v128
	v_fmamk_f32 v128, v132, 0x3e38aa3b, v164
	v_fmamk_f32 v132, v134, 0x3e38aa3b, v164
	v_fmamk_f32 v145, v145, 0x3e38aa3b, v173
	v_fmamk_f32 v146, v146, 0x3e38aa3b, v173
	v_fmamk_f32 v147, v147, 0x3e38aa3b, v173
	v_fmamk_f32 v148, v148, 0x3e38aa3b, v173
	v_fmamk_f32 v149, v149, 0x3e38aa3b, v173
	v_fmamk_f32 v150, v150, 0x3e38aa3b, v173
	v_fmamk_f32 v151, v151, 0x3e38aa3b, v173
	v_exp_f32_e32 v179, v144
	v_fmamk_f32 v144, v156, 0x3e38aa3b, v173
	v_exp_f32_e32 v198, v128
	v_fmamk_f32 v128, v133, 0x3e38aa3b, v164
	v_add_u32_e32 v156, s0, v175
	v_exp_f32_e32 v175, v132
	v_fmamk_f32 v132, v135, 0x3e38aa3b, v164
	v_exp_f32_e32 v161, v145
	v_exp_f32_e32 v162, v146
	v_exp_f32_e32 v163, v147
	v_exp_f32_e32 v170, v148
	v_exp_f32_e32 v171, v149
	v_exp_f32_e32 v172, v150
	v_exp_f32_e32 v174, v151
	v_exp_f32_e32 v199, v128
	v_exp_f32_e32 v200, v132
	v_fmamk_f32 v152, v152, 0x3e38aa3b, v173
	v_exp_f32_e32 v180, v144
	v_fmamk_f32 v144, v157, 0x3e38aa3b, v173
	v_exp_f32_e32 v176, v152
	v_exp_f32_e32 v181, v144
	v_fmamk_f32 v144, v158, 0x3e38aa3b, v173
	v_add_u32_e32 v152, 0x4000, v156
	v_fmamk_f32 v136, v136, 0x3e38aa3b, v164
	v_exp_f32_e32 v193, v144
	v_cvt_pk_bf16_f32 v144, v160, v161
	v_cvt_pk_bf16_f32 v145, v162, v163
	v_cvt_pk_bf16_f32 v146, v170, v171
	v_cvt_pk_bf16_f32 v147, v172, v174
	ds_read2_b64 v[128:131], v152 offset0:128 offset1:130
	v_cvt_pk_bf16_f32 v132, v194, v195
	v_cvt_pk_bf16_f32 v133, v196, v197
	v_cvt_pk_bf16_f32 v134, v198, v199
	v_cvt_pk_bf16_f32 v135, v175, v200
	v_exp_f32_e32 v201, v136
	v_fmamk_f32 v136, v137, 0x3e38aa3b, v164
	v_exp_f32_e32 v202, v136
	v_fmamk_f32 v136, v138, 0x3e38aa3b, v164
	v_exp_f32_e32 v203, v136
	v_fmamk_f32 v136, v139, 0x3e38aa3b, v164
	v_fmamk_f32 v153, v153, 0x3e38aa3b, v173
	v_exp_f32_e32 v204, v136
	v_fmamk_f32 v136, v140, 0x3e38aa3b, v164
	v_exp_f32_e32 v177, v153
	v_add_u32_e32 v153, 0x4800, v156
	v_exp_f32_e32 v205, v136
	v_fmamk_f32 v136, v141, 0x3e38aa3b, v164
	v_fmamk_f32 v154, v154, 0x3e38aa3b, v173
	v_fmac_f32_e32 v173, 0x3e38aa3b, v159
	s_waitcnt lgkmcnt(0)
	v_mfma_f32_32x32x16_bf16 v[64:79], v[144:147], v[128:131], v[64:79]
	v_exp_f32_e32 v206, v136
	v_fmamk_f32 v136, v142, 0x3e38aa3b, v164
	v_fmac_f32_e32 v164, 0x3e38aa3b, v143
	v_exp_f32_e32 v178, v154
	v_exp_f32_e32 v173, v173
	v_exp_f32_e32 v207, v136
	v_exp_f32_e32 v164, v164
	v_mfma_f32_32x32x16_bf16 v[48:63], v[132:135], v[128:131], v[48:63]
	ds_read2_b64 v[128:131], v153 offset0:160 offset1:162
	v_cvt_pk_bf16_f32 v148, v176, v177
	v_cvt_pk_bf16_f32 v149, v178, v179
	v_cvt_pk_bf16_f32 v150, v180, v181
	v_cvt_pk_bf16_f32 v151, v193, v173
	v_cvt_pk_bf16_f32 v136, v201, v202
	v_cvt_pk_bf16_f32 v137, v203, v204
	s_waitcnt lgkmcnt(0)
	v_mfma_f32_32x32x16_bf16 v[80:95], v[144:147], v[128:131], v[80:95]
	v_cvt_pk_bf16_f32 v138, v205, v206
	v_cvt_pk_bf16_f32 v139, v207, v164
	v_add_f32_e32 v160, v168, v160
	v_add_f32_e32 v160, v161, v160
	v_mfma_f32_32x32x16_bf16 v[32:47], v[132:135], v[128:131], v[32:47]
	ds_read2_b64 v[128:131], v152 offset0:132 offset1:134
	v_add_u32_e32 v152, 0x5000, v156
	v_add_u32_e32 v156, 0x5800, v156
	s_waitcnt lgkmcnt(0)
	v_mfma_f32_32x32x16_bf16 v[64:79], v[148:151], v[128:131], v[64:79]
	v_mfma_f32_32x32x16_bf16 v[48:63], v[136:139], v[128:131], v[48:63]
	ds_read2_b64 v[128:131], v153 offset0:164 offset1:166
	ds_read2_b64 v[140:143], v152 offset0:192 offset1:194
	ds_read2_b64 v[152:155], v152 offset0:196 offset1:198
	s_waitcnt lgkmcnt(2)
	v_mfma_f32_32x32x16_bf16 v[80:95], v[148:151], v[128:131], v[80:95]
	v_mfma_f32_32x32x16_bf16 v[32:47], v[136:139], v[128:131], v[32:47]
	ds_read2_b64 v[128:131], v156 offset0:224 offset1:226
	ds_read2_b64 v[156:159], v156 offset0:228 offset1:230
	s_waitcnt lgkmcnt(0)
	s_barrier
; #define MFMA32(a, b, c) __builtin_amdgcn_mfma_f32_32x32x16_bf16((a), (b), (c), 0, 0, 0)
; DI int crow(int i, int h) { return (i & 3) + 8 * (i >> 2) + 4 * h; }
; __device__ __forceinline__ void attn_item_A(const Params& p, int layer, int head, int q0u, char* lds) {
;     ...
;       o1[d] = MFMA32(a1, v1, o1[d]);
;       o2[d] = MFMA32(b1, v1, o2[d]);
;       o1[d + 1] = MFMA32(a1, u1, o1[d + 1]);
;       o2[d + 1] = MFMA32(b1, u1, o2[d + 1]);
;     }
;     if (more) { ATT_STOREK(buf ^ 1); ATT_STOREV(buf ^ 1); }
;     __syncthreads();
;   }
;   int lane_e = lane; asm volatile("" : "+v"(lane_e));
;   const int r_e = lane_e & 31, h_e = lane_e >> 5;
;   lA += __shfl_xor(lA, 32); lB += __shfl_xor(lB, 32);
;   const float lam = ((const float*)(p.ws + OFF_LAM))[layer];
;   const float iA = 1.f / lA, iB = lam / lB;
;   u16* Mx = (u16*)(p.ws + OFF_M);
;   const int orow0 = q0u + wid * 32;
;   const float lam_init = 0.8f - 0.6f * expf(-0.3f * (float)layer);
;   float sw[4];
; #pragma unroll
;   for (int d = 0; d < 4; ++d) sw[d] = p.subln[layer * 128 + d * 32 + r_e] * (1.f - lam_init);
; #pragma unroll
;   for (int e = 0; e < 16; ++e) {
;     const int qq = crow(e, h_e);
;     const float ia = __shfl(iA, qq), ib = __shfl(iB, qq);
;     float ov[4];
;     float ss = 0.f;
; #pragma unroll
;     for (int d = 0; d < 4; ++d) { ov[d] = o1[d][e] * ia - o2[d][e] * ib; ss += ov[d] * ov[d]; }
; #pragma unroll
;     for (int x = 16; x >= 1; x >>= 1) ss += __shfl_xor(ss, x);
;     const float rs = rsqrtf(ss * (1.f / 128.f) + LN_EPS);
	global_load_dword v208, v165, s[16:17]
	v_and_b32_e32 v209, 31, v167
	v_mfma_f32_32x32x16_bf16 v[96:111], v[144:147], v[140:143], v[96:111]
	v_lshlrev_b32_e32 v210, 2, v209
	global_load_dword v212, v210, s[54:55]
	global_load_dword v213, v210, s[54:55] offset:128
	global_load_dword v215, v210, s[54:55] offset:256
	v_mfma_f32_32x32x16_bf16 v[16:31], v[132:135], v[140:143], v[16:31]
	v_add_f32_e32 v141, v169, v194
	v_add_f32_e32 v141, v195, v141
	v_add_f32_e32 v141, v196, v141
	v_add_f32_e32 v141, v197, v141
	v_add_f32_e32 v140, v162, v160
	v_add_f32_e32 v140, v163, v140
	v_add_f32_e32 v140, v170, v140
	v_mfma_f32_32x32x16_bf16 v[112:127], v[144:147], v[128:131], v[112:127]
	v_add_f32_e32 v140, v171, v140
	v_add_f32_e32 v140, v172, v140
	v_add_f32_e32 v140, v174, v140
	v_add_f32_e32 v140, v176, v140
	v_add_f32_e32 v140, v177, v140
	v_add_f32_e32 v140, v178, v140
	v_add_f32_e32 v140, v179, v140
	v_mfma_f32_32x32x16_bf16 v[0:15], v[132:135], v[128:131], v[0:15]
	v_add_f32_e32 v128, v198, v141
	v_add_f32_e32 v128, v199, v128
	v_add_f32_e32 v128, v175, v128
	v_add_f32_e32 v128, v200, v128
	v_add_f32_e32 v128, v201, v128
	v_add_f32_e32 v128, v202, v128
	v_add_f32_e32 v128, v203, v128
	v_add_f32_e32 v128, v204, v128
	v_add_f32_e32 v128, v205, v128
	v_add_f32_e32 v128, v206, v128
	v_add_f32_e32 v128, v207, v128
	v_add_f32_e32 v128, v164, v128
	ds_bpermute_b32 v129, v192, v128
	v_add_f32_e32 v130, v180, v140
	v_add_f32_e32 v130, v181, v130
	v_add_f32_e32 v130, v193, v130
	v_add_f32_e32 v130, v173, v130
	s_waitcnt lgkmcnt(0)
	v_add_f32_e32 v128, v128, v129
	ds_bpermute_b32 v133, v192, v130
	v_mfma_f32_32x32x16_bf16 v[0:15], v[136:139], v[156:159], v[0:15]
	v_mov_b32_e32 v143, v32
	v_mov_b32_e32 v140, v64
	v_mov_b32_e32 v142, v48
	s_waitcnt lgkmcnt(0)
	v_add_f32_e32 v133, v130, v133
	v_mov_b32_e32 v141, v80
	v_mov_b32_e32 v80, v65
	v_lshlrev_b32_e32 v164, 1, v209
	v_mfma_f32_32x32x16_bf16 v[16:31], v[136:139], v[152:155], v[16:31]
	s_nop 2
	v_mov_b32_e32 v146, v0
	v_xor_b32_e32 v0, 16, v214
	s_waitcnt vmcnt(3)
	v_div_scale_f32 v129, s[0:1], v128, v128, v208
	v_rcp_f32_e32 v131, v129
	v_mfma_f32_32x32x16_bf16 v[96:111], v[148:151], v[152:155], v[96:111]
	s_nop 2
	v_mov_b32_e32 v147, v16
	s_waitcnt vmcnt(1)
	v_mul_f32_e32 v130, 0x3f4ccccd, v213
	v_fma_f32 v132, -v129, v131, 1.0
	v_fmac_f32_e32 v131, v132, v131
	v_div_scale_f32 v132, vcc, v208, v128, v208
	v_mul_f32_e32 v134, v132, v131
	v_fma_f32 v135, -v129, v134, v132
	v_fmac_f32_e32 v134, v135, v131
	v_fma_f32 v129, -v129, v134, v132
	v_div_fmas_f32 v129, v129, v131, v134
	v_div_scale_f32 v134, s[0:1], v133, v133, 1.0
	v_rcp_f32_e32 v135, v134
	v_mfma_f32_32x32x16_bf16 v[112:127], v[148:151], v[156:159], v[112:127]
	v_div_fixup_f32 v132, v129, v128, v208
	v_mov_b32_e32 v145, v96
	v_fma_f32 v136, -v134, v135, 1.0
	v_fmac_f32_e32 v135, v136, v135
	v_div_scale_f32 v136, vcc, 1.0, v133, 1.0
	v_mul_f32_e32 v137, v136, v135
	v_fma_f32 v138, -v134, v137, v136
	v_fmac_f32_e32 v137, v138, v135
	v_fma_f32 v134, -v134, v137, v136
	v_div_fmas_f32 v134, v134, v135, v137
	v_ashrrev_i32_e32 v135, 3, v167
	v_div_fixup_f32 v133, v134, v133, 1.0
	v_and_b32_e32 v134, -4, v135
	v_cmp_lt_i32_e32 vcc, v0, v188
	v_or_b32_e32 v150, 1, v134
	v_and_or_b32 v136, v135, 60, v187
	v_cndmask_b32_e32 v16, v214, v0, vcc
	v_and_or_b32 v0, v150, 61, v187
	v_lshlrev_b32_e32 v137, 2, v136
	v_lshlrev_b32_e32 v32, 2, v0
	ds_bpermute_b32 v138, v137, v132
	ds_bpermute_b32 v0, v32, v132
	ds_bpermute_b32 v136, v137, v133
	ds_bpermute_b32 v64, v32, v133
	v_mov_b32_e32 v32, v49
	s_waitcnt lgkmcnt(3)
	v_pk_mul_f32 v[142:143], v[142:143], v[138:139] op_sel_hi:[1,0]
	v_mov_b32_e32 v144, v112
	v_pk_mul_f32 v[138:139], v[146:147], v[138:139] op_sel_hi:[1,0]
	v_lshlrev_b32_e32 v48, 2, v16
	s_waitcnt lgkmcnt(2)
	v_pk_mul_f32 v[32:33], v[32:33], v[0:1] op_sel_hi:[1,0]
	v_mov_b32_e32 v16, v1
	s_waitcnt lgkmcnt(1)
	v_pk_fma_f32 v[140:141], v[140:141], v[136:137], v[142:143] op_sel_hi:[1,0,1] neg_lo:[0,0,1] neg_hi:[0,0,1]
	v_pk_fma_f32 v[136:137], v[144:145], v[136:137], v[138:139] op_sel_hi:[1,0,1] neg_lo:[0,0,1] neg_hi:[0,0,1]
	s_waitcnt lgkmcnt(0)
	v_pk_fma_f32 v[144:145], v[80:81], v[64:65], v[32:33] op_sel_hi:[1,0,1] neg_lo:[0,0,1] neg_hi:[0,0,1]
	v_mov_b32_e32 v96, v113
	v_pk_mul_f32 v[0:1], v[16:17], v[0:1] op_sel_hi:[1,0]
	v_pk_mul_f32 v[142:143], v[140:141], v[140:141]
	v_pk_mul_f32 v[32:33], v[144:145], v[144:145]
	v_pk_fma_f32 v[96:97], v[96:97], v[64:65], v[0:1] op_sel_hi:[1,0,1] neg_lo:[0,0,1] neg_hi:[0,0,1]
	v_pk_mul_f32 v[138:139], v[136:137], v[136:137]
	v_pk_mul_f32 v[0:1], v[96:97], v[96:97]
	v_mov_b32_e32 v16, v32
	v_mov_b32_e32 v17, v142
	v_mov_b32_e32 v142, v33
	v_pk_add_f32 v[16:17], v[16:17], v[142:143]
	v_mov_b32_e32 v32, v1
	v_mov_b32_e32 v33, v139
	v_pk_add_f32 v[16:17], v[32:33], v[16:17]
	v_mov_b32_e32 v1, v138
	v_pk_add_f32 v[0:1], v[0:1], v[16:17]
	ds_bpermute_b32 v17, v48, v1
	ds_bpermute_b32 v16, v48, v0
	v_xor_b32_e32 v32, 8, v214
	v_cmp_lt_i32_e32 vcc, v32, v188
	s_add_u32 s0, s31, s4
	s_addc_u32 s1, s34, s5
	v_cndmask_b32_e32 v32, v214, v32, vcc
	v_lshlrev_b32_e32 v49, 2, v32
	s_waitcnt lgkmcnt(0)
	v_pk_add_f32 v[0:1], v[0:1], v[16:17]
	ds_bpermute_b32 v17, v49, v1
	ds_bpermute_b32 v16, v49, v0
	v_xor_b32_e32 v32, 4, v214
	v_cmp_lt_i32_e32 vcc, v32, v188
	v_mul_f32_e32 v131, 0x3f4ccccd, v212
	s_waitcnt vmcnt(0)
	v_mul_f32_e32 v129, 0x3f4ccccd, v215
	v_cndmask_b32_e32 v32, v214, v32, vcc
	v_lshlrev_b32_e32 v64, 2, v32
	s_waitcnt lgkmcnt(0)
	v_pk_add_f32 v[0:1], v[0:1], v[16:17]
	ds_bpermute_b32 v17, v64, v1
	ds_bpermute_b32 v16, v64, v0
	v_xor_b32_e32 v32, 2, v214
	v_cmp_lt_i32_e32 vcc, v32, v188
	v_or_b32_e32 v152, 2, v134
	v_or_b32_e32 v135, 3, v135
	v_cndmask_b32_e32 v32, v214, v32, vcc
	v_lshlrev_b32_e32 v65, 2, v32
	s_waitcnt lgkmcnt(0)
; DI u16 f2bf(float a) { return (u16)(pk2(a, 0.f) & 0xffffu); }
; DI int crow(int i, int h) { return (i & 3) + 8 * (i >> 2) + 4 * h; }
; __device__ __forceinline__ void attn_item_A(const Params& p, int layer, int head, int q0u, char* lds) {
;     ...
; #pragma unroll
;   for (int e = 0; e < 16; ++e) {
;     const int qq = crow(e, h_e);
;     const float ia = __shfl(iA, qq), ib = __shfl(iB, qq);
;     float ov[4];
;     float ss = 0.f;
; #pragma unroll
;     for (int d = 0; d < 4; ++d) { ov[d] = o1[d][e] * ia - o2[d][e] * ib; ss += ov[d] * ov[d]; }
; #pragma unroll
;     for (int x = 16; x >= 1; x >>= 1) ss += __shfl_xor(ss, x);
;     const float rs = rsqrtf(ss * (1.f / 128.f) + LN_EPS);
;     const size_t rowoff = (size_t)(orow0 + qq) * LDX + ocol + r_e;
; #pragma unroll
;     for (int d = 0; d < 4; ++d) Mx[rowoff + d * 32] = f2bf(ov[d] * rs * sw[d]);
;   }
	v_pk_add_f32 v[0:1], v[0:1], v[16:17]
	ds_bpermute_b32 v17, v65, v1
	ds_bpermute_b32 v16, v65, v0
	v_xor_b32_e32 v32, 1, v214
	v_cmp_lt_i32_e32 vcc, v32, v188
	v_mov_b32_e32 v148, v2
	v_and_or_b32 v2, v135, 63, v187
	v_cndmask_b32_e32 v32, v214, v32, vcc
	v_lshlrev_b32_e32 v80, 2, v32
	s_waitcnt lgkmcnt(0)
	v_pk_add_f32 v[0:1], v[0:1], v[16:17]
	ds_bpermute_b32 v33, v80, v1
	ds_bpermute_b32 v32, v80, v0
	v_lshl_add_u64 v[16:17], s[0:1], 0, v[164:165]
	v_mov_b32_e32 v149, v18
	v_lshlrev_b32_e32 v18, 2, v2
	ds_bpermute_b32 v2, v18, v132
	s_waitcnt lgkmcnt(1)
	v_pk_add_f32 v[0:1], v[0:1], v[32:33]
	v_mov_b64_e32 v[32:33], s[30:31]
	v_pk_fma_f32 v[112:113], v[0:1], s[28:29], v[32:33] op_sel_hi:[1,0,0]
	v_mov_b32_e32 v142, v50
	v_mul_f32_e32 v0, 0x4b800000, v113
	v_cmp_gt_f32_e32 vcc, s80, v113
	ds_bpermute_b32 v50, v18, v133
	v_mov_b32_e32 v143, v34
	v_cndmask_b32_e32 v0, v113, v0, vcc
	v_rsq_f32_e32 v81, v0
	v_add_u32_e32 v0, v134, v191
	v_mad_i64_i32 v[0:1], s[0:1], v0, s77, v[16:17]
	v_mul_f32_e32 v113, 0x45800000, v81
	v_cndmask_b32_e32 v81, v81, v113, vcc
	v_mul_f32_e32 v113, v140, v81
	v_mul_f32_e32 v113, v131, v113
	v_cvt_pk_bf16_f32 v113, v113, s0
	global_store_short v[0:1], v113, off
	v_mul_f32_e32 v113, v141, v81
	v_mul_f32_e32 v113, v130, v113
	v_cvt_pk_bf16_f32 v113, v113, s0
	global_store_short v[0:1], v113, off offset:64
	v_mul_f32_e32 v113, v137, v81
	v_mul_f32_e32 v113, v129, v113
	v_cvt_pk_bf16_f32 v137, v113, s0
	v_mul_f32_e32 v113, 0x4b800000, v112
	v_cmp_gt_f32_e32 vcc, s80, v112
	v_mov_b32_e32 v34, v51
	v_mov_b32_e32 v140, v66
	v_cndmask_b32_e32 v112, v112, v113, vcc
	v_rsq_f32_e32 v151, v112
	v_and_or_b32 v112, v152, 62, v187
	v_lshlrev_b32_e32 v113, 2, v112
	ds_bpermute_b32 v138, v113, v132
	ds_bpermute_b32 v112, v113, v133
	v_mov_b32_e32 v141, v82
	v_mov_b32_e32 v82, v67
	s_waitcnt lgkmcnt(3)
	v_pk_mul_f32 v[34:35], v[34:35], v[2:3] op_sel_hi:[1,0]
	s_waitcnt lgkmcnt(1)
	v_pk_mul_f32 v[142:143], v[142:143], v[138:139] op_sel_hi:[1,0]
	v_mov_b32_e32 v18, v3
	s_waitcnt lgkmcnt(0)
	v_pk_fma_f32 v[140:141], v[140:141], v[112:113], v[142:143] op_sel_hi:[1,0,1] neg_lo:[0,0,1] neg_hi:[0,0,1]
	v_mov_b32_e32 v146, v114
	v_mov_b32_e32 v147, v98
	v_pk_mul_f32 v[138:139], v[148:149], v[138:139] op_sel_hi:[1,0]
	v_pk_fma_f32 v[66:67], v[82:83], v[50:51], v[34:35] op_sel_hi:[1,0,1] neg_lo:[0,0,1] neg_hi:[0,0,1]
	v_mov_b32_e32 v98, v115
	v_pk_mul_f32 v[2:3], v[18:19], v[2:3] op_sel_hi:[1,0]
	v_pk_mul_f32 v[142:143], v[140:141], v[140:141]
	v_pk_fma_f32 v[112:113], v[146:147], v[112:113], v[138:139] op_sel_hi:[1,0,1] neg_lo:[0,0,1] neg_hi:[0,0,1]
	v_pk_mul_f32 v[34:35], v[66:67], v[66:67]
	v_pk_fma_f32 v[50:51], v[98:99], v[50:51], v[2:3] op_sel_hi:[1,0,1] neg_lo:[0,0,1] neg_hi:[0,0,1]
	v_pk_mul_f32 v[138:139], v[112:113], v[112:113]
	v_pk_mul_f32 v[2:3], v[50:51], v[50:51]
	v_mov_b32_e32 v18, v34
	v_mov_b32_e32 v19, v142
	v_mov_b32_e32 v142, v35
	v_pk_add_f32 v[18:19], v[18:19], v[142:143]
	v_mov_b32_e32 v34, v3
	v_mov_b32_e32 v35, v139
	v_pk_add_f32 v[18:19], v[34:35], v[18:19]
	v_mov_b32_e32 v3, v138
	v_pk_add_f32 v[2:3], v[2:3], v[18:19]
	ds_bpermute_b32 v19, v48, v3
	ds_bpermute_b32 v18, v48, v2
	v_mul_f32_e32 v35, 0x45800000, v151
	v_cndmask_b32_e32 v35, v151, v35, vcc
	v_mul_f32_e32 v34, v136, v81
	v_mul_f32_e32 v81, v144, v35
	s_waitcnt lgkmcnt(0)
	v_pk_add_f32 v[18:19], v[2:3], v[18:19]
	ds_bpermute_b32 v83, v49, v19
	ds_bpermute_b32 v82, v49, v18
	v_add_u32_e32 v2, v150, v191
	v_mad_i64_i32 v[2:3], s[0:1], v2, s77, v[16:17]
	v_mul_f32_e32 v81, v131, v81
	s_waitcnt lgkmcnt(0)
	v_pk_add_f32 v[18:19], v[18:19], v[82:83]
	ds_bpermute_b32 v83, v64, v19
	ds_bpermute_b32 v82, v64, v18
	v_cvt_pk_bf16_f32 v81, v81, s0
	global_store_short v[2:3], v81, off
	v_mul_f32_e32 v81, v145, v35
	v_mul_f32_e32 v81, v130, v81
	s_waitcnt lgkmcnt(0)
	v_pk_add_f32 v[18:19], v[18:19], v[82:83]
	ds_bpermute_b32 v83, v65, v19
	ds_bpermute_b32 v82, v65, v18
	v_cvt_pk_bf16_f32 v81, v81, s0
	global_store_short v[2:3], v81, off offset:64
	v_mul_f32_e32 v81, v97, v35
	v_mul_f32_e32 v81, v129, v81
	s_waitcnt lgkmcnt(0)
	v_pk_add_f32 v[18:19], v[18:19], v[82:83]
	ds_bpermute_b32 v83, v80, v19
	ds_bpermute_b32 v82, v80, v18
	v_cvt_pk_bf16_f32 v81, v81, s0
	global_store_short v[2:3], v81, off offset:128
	v_mov_b32_e32 v136, v116
	v_add_u32_e32 v116, 9, v134
	s_waitcnt lgkmcnt(0)
	v_pk_add_f32 v[18:19], v[18:19], v[82:83]
	v_mov_b32_e32 v138, v4
	v_pk_fma_f32 v[82:83], v[18:19], s[28:29], v[32:33] op_sel_hi:[1,0,0]
	v_and_or_b32 v4, v116, 61, v187
	v_mul_f32_e32 v18, 0x4b800000, v83
	v_cmp_gt_f32_e32 vcc, s80, v83
	v_mov_b32_e32 v139, v20
	v_lshlrev_b32_e32 v20, 2, v4
	v_cndmask_b32_e32 v18, v83, v18, vcc
	v_rsq_f32_e32 v81, v18
	v_add_u32_e32 v18, v152, v191
	v_mad_i64_i32 v[18:19], s[0:1], v18, s77, v[16:17]
	v_mul_f32_e32 v83, 0x45800000, v81
	v_cndmask_b32_e32 v81, v81, v83, vcc
	v_mul_f32_e32 v83, v140, v81
	v_mul_f32_e32 v83, v131, v83
	v_cvt_pk_bf16_f32 v83, v83, s0
	global_store_short v[18:19], v83, off
	v_mul_f32_e32 v83, v141, v81
	v_mul_f32_e32 v83, v130, v83
	v_cvt_pk_bf16_f32 v83, v83, s0
	global_store_short v[18:19], v83, off offset:64
	v_mul_f32_e32 v83, v113, v81
	v_mul_f32_e32 v83, v129, v83
	v_cvt_pk_bf16_f32 v113, v83, s0
	v_mul_f32_e32 v83, 0x4b800000, v82
	v_cmp_gt_f32_e32 vcc, s80, v82
	v_add_u32_e32 v141, 8, v134
	v_mul_f32_e32 v35, v96, v35
	v_cndmask_b32_e32 v82, v82, v83, vcc
	v_rsq_f32_e32 v140, v82
	v_and_or_b32 v82, v141, 60, v187
	v_lshlrev_b32_e32 v83, 2, v82
	ds_bpermute_b32 v96, v83, v132
	ds_bpermute_b32 v4, v20, v132
	ds_bpermute_b32 v82, v83, v133
	v_mov_b32_e32 v114, v52
	ds_bpermute_b32 v52, v20, v133
	v_mov_b32_e32 v115, v36
	v_mov_b32_e32 v36, v53
	v_mov_b32_e32 v98, v68
	v_mov_b32_e32 v99, v84
	s_waitcnt lgkmcnt(3)
; DI u16 f2bf(float a) { return (u16)(pk2(a, 0.f) & 0xffffu); }
; DI int crow(int i, int h) { return (i & 3) + 8 * (i >> 2) + 4 * h; }
; __device__ __forceinline__ void attn_item_A(const Params& p, int layer, int head, int q0u, char* lds) {
;     ...
; #pragma unroll
;   for (int e = 0; e < 16; ++e) {
;     const int qq = crow(e, h_e);
;     const float ia = __shfl(iA, qq), ib = __shfl(iB, qq);
;     float ov[4];
;     float ss = 0.f;
; #pragma unroll
;     for (int d = 0; d < 4; ++d) { ov[d] = o1[d][e] * ia - o2[d][e] * ib; ss += ov[d] * ov[d]; }
; #pragma unroll
;     for (int x = 16; x >= 1; x >>= 1) ss += __shfl_xor(ss, x);
;     const float rs = rsqrtf(ss * (1.f / 128.f) + LN_EPS);
;     const size_t rowoff = (size_t)(orow0 + qq) * LDX + ocol + r_e;
; #pragma unroll
;     for (int d = 0; d < 4; ++d) Mx[rowoff + d * 32] = f2bf(ov[d] * rs * sw[d]);
;   }
	v_pk_mul_f32 v[114:115], v[114:115], v[96:97] op_sel_hi:[1,0]
	v_mov_b32_e32 v84, v69
	s_waitcnt lgkmcnt(2)
	v_pk_mul_f32 v[36:37], v[36:37], v[4:5] op_sel_hi:[1,0]
	v_mov_b32_e32 v20, v5
	global_store_short v[0:1], v137, off offset:128
	s_waitcnt lgkmcnt(1)
	v_pk_fma_f32 v[98:99], v[98:99], v[82:83], v[114:115] op_sel_hi:[1,0,1] neg_lo:[0,0,1] neg_hi:[0,0,1]
	v_mov_b32_e32 v137, v100
	v_pk_mul_f32 v[96:97], v[138:139], v[96:97] op_sel_hi:[1,0]
	s_waitcnt lgkmcnt(0)
	v_pk_fma_f32 v[68:69], v[84:85], v[52:53], v[36:37] op_sel_hi:[1,0,1] neg_lo:[0,0,1] neg_hi:[0,0,1]
	v_mov_b32_e32 v100, v117
	v_pk_mul_f32 v[4:5], v[20:21], v[4:5] op_sel_hi:[1,0]
	v_pk_mul_f32 v[114:115], v[98:99], v[98:99]
	v_pk_fma_f32 v[82:83], v[136:137], v[82:83], v[96:97] op_sel_hi:[1,0,1] neg_lo:[0,0,1] neg_hi:[0,0,1]
	v_pk_mul_f32 v[36:37], v[68:69], v[68:69]
	v_pk_fma_f32 v[52:53], v[100:101], v[52:53], v[4:5] op_sel_hi:[1,0,1] neg_lo:[0,0,1] neg_hi:[0,0,1]
	v_pk_mul_f32 v[96:97], v[82:83], v[82:83]
	v_pk_mul_f32 v[4:5], v[52:53], v[52:53]
	v_mov_b32_e32 v20, v36
	v_mov_b32_e32 v21, v114
	v_mov_b32_e32 v114, v37
	v_pk_add_f32 v[20:21], v[20:21], v[114:115]
	v_mov_b32_e32 v36, v5
	v_mov_b32_e32 v37, v97
	v_pk_add_f32 v[20:21], v[36:37], v[20:21]
	v_mov_b32_e32 v5, v96
	v_pk_add_f32 v[4:5], v[4:5], v[20:21]
	ds_bpermute_b32 v21, v48, v5
	ds_bpermute_b32 v20, v48, v4
	v_mul_f32_e32 v37, 0x45800000, v140
	v_cndmask_b32_e32 v37, v140, v37, vcc
	v_mul_f32_e32 v66, v66, v37
	v_mul_f32_e32 v66, v131, v66
	s_waitcnt lgkmcnt(0)
	v_pk_add_f32 v[20:21], v[4:5], v[20:21]
	ds_bpermute_b32 v85, v49, v21
	ds_bpermute_b32 v84, v49, v20
	v_add_u32_e32 v4, v135, v191
	v_mad_i64_i32 v[4:5], s[0:1], v4, s77, v[16:17]
	v_mul_f32_e32 v36, v112, v81
	s_waitcnt lgkmcnt(0)
	v_pk_add_f32 v[20:21], v[20:21], v[84:85]
	ds_bpermute_b32 v85, v64, v21
	ds_bpermute_b32 v84, v64, v20
	v_cvt_pk_bf16_f32 v66, v66, s0
	global_store_short v[4:5], v66, off
	v_mul_f32_e32 v81, v67, v37
	v_mul_f32_e32 v51, v51, v37
	s_waitcnt lgkmcnt(0)
	v_pk_add_f32 v[20:21], v[20:21], v[84:85]
	ds_bpermute_b32 v67, v65, v21
	ds_bpermute_b32 v66, v65, v20
	v_mul_f32_e32 v51, v129, v51
	v_cvt_pk_bf16_f32 v51, v51, s0
	global_store_short v[4:5], v51, off offset:128
	v_mul_f32_e32 v37, v50, v37
	s_waitcnt lgkmcnt(0)
	v_pk_add_f32 v[20:21], v[20:21], v[66:67]
	ds_bpermute_b32 v67, v80, v21
	ds_bpermute_b32 v66, v80, v20
	v_mul_f32_e32 v81, v130, v81
	v_cvt_pk_bf16_f32 v81, v81, s0
	global_store_short v[4:5], v81, off offset:64
	global_store_short v[18:19], v113, off offset:128
	s_waitcnt lgkmcnt(0)
	v_pk_add_f32 v[20:21], v[20:21], v[66:67]
	v_add_u32_e32 v113, 10, v134
	v_pk_fma_f32 v[50:51], v[20:21], s[28:29], v[32:33] op_sel_hi:[1,0,0]
	v_mov_b32_e32 v96, v54
	v_mul_f32_e32 v20, 0x4b800000, v51
	v_cmp_gt_f32_e32 vcc, s80, v51
	v_mov_b32_e32 v97, v38
	v_mov_b32_e32 v100, v6
	v_cndmask_b32_e32 v20, v51, v20, vcc
	v_rsq_f32_e32 v51, v20
	v_add_u32_e32 v20, v141, v191
	v_mad_i64_i32 v[20:21], s[0:1], v20, s77, v[16:17]
	v_mul_f32_e32 v66, 0x45800000, v51
	v_cndmask_b32_e32 v81, v51, v66, vcc
	v_mul_f32_e32 v51, v98, v81
	v_mul_f32_e32 v51, v131, v51
	v_cvt_pk_bf16_f32 v51, v51, s0
	global_store_short v[20:21], v51, off
	v_mul_f32_e32 v51, v99, v81
	v_mul_f32_e32 v51, v130, v51
	v_cvt_pk_bf16_f32 v51, v51, s0
	global_store_short v[20:21], v51, off offset:64
	v_mul_f32_e32 v51, v83, v81
	v_mul_f32_e32 v51, v129, v51
	v_cvt_pk_bf16_f32 v83, v51, s0
	v_mul_f32_e32 v51, 0x4b800000, v50
	v_cmp_gt_f32_e32 vcc, s80, v50
	v_mov_b32_e32 v101, v22
	v_mov_b32_e32 v84, v70
	v_cndmask_b32_e32 v50, v50, v51, vcc
	v_rsq_f32_e32 v112, v50
	v_and_or_b32 v50, v113, 62, v187
	v_lshlrev_b32_e32 v51, 2, v50
	ds_bpermute_b32 v66, v51, v132
	ds_bpermute_b32 v50, v51, v133
	v_mov_b32_e32 v85, v86
	v_mov_b32_e32 v98, v118
	v_mov_b32_e32 v99, v102
	s_waitcnt lgkmcnt(1)
	v_pk_mul_f32 v[96:97], v[96:97], v[66:67] op_sel_hi:[1,0]
	v_pk_mul_f32 v[66:67], v[100:101], v[66:67] op_sel_hi:[1,0]
	s_waitcnt lgkmcnt(0)
	v_pk_fma_f32 v[84:85], v[84:85], v[50:51], v[96:97] op_sel_hi:[1,0,1] neg_lo:[0,0,1] neg_hi:[0,0,1]
	v_pk_fma_f32 v[50:51], v[98:99], v[50:51], v[66:67] op_sel_hi:[1,0,1] neg_lo:[0,0,1] neg_hi:[0,0,1]
	v_add_u32_e32 v98, 11, v134
	v_and_or_b32 v6, v98, 63, v187
	v_lshlrev_b32_e32 v22, 2, v6
	ds_bpermute_b32 v6, v22, v132
	ds_bpermute_b32 v54, v22, v133
	v_mov_b32_e32 v38, v55
	v_mov_b32_e32 v86, v71
	v_mov_b32_e32 v22, v7
	s_waitcnt lgkmcnt(1)
	v_pk_mul_f32 v[38:39], v[38:39], v[6:7] op_sel_hi:[1,0]
	v_mov_b32_e32 v102, v119
	s_waitcnt lgkmcnt(0)
	v_pk_fma_f32 v[70:71], v[86:87], v[54:55], v[38:39] op_sel_hi:[1,0,1] neg_lo:[0,0,1] neg_hi:[0,0,1]
	v_pk_mul_f32 v[6:7], v[22:23], v[6:7] op_sel_hi:[1,0]
	v_pk_mul_f32 v[96:97], v[84:85], v[84:85]
	v_pk_mul_f32 v[38:39], v[70:71], v[70:71]
	v_pk_fma_f32 v[54:55], v[102:103], v[54:55], v[6:7] op_sel_hi:[1,0,1] neg_lo:[0,0,1] neg_hi:[0,0,1]
	v_pk_mul_f32 v[66:67], v[50:51], v[50:51]
	v_pk_mul_f32 v[6:7], v[54:55], v[54:55]
	v_mov_b32_e32 v22, v38
	v_mov_b32_e32 v23, v96
	v_mov_b32_e32 v96, v39
	v_pk_add_f32 v[22:23], v[22:23], v[96:97]
	v_mov_b32_e32 v38, v7
	v_mov_b32_e32 v39, v67
	v_pk_add_f32 v[22:23], v[38:39], v[22:23]
	v_mov_b32_e32 v7, v66
	v_pk_add_f32 v[6:7], v[6:7], v[22:23]
	ds_bpermute_b32 v23, v48, v7
	ds_bpermute_b32 v22, v48, v6
	v_mul_f32_e32 v39, 0x45800000, v112
	v_cndmask_b32_e32 v39, v112, v39, vcc
	v_mul_f32_e32 v68, v68, v39
	v_mul_f32_e32 v53, v53, v39
	s_waitcnt lgkmcnt(0)
	v_pk_add_f32 v[22:23], v[6:7], v[22:23]
	ds_bpermute_b32 v67, v49, v23
	ds_bpermute_b32 v66, v49, v22
	v_add_u32_e32 v6, v116, v191
	v_mad_i64_i32 v[6:7], s[0:1], v6, s77, v[16:17]
	v_mul_f32_e32 v68, v131, v68
	s_waitcnt lgkmcnt(0)
; DI u16 f2bf(float a) { return (u16)(pk2(a, 0.f) & 0xffffu); }
; DI int crow(int i, int h) { return (i & 3) + 8 * (i >> 2) + 4 * h; }
; __device__ __forceinline__ void attn_item_A(const Params& p, int layer, int head, int q0u, char* lds) {
;     ...
; #pragma unroll
;   for (int e = 0; e < 16; ++e) {
;     const int qq = crow(e, h_e);
;     const float ia = __shfl(iA, qq), ib = __shfl(iB, qq);
;     float ov[4];
;     float ss = 0.f;
; #pragma unroll
;     for (int d = 0; d < 4; ++d) { ov[d] = o1[d][e] * ia - o2[d][e] * ib; ss += ov[d] * ov[d]; }
; #pragma unroll
;     for (int x = 16; x >= 1; x >>= 1) ss += __shfl_xor(ss, x);
;     const float rs = rsqrtf(ss * (1.f / 128.f) + LN_EPS);
;     const size_t rowoff = (size_t)(orow0 + qq) * LDX + ocol + r_e;
; #pragma unroll
;     for (int d = 0; d < 4; ++d) Mx[rowoff + d * 32] = f2bf(ov[d] * rs * sw[d]);
;   }
	v_pk_add_f32 v[22:23], v[22:23], v[66:67]
	ds_bpermute_b32 v67, v64, v23
	ds_bpermute_b32 v66, v64, v22
	v_mul_f32_e32 v53, v129, v53
	v_cvt_pk_bf16_f32 v68, v68, s0
	v_cvt_pk_bf16_f32 v53, v53, s0
	global_store_short v[6:7], v68, off
	s_waitcnt lgkmcnt(0)
	v_pk_add_f32 v[22:23], v[22:23], v[66:67]
	ds_bpermute_b32 v67, v65, v23
	ds_bpermute_b32 v66, v65, v22
	v_mul_f32_e32 v68, v69, v39
	global_store_short v[6:7], v53, off offset:128
	v_mul_f32_e32 v39, v52, v39
	v_mul_f32_e32 v38, v82, v81
	s_waitcnt lgkmcnt(0)
	v_pk_add_f32 v[22:23], v[22:23], v[66:67]
	ds_bpermute_b32 v67, v80, v23
	ds_bpermute_b32 v66, v80, v22
	v_mul_f32_e32 v68, v130, v68
	v_cvt_pk_bf16_f32 v68, v68, s0
	v_add_u32_e32 v97, 16, v134
	global_store_short v[20:21], v83, off offset:128
	s_waitcnt lgkmcnt(0)
	v_pk_add_f32 v[22:23], v[22:23], v[66:67]
	v_mov_b32_e32 v82, v56
	v_pk_fma_f32 v[52:53], v[22:23], s[28:29], v[32:33] op_sel_hi:[1,0,0]
	v_mov_b32_e32 v83, v40
	v_mul_f32_e32 v22, 0x4b800000, v53
	v_cmp_gt_f32_e32 vcc, s80, v53
	v_mov_b32_e32 v86, v8
	v_mov_b32_e32 v87, v24
	v_cndmask_b32_e32 v22, v53, v22, vcc
	v_rsq_f32_e32 v53, v22
	v_add_u32_e32 v22, v113, v191
	v_mad_i64_i32 v[22:23], s[0:1], v22, s77, v[16:17]
	v_mul_f32_e32 v66, 0x45800000, v53
	v_cndmask_b32_e32 v81, v53, v66, vcc
	v_mul_f32_e32 v53, v84, v81
	v_mul_f32_e32 v53, v131, v53
	v_cvt_pk_bf16_f32 v53, v53, s0
	global_store_short v[22:23], v53, off
	v_mul_f32_e32 v53, v85, v81
	v_mul_f32_e32 v53, v130, v53
	v_cvt_pk_bf16_f32 v53, v53, s0
	global_store_short v[22:23], v53, off offset:64
	v_mul_f32_e32 v53, 0x4b800000, v52
	v_cmp_gt_f32_e32 vcc, s80, v52
	global_store_short v[6:7], v68, off offset:64
	v_mov_b32_e32 v68, v72
	v_cndmask_b32_e32 v52, v52, v53, vcc
	v_rsq_f32_e32 v96, v52
	v_and_or_b32 v52, v97, 60, v187
	v_lshlrev_b32_e32 v53, 2, v52
	ds_bpermute_b32 v66, v53, v132
	ds_bpermute_b32 v52, v53, v133
	v_mov_b32_e32 v69, v88
	v_mov_b32_e32 v84, v120
	v_mov_b32_e32 v85, v104
	s_waitcnt lgkmcnt(1)
	v_pk_mul_f32 v[82:83], v[82:83], v[66:67] op_sel_hi:[1,0]
	v_pk_mul_f32 v[66:67], v[86:87], v[66:67] op_sel_hi:[1,0]
	s_waitcnt lgkmcnt(0)
	v_pk_fma_f32 v[68:69], v[68:69], v[52:53], v[82:83] op_sel_hi:[1,0,1] neg_lo:[0,0,1] neg_hi:[0,0,1]
	v_pk_fma_f32 v[52:53], v[84:85], v[52:53], v[66:67] op_sel_hi:[1,0,1] neg_lo:[0,0,1] neg_hi:[0,0,1]
	v_add_u32_e32 v84, 17, v134
	v_and_or_b32 v8, v84, 61, v187
	v_lshlrev_b32_e32 v24, 2, v8
	ds_bpermute_b32 v8, v24, v132
	ds_bpermute_b32 v56, v24, v133
	v_mov_b32_e32 v40, v57
	v_mov_b32_e32 v88, v73
	v_mov_b32_e32 v24, v9
	s_waitcnt lgkmcnt(1)
	v_pk_mul_f32 v[40:41], v[40:41], v[8:9] op_sel_hi:[1,0]
	v_mov_b32_e32 v104, v121
	s_waitcnt lgkmcnt(0)
	v_pk_fma_f32 v[72:73], v[88:89], v[56:57], v[40:41] op_sel_hi:[1,0,1] neg_lo:[0,0,1] neg_hi:[0,0,1]
	v_pk_mul_f32 v[8:9], v[24:25], v[8:9] op_sel_hi:[1,0]
	v_pk_mul_f32 v[82:83], v[68:69], v[68:69]
	v_pk_mul_f32 v[40:41], v[72:73], v[72:73]
	v_pk_fma_f32 v[56:57], v[104:105], v[56:57], v[8:9] op_sel_hi:[1,0,1] neg_lo:[0,0,1] neg_hi:[0,0,1]
	v_pk_mul_f32 v[66:67], v[52:53], v[52:53]
	v_pk_mul_f32 v[8:9], v[56:57], v[56:57]
	v_mov_b32_e32 v24, v40
	v_mov_b32_e32 v25, v82
	v_mov_b32_e32 v82, v41
	v_pk_add_f32 v[24:25], v[24:25], v[82:83]
	v_mov_b32_e32 v40, v9
	v_mov_b32_e32 v41, v67
	v_pk_add_f32 v[24:25], v[40:41], v[24:25]
	v_mov_b32_e32 v9, v66
	v_pk_add_f32 v[8:9], v[8:9], v[24:25]
	ds_bpermute_b32 v25, v48, v9
	ds_bpermute_b32 v24, v48, v8
	v_mul_f32_e32 v51, v51, v81
	v_mul_f32_e32 v51, v129, v51
	v_cvt_pk_bf16_f32 v51, v51, s0
	global_store_short v[22:23], v51, off offset:128
	s_waitcnt lgkmcnt(0)
	v_pk_add_f32 v[24:25], v[8:9], v[24:25]
	v_mul_f32_e32 v40, v50, v81
	ds_bpermute_b32 v51, v49, v25
	ds_bpermute_b32 v50, v49, v24
	v_mul_f32_e32 v41, 0x45800000, v96
	v_cndmask_b32_e32 v41, v96, v41, vcc
	v_add_u32_e32 v8, v98, v191
	v_mul_f32_e32 v66, v70, v41
	s_waitcnt lgkmcnt(0)
	v_pk_add_f32 v[24:25], v[24:25], v[50:51]
	ds_bpermute_b32 v51, v64, v25
	ds_bpermute_b32 v50, v64, v24
	v_mad_i64_i32 v[8:9], s[0:1], v8, s77, v[16:17]
	v_mul_f32_e32 v66, v131, v66
	s_nop 0
	v_cvt_pk_bf16_f32 v66, v66, s0
	s_waitcnt lgkmcnt(0)
	v_pk_add_f32 v[24:25], v[24:25], v[50:51]
	ds_bpermute_b32 v51, v65, v25
	ds_bpermute_b32 v50, v65, v24
	global_store_short v[8:9], v66, off
	v_mul_f32_e32 v66, v71, v41
	v_mul_f32_e32 v55, v55, v41
	v_mul_f32_e32 v41, v54, v41
	s_waitcnt lgkmcnt(0)
	v_pk_add_f32 v[24:25], v[24:25], v[50:51]
	ds_bpermute_b32 v51, v80, v25
	ds_bpermute_b32 v50, v80, v24
	v_mul_f32_e32 v66, v130, v66
	v_mul_f32_e32 v55, v129, v55
	v_cvt_pk_bf16_f32 v66, v66, s0
	v_cvt_pk_bf16_f32 v55, v55, s0
	s_waitcnt lgkmcnt(0)
	v_pk_add_f32 v[24:25], v[24:25], v[50:51]
	v_add_u32_e32 v86, 18, v134
	v_pk_fma_f32 v[50:51], v[24:25], s[28:29], v[32:33] op_sel_hi:[1,0,0]
	global_store_short v[8:9], v66, off offset:64
	v_mul_f32_e32 v24, 0x4b800000, v51
	v_cmp_gt_f32_e32 vcc, s80, v51
	v_mov_b32_e32 v66, v74
	v_add_u32_e32 v74, 19, v134
	v_cndmask_b32_e32 v24, v51, v24, vcc
	v_rsq_f32_e32 v51, v24
	v_add_u32_e32 v24, v97, v191
	v_mad_i64_i32 v[24:25], s[0:1], v24, s77, v[16:17]
	v_mul_f32_e32 v54, 0x45800000, v51
	v_cndmask_b32_e32 v81, v51, v54, vcc
	v_mul_f32_e32 v51, v68, v81
	v_mul_f32_e32 v51, v131, v51
	v_cvt_pk_bf16_f32 v51, v51, s0
	global_store_short v[24:25], v51, off
	v_mul_f32_e32 v51, v69, v81
	v_mul_f32_e32 v51, v130, v51
	v_cvt_pk_bf16_f32 v51, v51, s0
	global_store_short v[24:25], v51, off offset:64
	v_mul_f32_e32 v51, v53, v81
	v_mul_f32_e32 v51, v129, v51
	v_cvt_pk_bf16_f32 v53, v51, s0
	v_mul_f32_e32 v51, 0x4b800000, v50
	v_cmp_gt_f32_e32 vcc, s80, v50
	v_mov_b32_e32 v82, v10
	v_and_or_b32 v10, v74, 63, v187
	v_cndmask_b32_e32 v50, v50, v51, vcc
	v_rsq_f32_e32 v85, v50
	v_and_or_b32 v50, v86, 62, v187
	v_lshlrev_b32_e32 v51, 2, v50
	ds_bpermute_b32 v54, v51, v132
	ds_bpermute_b32 v50, v51, v133
	v_mov_b32_e32 v68, v58
	v_mov_b32_e32 v69, v42
	v_mov_b32_e32 v83, v26
	v_lshlrev_b32_e32 v26, 2, v10
	global_store_short v[8:9], v55, off offset:128
	v_mov_b32_e32 v67, v90
	s_waitcnt lgkmcnt(1)
; DI u16 f2bf(float a) { return (u16)(pk2(a, 0.f) & 0xffffu); }
; DI int crow(int i, int h) { return (i & 3) + 8 * (i >> 2) + 4 * h; }
; __device__ __forceinline__ void attn_item_A(const Params& p, int layer, int head, int q0u, char* lds) {
;     ...
; #pragma unroll
;   for (int e = 0; e < 16; ++e) {
;     const int qq = crow(e, h_e);
;     const float ia = __shfl(iA, qq), ib = __shfl(iB, qq);
;     float ov[4];
;     float ss = 0.f;
; #pragma unroll
;     for (int d = 0; d < 4; ++d) { ov[d] = o1[d][e] * ia - o2[d][e] * ib; ss += ov[d] * ov[d]; }
; #pragma unroll
;     for (int x = 16; x >= 1; x >>= 1) ss += __shfl_xor(ss, x);
;     const float rs = rsqrtf(ss * (1.f / 128.f) + LN_EPS);
;     const size_t rowoff = (size_t)(orow0 + qq) * LDX + ocol + r_e;
; #pragma unroll
;     for (int d = 0; d < 4; ++d) Mx[rowoff + d * 32] = f2bf(ov[d] * rs * sw[d]);
;   }
	v_pk_mul_f32 v[68:69], v[68:69], v[54:55] op_sel_hi:[1,0]
	v_mov_b32_e32 v70, v122
	v_mov_b32_e32 v71, v106
	v_pk_mul_f32 v[54:55], v[82:83], v[54:55] op_sel_hi:[1,0]
	ds_bpermute_b32 v10, v26, v132
	s_waitcnt lgkmcnt(1)
	v_pk_fma_f32 v[66:67], v[66:67], v[50:51], v[68:69] op_sel_hi:[1,0,1] neg_lo:[0,0,1] neg_hi:[0,0,1]
	v_pk_fma_f32 v[50:51], v[70:71], v[50:51], v[54:55] op_sel_hi:[1,0,1] neg_lo:[0,0,1] neg_hi:[0,0,1]
	ds_bpermute_b32 v54, v26, v133
	v_mov_b32_e32 v42, v59
	v_mov_b32_e32 v90, v75
	s_waitcnt lgkmcnt(1)
	v_pk_mul_f32 v[42:43], v[42:43], v[10:11] op_sel_hi:[1,0]
	v_mov_b32_e32 v26, v11
	s_waitcnt lgkmcnt(0)
	v_pk_fma_f32 v[42:43], v[90:91], v[54:55], v[42:43] op_sel_hi:[1,0,1] neg_lo:[0,0,1] neg_hi:[0,0,1]
	v_mov_b32_e32 v106, v123
	v_pk_mul_f32 v[10:11], v[26:27], v[10:11] op_sel_hi:[1,0]
	v_pk_mul_f32 v[68:69], v[66:67], v[66:67]
	v_pk_mul_f32 v[58:59], v[42:43], v[42:43]
	v_pk_fma_f32 v[54:55], v[106:107], v[54:55], v[10:11] op_sel_hi:[1,0,1] neg_lo:[0,0,1] neg_hi:[0,0,1]
	v_pk_mul_f32 v[70:71], v[50:51], v[50:51]
	v_pk_mul_f32 v[10:11], v[54:55], v[54:55]
	v_mov_b32_e32 v26, v58
	v_mov_b32_e32 v27, v68
	v_mov_b32_e32 v68, v59
	v_pk_add_f32 v[26:27], v[26:27], v[68:69]
	v_mov_b32_e32 v58, v11
	v_mov_b32_e32 v59, v71
	v_pk_add_f32 v[26:27], v[58:59], v[26:27]
	v_mov_b32_e32 v11, v70
	v_pk_add_f32 v[10:11], v[10:11], v[26:27]
	ds_bpermute_b32 v27, v48, v11
	ds_bpermute_b32 v26, v48, v10
	v_mul_f32_e32 v75, v52, v81
	v_mul_f32_e32 v52, 0x45800000, v85
	global_store_short v[24:25], v53, off offset:128
	v_cndmask_b32_e32 v58, v85, v52, vcc
	s_waitcnt lgkmcnt(0)
	v_pk_add_f32 v[26:27], v[10:11], v[26:27]
	ds_bpermute_b32 v53, v49, v27
	ds_bpermute_b32 v52, v49, v26
	v_add_u32_e32 v10, v84, v191
	v_mul_f32_e32 v59, v72, v58
	v_mad_i64_i32 v[10:11], s[0:1], v10, s77, v[16:17]
	s_waitcnt lgkmcnt(0)
	v_pk_add_f32 v[26:27], v[26:27], v[52:53]
	ds_bpermute_b32 v53, v64, v27
	ds_bpermute_b32 v52, v64, v26
	v_mul_f32_e32 v59, v131, v59
	v_cvt_pk_bf16_f32 v59, v59, s0
	v_mul_f32_e32 v72, v56, v58
	global_store_short v[10:11], v59, off
	s_waitcnt lgkmcnt(0)
	v_pk_add_f32 v[26:27], v[26:27], v[52:53]
	ds_bpermute_b32 v53, v65, v27
	ds_bpermute_b32 v52, v65, v26
	v_mul_f32_e32 v59, v73, v58
	v_mul_f32_e32 v57, v57, v58
	v_mul_f32_e32 v59, v130, v59
	v_mul_f32_e32 v57, v129, v57
	s_waitcnt lgkmcnt(0)
	v_pk_add_f32 v[26:27], v[26:27], v[52:53]
	ds_bpermute_b32 v53, v80, v27
	ds_bpermute_b32 v52, v80, v26
	v_cvt_pk_bf16_f32 v59, v59, s0
	v_cvt_pk_bf16_f32 v57, v57, s0
	v_add_u32_e32 v82, 24, v134
	v_mov_b32_e32 v70, v12
	s_waitcnt lgkmcnt(0)
	v_pk_add_f32 v[26:27], v[26:27], v[52:53]
	v_mov_b32_e32 v71, v28
	v_pk_fma_f32 v[52:53], v[26:27], s[28:29], v[32:33] op_sel_hi:[1,0,0]
	global_store_short v[10:11], v57, off offset:128
	v_mul_f32_e32 v26, 0x4b800000, v53
	v_cmp_gt_f32_e32 vcc, s80, v53
	global_store_short v[10:11], v59, off offset:64
	v_mov_b32_e32 v58, v76
	v_cndmask_b32_e32 v26, v53, v26, vcc
	v_rsq_f32_e32 v53, v26
	v_add_u32_e32 v26, v86, v191
	v_mad_i64_i32 v[26:27], s[0:1], v26, s77, v[16:17]
	v_mul_f32_e32 v56, 0x45800000, v53
	v_cndmask_b32_e32 v73, v53, v56, vcc
	v_mul_f32_e32 v53, v66, v73
	v_mul_f32_e32 v53, v131, v53
	v_cvt_pk_bf16_f32 v53, v53, s0
	global_store_short v[26:27], v53, off
	v_mul_f32_e32 v53, v67, v73
	v_mul_f32_e32 v53, v130, v53
	v_cvt_pk_bf16_f32 v53, v53, s0
	global_store_short v[26:27], v53, off offset:64
	v_mul_f32_e32 v53, 0x4b800000, v52
	v_cmp_gt_f32_e32 vcc, s80, v52
	v_mov_b32_e32 v66, v60
	v_mov_b32_e32 v67, v44
	v_cndmask_b32_e32 v52, v52, v53, vcc
	v_rsq_f32_e32 v81, v52
	v_and_or_b32 v52, v82, 60, v187
	v_lshlrev_b32_e32 v53, 2, v52
	ds_bpermute_b32 v56, v53, v132
	ds_bpermute_b32 v52, v53, v133
	v_mov_b32_e32 v59, v92
	v_mov_b32_e32 v68, v124
	v_mov_b32_e32 v69, v108
	s_waitcnt lgkmcnt(1)
	v_pk_mul_f32 v[66:67], v[66:67], v[56:57] op_sel_hi:[1,0]
	v_pk_mul_f32 v[56:57], v[70:71], v[56:57] op_sel_hi:[1,0]
	v_add_u32_e32 v70, 25, v134
	v_and_or_b32 v12, v70, 61, v187
	v_lshlrev_b32_e32 v28, 2, v12
	ds_bpermute_b32 v12, v28, v132
	s_waitcnt lgkmcnt(1)
	v_pk_fma_f32 v[58:59], v[58:59], v[52:53], v[66:67] op_sel_hi:[1,0,1] neg_lo:[0,0,1] neg_hi:[0,0,1]
	v_pk_fma_f32 v[52:53], v[68:69], v[52:53], v[56:57] op_sel_hi:[1,0,1] neg_lo:[0,0,1] neg_hi:[0,0,1]
	ds_bpermute_b32 v56, v28, v133
	v_mov_b32_e32 v44, v61
	v_mov_b32_e32 v92, v77
	s_waitcnt lgkmcnt(1)
	v_pk_mul_f32 v[44:45], v[44:45], v[12:13] op_sel_hi:[1,0]
	v_mov_b32_e32 v28, v13
	s_waitcnt lgkmcnt(0)
	v_pk_fma_f32 v[44:45], v[92:93], v[56:57], v[44:45] op_sel_hi:[1,0,1] neg_lo:[0,0,1] neg_hi:[0,0,1]
	v_mov_b32_e32 v108, v125
	v_pk_mul_f32 v[12:13], v[28:29], v[12:13] op_sel_hi:[1,0]
	v_pk_mul_f32 v[66:67], v[58:59], v[58:59]
	v_pk_mul_f32 v[60:61], v[44:45], v[44:45]
	v_pk_fma_f32 v[28:29], v[108:109], v[56:57], v[12:13] op_sel_hi:[1,0,1] neg_lo:[0,0,1] neg_hi:[0,0,1]
	v_pk_mul_f32 v[68:69], v[52:53], v[52:53]
	v_pk_mul_f32 v[12:13], v[28:29], v[28:29]
	v_mov_b32_e32 v56, v60
	v_mov_b32_e32 v57, v66
	v_mov_b32_e32 v66, v61
	v_pk_add_f32 v[56:57], v[56:57], v[66:67]
	v_mov_b32_e32 v60, v13
	v_mov_b32_e32 v61, v69
	v_pk_add_f32 v[56:57], v[60:61], v[56:57]
	v_mov_b32_e32 v13, v68
	v_pk_add_f32 v[12:13], v[12:13], v[56:57]
	ds_bpermute_b32 v57, v48, v13
	ds_bpermute_b32 v56, v48, v12
	v_mul_f32_e32 v51, v51, v73
	v_mul_f32_e32 v51, v129, v51
	v_cvt_pk_bf16_f32 v51, v51, s0
	v_mul_f32_e32 v68, v50, v73
	v_mul_f32_e32 v50, 0x45800000, v81
	global_store_short v[26:27], v51, off offset:128
	v_cndmask_b32_e32 v60, v81, v50, vcc
	s_waitcnt lgkmcnt(0)
; DI u16 f2bf(float a) { return (u16)(pk2(a, 0.f) & 0xffffu); }
; DI int crow(int i, int h) { return (i & 3) + 8 * (i >> 2) + 4 * h; }
; __device__ __forceinline__ void attn_item_A(const Params& p, int layer, int head, int q0u, char* lds) {
;     ...
; #pragma unroll
;   for (int e = 0; e < 16; ++e) {
;     const int qq = crow(e, h_e);
;     const float ia = __shfl(iA, qq), ib = __shfl(iB, qq);
;     float ov[4];
;     float ss = 0.f;
; #pragma unroll
;     for (int d = 0; d < 4; ++d) { ov[d] = o1[d][e] * ia - o2[d][e] * ib; ss += ov[d] * ov[d]; }
; #pragma unroll
;     for (int x = 16; x >= 1; x >>= 1) ss += __shfl_xor(ss, x);
;     const float rs = rsqrtf(ss * (1.f / 128.f) + LN_EPS);
;     const size_t rowoff = (size_t)(orow0 + qq) * LDX + ocol + r_e;
; #pragma unroll
;     for (int d = 0; d < 4; ++d) Mx[rowoff + d * 32] = f2bf(ov[d] * rs * sw[d]);
;   }
	v_pk_add_f32 v[50:51], v[12:13], v[56:57]
	ds_bpermute_b32 v57, v49, v51
	ds_bpermute_b32 v56, v49, v50
	v_add_u32_e32 v12, v74, v191
	v_mul_f32_e32 v42, v42, v60
	v_mad_i64_i32 v[12:13], s[0:1], v12, s77, v[16:17]
	s_waitcnt lgkmcnt(0)
	v_pk_add_f32 v[50:51], v[50:51], v[56:57]
	ds_bpermute_b32 v57, v64, v51
	ds_bpermute_b32 v56, v64, v50
	v_mul_f32_e32 v42, v131, v42
	v_cvt_pk_bf16_f32 v42, v42, s0
	global_store_short v[12:13], v42, off
	v_mul_f32_e32 v61, v43, v60
	s_waitcnt lgkmcnt(0)
	v_pk_add_f32 v[42:43], v[50:51], v[56:57]
	ds_bpermute_b32 v51, v65, v43
	ds_bpermute_b32 v50, v65, v42
	v_mul_f32_e32 v69, v54, v60
	v_mul_f32_e32 v55, v55, v60
	v_mul_f32_e32 v56, v130, v61
	v_mul_f32_e32 v55, v129, v55
	s_waitcnt lgkmcnt(0)
	v_pk_add_f32 v[42:43], v[42:43], v[50:51]
	ds_bpermute_b32 v51, v80, v43
	ds_bpermute_b32 v50, v80, v42
	v_cvt_pk_bf16_f32 v56, v56, s0
	v_cvt_pk_bf16_f32 v55, v55, s0
	global_load_dword v128, v210, s[54:55] offset:384
	v_add_u32_e32 v74, 26, v134
	s_waitcnt lgkmcnt(0)
	v_pk_add_f32 v[42:43], v[42:43], v[50:51]
	v_add_u32_e32 v76, 27, v134
	v_pk_fma_f32 v[42:43], v[42:43], s[28:29], v[32:33] op_sel_hi:[1,0,0]
	v_mov_b32_e32 v66, v14
	v_mul_f32_e32 v50, 0x4b800000, v43
	v_cmp_gt_f32_e32 vcc, s80, v43
	v_mov_b32_e32 v67, v30
	v_and_or_b32 v14, v76, 63, v187
	v_cndmask_b32_e32 v43, v43, v50, vcc
	v_rsq_f32_e32 v43, v43
	v_add_u32_e32 v50, v82, v191
	v_mad_i64_i32 v[50:51], s[0:1], v50, s77, v[16:17]
	v_mul_f32_e32 v54, 0x45800000, v43
	v_cndmask_b32_e32 v71, v43, v54, vcc
	v_mul_f32_e32 v43, v58, v71
	v_mul_f32_e32 v43, v131, v43
	v_cvt_pk_bf16_f32 v43, v43, s0
	global_store_short v[50:51], v43, off
	v_mul_f32_e32 v43, v59, v71
	v_mul_f32_e32 v43, v130, v43
	v_cvt_pk_bf16_f32 v43, v43, s0
	global_store_short v[50:51], v43, off offset:64
	v_mul_f32_e32 v43, v53, v71
	v_mul_f32_e32 v43, v129, v43
	v_cvt_pk_bf16_f32 v53, v43, s0
	v_mul_f32_e32 v43, 0x4b800000, v42
	v_cmp_gt_f32_e32 vcc, s80, v42
	v_mov_b32_e32 v58, v62
	v_mov_b32_e32 v59, v46
	v_cndmask_b32_e32 v42, v42, v43, vcc
	v_rsq_f32_e32 v73, v42
	v_and_or_b32 v42, v74, 62, v187
	v_lshlrev_b32_e32 v43, 2, v42
	ds_bpermute_b32 v54, v43, v132
	ds_bpermute_b32 v42, v43, v133
	global_store_short v[12:13], v56, off offset:64
	global_store_short v[12:13], v55, off offset:128
	v_mov_b32_e32 v56, v78
	v_mov_b32_e32 v57, v94
	s_waitcnt lgkmcnt(1)
	v_pk_mul_f32 v[58:59], v[58:59], v[54:55] op_sel_hi:[1,0]
	v_mov_b32_e32 v60, v126
	v_mov_b32_e32 v61, v110
	v_pk_mul_f32 v[54:55], v[66:67], v[54:55] op_sel_hi:[1,0]
	v_lshlrev_b32_e32 v14, 2, v14
	s_waitcnt lgkmcnt(0)
	v_pk_fma_f32 v[56:57], v[56:57], v[42:43], v[58:59] op_sel_hi:[1,0,1] neg_lo:[0,0,1] neg_hi:[0,0,1]
	v_pk_fma_f32 v[42:43], v[60:61], v[42:43], v[54:55] op_sel_hi:[1,0,1] neg_lo:[0,0,1] neg_hi:[0,0,1]
	ds_bpermute_b32 v55, v14, v132
	ds_bpermute_b32 v54, v14, v133
	v_mov_b32_e32 v46, v63
	v_mov_b32_e32 v94, v79
	v_pk_mul_f32 v[58:59], v[56:57], v[56:57]
	s_waitcnt lgkmcnt(1)
	v_mov_b32_e32 v14, v55
	v_pk_mul_f32 v[46:47], v[46:47], v[14:15] op_sel_hi:[1,0]
	v_mov_b32_e32 v14, v127
	s_waitcnt lgkmcnt(0)
	v_pk_mul_f32 v[14:15], v[14:15], v[54:55]
	v_pk_fma_f32 v[46:47], v[94:95], v[54:55], v[46:47] op_sel_hi:[1,0,1] neg_lo:[0,0,1] neg_hi:[0,0,1]
	v_mul_f32_e32 v67, v111, v54
	v_mul_f32_e32 v31, v31, v55
	v_mov_b32_e32 v66, v14
	v_mov_b32_e32 v30, v15
	v_pk_mul_f32 v[62:63], v[46:47], v[46:47]
	v_pk_add_f32 v[14:15], v[66:67], v[30:31] neg_lo:[0,1] neg_hi:[0,1]
	v_pk_mul_f32 v[60:61], v[42:43], v[42:43]
	v_pk_mul_f32 v[30:31], v[14:15], v[14:15]
	v_mov_b32_e32 v54, v62
	v_mov_b32_e32 v55, v58
	v_mov_b32_e32 v58, v63
	v_pk_add_f32 v[54:55], v[54:55], v[58:59]
	v_mov_b32_e32 v58, v31
	v_mov_b32_e32 v59, v61
	v_pk_add_f32 v[54:55], v[58:59], v[54:55]
	v_mov_b32_e32 v31, v60
	v_pk_add_f32 v[30:31], v[30:31], v[54:55]
	ds_bpermute_b32 v55, v48, v31
	ds_bpermute_b32 v54, v48, v30
	global_store_short v[50:51], v53, off offset:128
	v_mul_f32_e32 v58, v52, v71
	v_mul_f32_e32 v48, 0x45800000, v73
	v_cndmask_b32_e32 v59, v73, v48, vcc
	s_waitcnt lgkmcnt(0)
	v_pk_add_f32 v[30:31], v[30:31], v[54:55]
	ds_bpermute_b32 v53, v49, v31
	ds_bpermute_b32 v52, v49, v30
	v_add_u32_e32 v48, v70, v191
	v_mul_f32_e32 v44, v44, v59
	v_mad_i64_i32 v[48:49], s[0:1], v48, s77, v[16:17]
	s_waitcnt lgkmcnt(0)
; DI u16 f2bf(float a) { return (u16)(pk2(a, 0.f) & 0xffffu); }
; DI int crow(int i, int h) { return (i & 3) + 8 * (i >> 2) + 4 * h; }
; __device__ __forceinline__ void attn_item_A(const Params& p, int layer, int head, int q0u, char* lds) {
;     ...
; #pragma unroll
;   for (int e = 0; e < 16; ++e) {
;     const int qq = crow(e, h_e);
;     const float ia = __shfl(iA, qq), ib = __shfl(iB, qq);
;     float ov[4];
;     float ss = 0.f;
; #pragma unroll
;     for (int d = 0; d < 4; ++d) { ov[d] = o1[d][e] * ia - o2[d][e] * ib; ss += ov[d] * ov[d]; }
; #pragma unroll
;     for (int x = 16; x >= 1; x >>= 1) ss += __shfl_xor(ss, x);
;     const float rs = rsqrtf(ss * (1.f / 128.f) + LN_EPS);
;     const size_t rowoff = (size_t)(orow0 + qq) * LDX + ocol + r_e;
; #pragma unroll
;     for (int d = 0; d < 4; ++d) Mx[rowoff + d * 32] = f2bf(ov[d] * rs * sw[d]);
;   }
	v_pk_add_f32 v[30:31], v[30:31], v[52:53]
	ds_bpermute_b32 v53, v64, v31
	ds_bpermute_b32 v52, v64, v30
	v_mul_f32_e32 v44, v131, v44
	v_cvt_pk_bf16_f32 v44, v44, s0
	global_store_short v[48:49], v44, off
	v_mul_f32_e32 v54, v45, v59
	s_waitcnt lgkmcnt(0)
	v_pk_add_f32 v[30:31], v[30:31], v[52:53]
	ds_bpermute_b32 v45, v65, v31
	ds_bpermute_b32 v44, v65, v30
	v_mul_f32_e32 v29, v29, v59
	v_mul_f32_e32 v52, v130, v54
	v_mul_f32_e32 v29, v129, v29
	v_cvt_pk_bf16_f32 v52, v52, s0
	s_waitcnt lgkmcnt(0)
	v_pk_add_f32 v[30:31], v[30:31], v[44:45]
	ds_bpermute_b32 v45, v80, v31
	ds_bpermute_b32 v44, v80, v30
	v_cvt_pk_bf16_f32 v29, v29, s0
	global_store_short v[48:49], v52, off offset:64
	global_store_short v[48:49], v29, off offset:128
	v_mul_f32_e32 v52, v28, v59
	s_waitcnt lgkmcnt(0)
	v_pk_add_f32 v[28:29], v[30:31], v[44:45]
	s_nop 0
	v_pk_fma_f32 v[28:29], v[28:29], s[28:29], v[32:33] op_sel_hi:[1,0,0]
	s_nop 0
	v_mul_f32_e32 v30, 0x4b800000, v29
	v_cmp_gt_f32_e32 vcc, s80, v29
	v_mul_f32_e32 v33, 0x4b800000, v28
	s_nop 0
	v_cndmask_b32_e32 v29, v29, v30, vcc
	v_rsq_f32_e32 v29, v29
	v_add_u32_e32 v30, v74, v191
	v_mad_i64_i32 v[30:31], s[0:1], v30, s77, v[16:17]
	v_mul_f32_e32 v32, 0x45800000, v29
	v_cndmask_b32_e32 v29, v29, v32, vcc
	v_mul_f32_e32 v32, v56, v29
	v_mul_f32_e32 v32, v131, v32
	v_cvt_pk_bf16_f32 v32, v32, s0
	global_store_short v[30:31], v32, off
	v_mul_f32_e32 v32, v57, v29
	v_cmp_gt_f32_e32 vcc, s80, v28
	v_mul_f32_e32 v32, v130, v32
	v_cvt_pk_bf16_f32 v32, v32, s0
	v_cndmask_b32_e32 v28, v28, v33, vcc
	v_rsq_f32_e32 v28, v28
	global_store_short v[30:31], v32, off offset:64
	v_mul_f32_e32 v32, v43, v29
	v_mul_f32_e32 v32, v129, v32
	v_cvt_pk_bf16_f32 v32, v32, s0
	global_store_short v[30:31], v32, off offset:128
	v_mul_f32_e32 v32, 0x45800000, v28
	v_cndmask_b32_e32 v167, v28, v32, vcc
	v_add_u32_e32 v28, v76, v191
	v_mad_i64_i32 v[16:17], s[0:1], v28, s77, v[16:17]
	v_mul_f32_e32 v28, v46, v167
	v_mul_f32_e32 v28, v131, v28
	v_cvt_pk_bf16_f32 v28, v28, s0
	v_mul_f32_e32 v15, v15, v167
	global_store_short v[16:17], v28, off
	v_mul_f32_e32 v28, v47, v167
	v_mul_f32_e32 v15, v129, v15
	v_mul_f32_e32 v28, v130, v28
	v_cvt_pk_bf16_f32 v15, v15, s0
	v_mov_b32_e32 v129, v14
	v_cvt_pk_bf16_f32 v28, v28, s0
	global_store_short v[16:17], v15, off offset:128
	s_waitcnt vmcnt(13)
	v_pk_mul_f32 v[14:15], v[128:129], v[166:167]
	global_store_short v[16:17], v28, off offset:64
	v_mul_f32_e32 v28, v14, v34
	v_cvt_pk_bf16_f32 v28, v28, s0
	global_store_short v[0:1], v28, off offset:192
	v_mul_f32_e32 v0, v14, v35
	v_cvt_pk_bf16_f32 v0, v0, s0
	global_store_short v[2:3], v0, off offset:192
	v_mul_f32_e32 v0, v14, v36
	v_cvt_pk_bf16_f32 v0, v0, s0
	global_store_short v[18:19], v0, off offset:192
	v_mul_f32_e32 v0, v14, v37
	v_cvt_pk_bf16_f32 v0, v0, s0
	global_store_short v[4:5], v0, off offset:192
	v_mul_f32_e32 v0, v14, v38
	v_cvt_pk_bf16_f32 v0, v0, s0
	global_store_short v[20:21], v0, off offset:192
	v_mul_f32_e32 v0, v14, v39
	v_cvt_pk_bf16_f32 v0, v0, s0
	global_store_short v[6:7], v0, off offset:192
	v_mul_f32_e32 v0, v14, v40
	v_cvt_pk_bf16_f32 v0, v0, s0
	global_store_short v[22:23], v0, off offset:192
	v_mul_f32_e32 v0, v14, v41
	v_cvt_pk_bf16_f32 v0, v0, s0
	global_store_short v[8:9], v0, off offset:192
	v_mul_f32_e32 v0, v14, v75
	v_cvt_pk_bf16_f32 v0, v0, s0
	global_store_short v[24:25], v0, off offset:192
	v_mul_f32_e32 v0, v14, v72
	v_cvt_pk_bf16_f32 v0, v0, s0
	global_store_short v[10:11], v0, off offset:192
	v_mul_f32_e32 v0, v14, v68
	v_cvt_pk_bf16_f32 v0, v0, s0
	global_store_short v[26:27], v0, off offset:192
	v_mul_f32_e32 v0, v14, v69
	v_cvt_pk_bf16_f32 v0, v0, s0
	global_store_short v[12:13], v0, off offset:192
	v_mul_f32_e32 v0, v14, v58
	v_cvt_pk_bf16_f32 v0, v0, s0
	global_store_short v[50:51], v0, off offset:192
	v_mul_f32_e32 v0, v14, v52
	v_mul_f32_e32 v29, v42, v29
	v_cvt_pk_bf16_f32 v0, v0, s0
	global_store_short v[48:49], v0, off offset:192
	v_mul_f32_e32 v0, v14, v29
	v_cvt_pk_bf16_f32 v0, v0, s0
	global_store_short v[30:31], v0, off offset:192
	v_mul_f32_e32 v0, v14, v15
	s_branch .LBB0_1476

; DI float bflo(unsigned u) { return __uint_as_float(u << 16); }
; DI float bfhi(unsigned u) { return __uint_as_float(u & 0xffff0000u); }
; __device__ __forceinline__ void attn_item_A(const Params& p, int layer, int head, int q0u, char* lds) {
;     ...
;   {
;     const u16* qg = P + (size_t)(q0u + wid * 32 + r) * LDP + qcol + 8 * h;
;     float nA = 0.f, nB = 0.f;
; #pragma unroll
;     for (int s = 0; s < 8; ++s) {
;       const u32x4 q = *(const u32x4*)(qg + 16 * s);
;       *(u32x4*)(Qs + s * 1024) = q;
;       float ss = 0.f;
; #pragma unroll
;       for (int j = 0; j < 4; ++j) { const float a = bflo(q[j]), b = bfhi(q[j]); ss += a * a + b * b; }
;       if (s < 4) nA += ss; else nB += ss;
;     }
;     nA += __shfl_xor(nA, 32); nB += __shfl_xor(nB, 32);
;     const float* km = (const float*)(p.ws + OFF_LAM) + 8 + layer * 24 + head * 2;
;     bA = sqrtf(nA) * km[0] * CS; bB = sqrtf(nB) * km[1] * CS;
;   }
.LBB0_2326:
	v_mov_b32_e32 v36, v211
	s_lshl_b32 s0, s48, 7
	v_ashrrev_i32_e32 v2, 6, v36
	v_and_b32_e32 v16, 31, v36
	v_lshl_add_u32 v190, v2, 5, s82
	v_or_b32_e32 v0, v190, v16
	v_mov_b64_e32 v[12:13], s[14:15]
	v_mad_i64_i32 v[0:1], s[4:5], v0, s68, v[12:13]
	s_ashr_i32 s1, s0, 31
	v_lshrrev_b32_e32 v3, 2, v36
	s_lshl_b64 s[4:5], s[0:1], 1
	v_and_b32_e32 v17, 8, v3
	v_lshl_add_u64 v[0:1], v[0:1], 0, s[4:5]
	v_lshlrev_b32_e32 v164, 1, v17
	v_lshl_add_u64 v[14:15], v[0:1], 0, v[164:165]
	global_load_dwordx4 v[18:21], v[14:15], off
	global_load_dwordx4 v[22:25], v[14:15], off offset:32
	global_load_dwordx4 v[26:29], v[14:15], off offset:64
	global_load_dwordx4 v[30:33], v[14:15], off offset:96
	v_lshlrev_b32_e32 v192, 13, v2
	global_load_dwordx4 v[0:3], v[14:15], off offset:128
	global_load_dwordx4 v[4:7], v[14:15], off offset:160
	global_load_dwordx4 v[8:11], v[14:15], off offset:192
	v_and_b32_e32 v167, 63, v36
	v_lshlrev_b32_e32 v193, 4, v167
	v_or_b32_e32 v40, v192, v193
	s_lshl_b32 s6, s48, 1
	s_ashr_i32 s7, s6, 31
	s_lshl_b64 s[6:7], s[6:7], 2
	s_add_u32 s6, s21, s6
	s_addc_u32 s7, s31, s7
	v_ashrrev_i32_e32 v194, 3, v36
	v_cmp_lt_i32_e32 vcc, v185, v187
	s_mov_b32 s8, 0
	v_mad_u32_u24 v195, v16, s71, v164
	s_waitcnt vmcnt(6)
	ds_write_b128 v40, v[18:21] offset:37888
	v_lshlrev_b32_e32 v34, 16, v18
	v_and_b32_e32 v18, 0xffff0000, v18
	v_lshlrev_b32_e32 v35, 16, v19
	v_and_b32_e32 v19, 0xffff0000, v19
	s_waitcnt vmcnt(5)
	ds_write_b128 v40, v[22:25] offset:38912
	v_lshlrev_b32_e32 v39, 16, v22
	v_and_b32_e32 v22, 0xffff0000, v22
	v_lshlrev_b32_e32 v41, 16, v23
	v_and_b32_e32 v23, 0xffff0000, v23
	v_lshlrev_b32_e32 v37, 16, v20
	v_and_b32_e32 v20, 0xffff0000, v20
	v_lshlrev_b32_e32 v42, 16, v24
	v_and_b32_e32 v24, 0xffff0000, v24
	v_mul_f32_e32 v18, v18, v18
	v_mul_f32_e32 v19, v19, v19
	v_mul_f32_e32 v22, v22, v22
	v_mul_f32_e32 v23, v23, v23
	v_lshlrev_b32_e32 v38, 16, v21
	v_and_b32_e32 v21, 0xffff0000, v21
	v_lshlrev_b32_e32 v43, 16, v25
	v_and_b32_e32 v25, 0xffff0000, v25
	s_waitcnt vmcnt(4)
	ds_write_b128 v40, v[26:29] offset:39936
	v_lshlrev_b32_e32 v44, 16, v26
	v_and_b32_e32 v26, 0xffff0000, v26
	v_lshlrev_b32_e32 v45, 16, v27
	v_and_b32_e32 v27, 0xffff0000, v27
	v_mul_f32_e32 v20, v20, v20
	v_mul_f32_e32 v24, v24, v24
	v_fmac_f32_e32 v18, v34, v34
	v_fmac_f32_e32 v19, v35, v35
	v_fmac_f32_e32 v22, v39, v39
	v_fmac_f32_e32 v23, v41, v41
	v_lshlrev_b32_e32 v46, 16, v28
	v_and_b32_e32 v28, 0xffff0000, v28
	v_mul_f32_e32 v21, v21, v21
	v_mul_f32_e32 v25, v25, v25
	v_mul_f32_e32 v26, v26, v26
	v_mul_f32_e32 v27, v27, v27
	v_fmac_f32_e32 v20, v37, v37
	v_fmac_f32_e32 v24, v42, v42
	v_add_f32_e32 v18, v18, v19
	v_add_f32_e32 v19, v22, v23
	v_lshlrev_b32_e32 v47, 16, v29
	v_and_b32_e32 v29, 0xffff0000, v29
	v_mul_f32_e32 v28, v28, v28
	v_fmac_f32_e32 v21, v38, v38
	v_fmac_f32_e32 v25, v43, v43
	v_fmac_f32_e32 v26, v44, v44
	v_fmac_f32_e32 v27, v45, v45
	v_add_f32_e32 v18, v20, v18
	v_add_f32_e32 v19, v24, v19
	v_mul_f32_e32 v29, v29, v29
	v_fmac_f32_e32 v28, v46, v46
	v_add_f32_e32 v22, v26, v27
	v_add_f32_e32 v18, v21, v18
	v_add_f32_e32 v19, v25, v19
	s_waitcnt vmcnt(3)
	ds_write_b128 v40, v[30:33] offset:40960
	v_lshlrev_b32_e32 v48, 16, v30
	v_and_b32_e32 v30, 0xffff0000, v30
	v_fmac_f32_e32 v29, v47, v47
	v_add_f32_e32 v20, v28, v22
	v_add_f32_e32 v18, v18, v19
	v_and_b32_e32 v19, 0xffff0000, v31
	v_lshlrev_b32_e32 v49, 16, v31
	v_mul_f32_e32 v30, v30, v30
	v_add_f32_e32 v20, v29, v20
	v_mul_f32_e32 v19, v19, v19
	v_and_b32_e32 v21, 0xffff0000, v32
	v_fmac_f32_e32 v30, v48, v48
	v_add_f32_e32 v18, v18, v20
	v_fmac_f32_e32 v19, v49, v49
	v_lshlrev_b32_e32 v20, 16, v32
	v_mul_f32_e32 v21, v21, v21
	v_add_f32_e32 v19, v30, v19
	v_fmac_f32_e32 v21, v20, v20
	v_add_f32_e32 v19, v21, v19
	v_and_b32_e32 v21, 0xffff0000, v33
	v_lshlrev_b32_e32 v20, 16, v33
	v_mul_f32_e32 v21, v21, v21
	v_fmac_f32_e32 v21, v20, v20
	v_add_f32_e32 v19, v21, v19
	v_add_f32_e32 v41, v18, v19
	s_waitcnt vmcnt(2)
	v_and_b32_e32 v19, 0xffff0000, v0
	v_lshlrev_b32_e32 v18, 16, v0
	v_mul_f32_e32 v22, v19, v19
	v_fmac_f32_e32 v22, v18, v18
	global_load_dwordx4 v[18:21], v[14:15], off offset:224
	global_load_dwordx2 v[34:35], v165, s[6:7]
	v_and_b32_e32 v24, 0xffff0000, v1
	v_lshlrev_b32_e32 v23, 16, v1
	v_mul_f32_e32 v14, v24, v24
	v_fmac_f32_e32 v14, v23, v23
	v_add_f32_e32 v14, v22, v14
	v_and_b32_e32 v22, 0xffff0000, v2
	v_lshlrev_b32_e32 v15, 16, v2
	v_mul_f32_e32 v22, v22, v22
	v_fmac_f32_e32 v22, v15, v15
	v_add_f32_e32 v14, v22, v14
	v_and_b32_e32 v22, 0xffff0000, v3
	v_lshlrev_b32_e32 v15, 16, v3
	v_mul_f32_e32 v22, v22, v22
	v_fmac_f32_e32 v22, v15, v15
	v_add_f32_e32 v14, v22, v14
	s_waitcnt vmcnt(3)
	v_and_b32_e32 v22, 0xffff0000, v4
	v_lshlrev_b32_e32 v15, 16, v4
	v_mul_f32_e32 v22, v22, v22
	v_and_b32_e32 v23, 0xffff0000, v5
	v_fmac_f32_e32 v22, v15, v15
	v_lshlrev_b32_e32 v15, 16, v5
	v_mul_f32_e32 v23, v23, v23
	v_fmac_f32_e32 v23, v15, v15
	v_add_f32_e32 v15, v22, v23
	v_and_b32_e32 v23, 0xffff0000, v6
	v_lshlrev_b32_e32 v22, 16, v6
	v_mul_f32_e32 v23, v23, v23
	v_fmac_f32_e32 v23, v22, v22
	v_add_f32_e32 v15, v23, v15
	v_and_b32_e32 v23, 0xffff0000, v7
	v_lshlrev_b32_e32 v22, 16, v7
	v_mul_f32_e32 v23, v23, v23
	v_fmac_f32_e32 v23, v22, v22
	v_add_f32_e32 v15, v23, v15
	v_add_f32_e32 v42, v14, v15
	s_waitcnt vmcnt(2)
; __device__ __forceinline__ void attn_item_A(const Params& p, int layer, int head, int q0u, char* lds) {
;     ...
;     nA += __shfl_xor(nA, 32); nB += __shfl_xor(nB, 32);
;     const float* km = (const float*)(p.ws + OFF_LAM) + 8 + layer * 24 + head * 2;
;     bA = sqrtf(nA) * km[0] * CS; bB = sqrtf(nB) * km[1] * CS;
;   }
;   const int srow = tid >> 3, sseg = (tid & 7) * 16;
;   const u16* VTg = (const u16*)(p.ws + OFF_VT) + (size_t)(head * 128 + (tid >> 1)) * LDVT + (tid & 1) * 16;
;   float lA = 0.f, lB = 0.f;
;   f32x16 o1[4], o2[4];
; #pragma unroll
;   for (int d = 0; d < 4; ++d)
; #pragma unroll
;     for (int e = 0; e < 16; ++e) { o1[d][e] = 0.f; o2[d][e] = 0.f; }
;   u32x4 rk0, rk1, rv0, rv1;
;   const u16* gnext;
;   ATT_LOADK(0); ATT_LOADV(0);
;   ATT_STOREK(0); ATT_STOREV(0);
;   __syncthreads();
	v_and_b32_e32 v15, 0xffff0000, v8
	v_lshlrev_b32_e32 v14, 16, v8
	v_mul_f32_e32 v15, v15, v15
	v_and_b32_e32 v22, 0xffff0000, v9
	v_fmac_f32_e32 v15, v14, v14
	v_lshlrev_b32_e32 v14, 16, v9
	v_mul_f32_e32 v22, v22, v22
	v_fmac_f32_e32 v22, v14, v14
	v_add_f32_e32 v14, v15, v22
	v_and_b32_e32 v22, 0xffff0000, v10
	v_lshlrev_b32_e32 v15, 16, v10
	v_mul_f32_e32 v22, v22, v22
	v_fmac_f32_e32 v22, v15, v15
	v_ashrrev_i32_e32 v46, 1, v36
	v_lshlrev_b32_e32 v28, 5, v36
	v_add_f32_e32 v43, v22, v14
	v_add_u32_e32 v22, s0, v46
	v_mov_b64_e32 v[14:15], s[16:17]
	v_mad_i64_i32 v[12:13], s[0:1], v194, s68, v[12:13]
	v_and_b32_e32 v36, 0xe0, v28
	v_mov_b32_e32 v37, v165
	v_mad_i64_i32 v[26:27], s[0:1], v22, s70, v[14:15]
	v_lshl_add_u64 v[12:13], v[12:13], 0, v[36:37]
	v_and_b32_e32 v38, 32, v28
	v_mov_b32_e32 v39, v165
	v_lshl_add_u64 v[22:23], v[12:13], 0, s[4:5]
	v_lshl_add_u64 v[170:171], v[26:27], 0, v[38:39]
	global_load_dwordx4 v[12:15], v[22:23], off offset:1040
	s_nop 0
	global_load_dwordx4 v[22:25], v[22:23], off offset:1024
	s_nop 0
	global_load_dwordx4 v[26:29], v[170:171], off offset:16
	global_load_dwordx4 v[30:33], v[170:171], off
	v_and_b32_e32 v45, 0xffff0000, v11
	v_lshlrev_b32_e32 v44, 16, v11
	v_mul_f32_e32 v39, v45, v45
	v_fmac_f32_e32 v39, v44, v44
	v_add_f32_e32 v39, v39, v43
	v_add_f32_e32 v39, v42, v39
	ds_write_b128 v40, v[0:3] offset:41984
	ds_write_b128 v40, v[4:7] offset:43008
	ds_write_b128 v40, v[8:11] offset:44032
	s_waitcnt vmcnt(5)
	ds_write_b128 v40, v[18:21] offset:45056
	s_mov_b32 s6, 32
	v_and_b32_e32 v43, 0xffff0000, v18
	v_lshlrev_b32_e32 v42, 16, v18
	v_mul_f32_e32 v43, v43, v43
	v_and_b32_e32 v44, 0xffff0000, v19
	v_fmac_f32_e32 v43, v42, v42
	v_lshlrev_b32_e32 v42, 16, v19
	v_mul_f32_e32 v44, v44, v44
	v_fmac_f32_e32 v44, v42, v42
	v_add_f32_e32 v42, v43, v44
	v_and_b32_e32 v44, 0xffff0000, v20
	v_lshlrev_b32_e32 v43, 16, v20
	v_mul_f32_e32 v44, v44, v44
	v_fmac_f32_e32 v44, v43, v43
	v_add_f32_e32 v42, v44, v42
	v_and_b32_e32 v44, 0xffff0000, v21
	v_lshlrev_b32_e32 v43, 16, v21
	v_mul_f32_e32 v44, v44, v44
	v_fmac_f32_e32 v44, v43, v43
	v_add_f32_e32 v42, v44, v42
	v_add_f32_e32 v39, v39, v42
	v_cndmask_b32_e32 v42, v214, v185, vcc
	v_lshlrev_b32_e32 v191, 2, v42
	ds_bpermute_b32 v42, v191, v39
	ds_bpermute_b32 v3, v191, v41
	s_waitcnt lgkmcnt(1)
	v_add_f32_e32 v0, v39, v42
	v_mul_f32_e32 v1, 0x4f800000, v0
	v_cmp_gt_f32_e32 vcc, s69, v0
	s_waitcnt lgkmcnt(0)
	v_add_f32_e32 v3, v41, v3
	v_cndmask_b32_e32 v1, v0, v1, vcc
	v_sqrt_f32_e32 v2, v1
	v_mov_b32_e32 v0, 0
	v_mov_b32_e32 v6, v0
	v_mov_b32_e32 v7, v0
	v_add_u32_e32 v4, -1, v2
	v_fma_f32 v5, -v4, v2, v1
	v_cmp_ge_f32_e64 s[0:1], 0, v5
	v_add_u32_e32 v5, 1, v2
	v_mov_b32_e32 v8, v0
	v_cndmask_b32_e64 v4, v2, v4, s[0:1]
	v_fma_f32 v2, -v5, v2, v1
	v_cmp_lt_f32_e64 s[0:1], 0, v2
	v_mov_b32_e32 v9, v0
	v_mov_b32_e32 v10, v0
	v_cndmask_b32_e64 v2, v4, v5, s[0:1]
	v_mul_f32_e32 v4, 0x37800000, v2
	v_cndmask_b32_e32 v2, v2, v4, vcc
	v_mul_f32_e32 v4, 0x4f800000, v3
	v_cmp_gt_f32_e32 vcc, s69, v3
	v_cmp_class_f32_e64 s[0:1], v1, v182
	v_mov_b32_e32 v11, v0
	v_cndmask_b32_e32 v3, v3, v4, vcc
	v_sqrt_f32_e32 v4, v3
	v_cndmask_b32_e64 v1, v2, v1, s[0:1]
	s_waitcnt vmcnt(4)
	v_mul_f32_e32 v1, v35, v1
	v_mov_b32_e32 v18, v0
	v_add_u32_e32 v2, -1, v4
	v_fma_f32 v5, -v2, v4, v3
	v_cmp_ge_f32_e64 s[0:1], 0, v5
	v_add_u32_e32 v5, 1, v4
	v_mov_b32_e32 v19, v0
	v_cndmask_b32_e64 v2, v4, v2, s[0:1]
	v_fma_f32 v4, -v5, v4, v3
	v_cmp_lt_f32_e64 s[0:1], 0, v4
	v_mov_b32_e32 v20, v0
	v_mov_b32_e32 v21, v0
	v_cndmask_b32_e64 v2, v2, v5, s[0:1]
	v_mul_f32_e32 v4, 0x37800000, v2
	v_cndmask_b32_e32 v2, v2, v4, vcc
	v_cmp_class_f32_e32 vcc, v3, v182
	v_mad_u64_u32 v[174:175], s[0:1], v46, s72, v[38:39]
	s_nop 0
	v_cndmask_b32_e32 v2, v2, v3, vcc
	v_mul_f32_e32 v4, v34, v2
	v_mad_u64_u32 v[172:173], s[0:1], v194, s71, v[36:37]
	v_add_u32_e32 v2, 0x4400, v174
	s_waitcnt vmcnt(2)
	ds_write_b128 v172, v[22:25]
	ds_write_b128 v172, v[12:15] offset:16
	s_waitcnt vmcnt(0)
	ds_write2_b64 v2, v[30:31], v[32:33] offset1:1
	v_add_u32_e32 v2, 0x4410, v174
	ds_write2_b64 v2, v[26:27], v[28:29] offset1:1
	v_lshl_add_u64 v[2:3], s[14:15], 0, v[36:37]
	v_lshl_add_u64 v[176:177], v[2:3], 0, s[4:5]
	v_mul_u32_u24_e32 v2, 0x110, v16
	v_mul_f32_e32 v173, 0xbe38aa3b, v1
	v_mul_i32_i24_e32 v1, 0xffffff38, v16
	v_mul_f32_e32 v175, 0xbe38aa3b, v4
	v_add3_u32 v164, v2, v1, v17
	v_mov_b32_e32 v1, v0
	v_mov_b32_e32 v2, v0
	v_mov_b32_e32 v3, v0
	v_mov_b32_e32 v4, v0
	v_mov_b32_e32 v5, v0
	v_mov_b32_e32 v12, v0
	v_mov_b32_e32 v13, v0
	v_mov_b32_e32 v14, v0
	v_mov_b32_e32 v15, v0
	v_mov_b32_e32 v16, v0
	v_mov_b32_e32 v17, v0
	v_mov_b32_e32 v22, v0
	v_mov_b32_e32 v23, v0
	v_mov_b32_e32 v24, v0
	v_mov_b32_e32 v25, v0
	v_mov_b32_e32 v26, v0
	v_mov_b32_e32 v27, v0
	v_mov_b32_e32 v28, v0
	v_mov_b32_e32 v29, v0
	v_mov_b32_e32 v30, v0
	v_mov_b32_e32 v31, v0
	v_mov_b32_e32 v32, v0
	v_mov_b32_e32 v33, v0
	v_mov_b32_e32 v34, v0
	v_mov_b32_e32 v35, v0
	v_mov_b32_e32 v36, v0
	v_mov_b32_e32 v37, v0
	v_mov_b32_e32 v38, v0
	v_mov_b32_e32 v39, v0
	v_mov_b32_e32 v40, v0
	v_mov_b32_e32 v41, v0
	v_mov_b32_e32 v42, v0
	v_mov_b32_e32 v43, v0
	v_mov_b32_e32 v44, v0
	v_mov_b32_e32 v45, v0
	v_mov_b32_e32 v46, v0
	v_mov_b32_e32 v47, v0
	v_mov_b32_e32 v48, v0
	v_mov_b32_e32 v49, v0
	v_mov_b32_e32 v50, v0
	v_mov_b32_e32 v51, v0
	v_mov_b32_e32 v52, v0
	v_mov_b32_e32 v53, v0
	v_mov_b32_e32 v54, v0
	v_mov_b32_e32 v55, v0
	v_mov_b32_e32 v56, v0
	v_mov_b32_e32 v57, v0
	v_mov_b32_e32 v58, v0
	v_mov_b32_e32 v59, v0
	v_mov_b32_e32 v60, v0
	v_mov_b32_e32 v61, v0
	v_mov_b32_e32 v62, v0
	v_mov_b32_e32 v63, v0
	v_mov_b32_e32 v64, v0
; #define MFMA32(a, b, c) __builtin_amdgcn_mfma_f32_32x32x16_bf16((a), (b), (c), 0, 0, 0)
; __device__ __forceinline__ void attn_item_A(const Params& p, int layer, int head, int q0u, char* lds) {
;     ...
; #pragma unroll
;   for (int d = 0; d < 4; ++d)
; #pragma unroll
;     for (int e = 0; e < 16; ++e) { o1[d][e] = 0.f; o2[d][e] = 0.f; }
;     ...
;   for (int t = 0; t < ntiles; ++t) {
;     const int buf = t & 1;
;     const bool more = (t + 1 < ntiles);
;     if (more) { ATT_LOADK(t + 1); ATT_LOADV(t + 1); }
;     const u16* kt_ = Ks + buf * 32 * KLD + r * KLD + 8 * h;
;     bf16x8 a0, a1, b0, b1;
;     {
;       f32x16 sx, sy;
; #pragma unroll
;       for (int e = 0; e < 16; ++e) { sx[e] = 0.f; sy[e] = 0.f; }
; #pragma unroll
;       for (int s = 0; s < 4; ++s) {
;         const bf16x8 kf = *(const bf16x8*)(kt_ + 16 * s);
;         const bf16x8 qf = *(const bf16x8*)(Qs + s * 1024);
;         sx = MFMA32(kf, qf, sx);
;       }
; #pragma unroll
;       for (int s = 4; s < 8; ++s) {
;         const bf16x8 kf = *(const bf16x8*)(kt_ + 16 * s);
;         const bf16x8 qf = *(const bf16x8*)(Qs + s * 1024);
;         sy = MFMA32(kf, qf, sy);
;       }
	v_mov_b32_e32 v65, v0
	v_mov_b32_e32 v66, v0
	v_mov_b32_e32 v67, v0
	v_mov_b32_e32 v68, v0
	v_mov_b32_e32 v69, v0
	v_mov_b32_e32 v70, v0
	v_mov_b32_e32 v71, v0
	v_mov_b32_e32 v72, v0
	v_mov_b32_e32 v73, v0
	v_mov_b32_e32 v74, v0
	v_mov_b32_e32 v75, v0
	v_mov_b32_e32 v76, v0
	v_mov_b32_e32 v77, v0
	v_mov_b32_e32 v78, v0
	v_mov_b32_e32 v79, v0
	v_mov_b32_e32 v80, v0
	v_mov_b32_e32 v81, v0
	v_mov_b32_e32 v82, v0
	v_mov_b32_e32 v83, v0
	v_mov_b32_e32 v84, v0
	v_mov_b32_e32 v85, v0
	v_mov_b32_e32 v86, v0
	v_mov_b32_e32 v87, v0
	v_mov_b32_e32 v88, v0
	v_mov_b32_e32 v89, v0
	v_mov_b32_e32 v90, v0
	v_mov_b32_e32 v91, v0
	v_mov_b32_e32 v92, v0
	v_mov_b32_e32 v93, v0
	v_mov_b32_e32 v94, v0
	v_mov_b32_e32 v95, v0
	v_mov_b32_e32 v96, v0
	v_mov_b32_e32 v97, v0
	v_mov_b32_e32 v98, v0
	v_mov_b32_e32 v99, v0
	v_mov_b32_e32 v100, v0
	v_mov_b32_e32 v101, v0
	v_mov_b32_e32 v102, v0
	v_mov_b32_e32 v103, v0
	v_mov_b32_e32 v104, v0
	v_mov_b32_e32 v105, v0
	v_mov_b32_e32 v106, v0
	v_mov_b32_e32 v107, v0
	v_mov_b32_e32 v108, v0
	v_mov_b32_e32 v109, v0
	v_mov_b32_e32 v110, v0
	v_mov_b32_e32 v111, v0
	v_mov_b32_e32 v112, v0
	v_mov_b32_e32 v113, v0
	v_mov_b32_e32 v114, v0
	v_mov_b32_e32 v115, v0
	v_mov_b32_e32 v116, v0
	v_mov_b32_e32 v117, v0
	v_mov_b32_e32 v118, v0
	v_mov_b32_e32 v119, v0
	v_mov_b32_e32 v120, v0
	v_mov_b32_e32 v121, v0
	v_mov_b32_e32 v122, v0
	v_mov_b32_e32 v123, v0
	v_mov_b32_e32 v124, v0
	v_mov_b32_e32 v125, v0
	v_mov_b32_e32 v126, v0
	v_mov_b32_e32 v127, v0
	v_mov_b32_e32 v168, v0
	v_mov_b32_e32 v169, v0
	v_add_u32_e32 v196, v192, v193
	ds_read_b128 v[240:243], v196 offset:39936
	ds_read_b128 v[244:247], v196 offset:40960
	ds_read_b128 v[248:251], v196 offset:44032
	ds_read_b128 v[252:255], v196 offset:45056
	s_and_b32 s0, s8, 1
	s_mul_i32 s1, s0, 0x2200
	v_add_u32_e32 v197, s1, v195
	s_waitcnt lgkmcnt(0)
	s_barrier
	ds_read_b128 v[128:131], v196 offset:37888
	ds_read_b128 v[160:163], v196 offset:38912
	ds_read_b128 v[144:147], v196 offset:41984
	ds_read_b128 v[178:181], v196 offset:43008
	ds_read_b128 v[132:135], v197
	ds_read_b128 v[148:151], v197 offset:128
	ds_read_b128 v[206:209], v197 offset:64
	ds_read_b128 v[220:223], v197 offset:192
	ds_read_b128 v[224:227], v197 offset:224
.LBB0_2327:
	s_setprio 1
	s_and_b32 s0, s8, 1
	s_mul_i32 s1, s0, 0x2200
	ds_read_b128 v[198:201], v197 offset:32
	ds_read_b128 v[202:205], v197 offset:160
	ds_read_b128 v[216:219], v197 offset:96
	s_waitcnt lgkmcnt(7)
	v_mfma_f32_32x32x16_bf16 v[128:143], v[132:135], v[128:131], 0
	s_mul_i32 s1, s0, 0x2400
	s_ashr_i32 s7, s6, 31
	s_xor_b32 s0, s0, 1
	s_add_i32 s8, s8, 1
	s_waitcnt lgkmcnt(6)
	v_mfma_f32_32x32x16_bf16 v[144:159], v[148:151], v[144:147], 0
	s_waitcnt lgkmcnt(2)
	v_mfma_f32_32x32x16_bf16 v[128:143], v[198:201], v[160:163], v[128:143]
	s_waitcnt lgkmcnt(1)
	v_mfma_f32_32x32x16_bf16 v[144:159], v[202:205], v[178:181], v[144:159]
	s_waitcnt lgkmcnt(1)
	v_mfma_f32_32x32x16_bf16 v[128:143], v[206:209], v[240:243], v[128:143]
	v_add_u32_e32 v197, s1, v164
	v_add_u32_e32 v210, 0x4000, v197
	v_add_u32_e32 v215, 0x4800, v197
	v_add_u32_e32 v238, 0x5000, v197
	v_add_u32_e32 v197, 0x5800, v197
	v_lshl_add_u64 v[178:179], s[6:7], 1, v[170:171]
	s_waitcnt lgkmcnt(1)
	v_mfma_f32_32x32x16_bf16 v[144:159], v[220:223], v[248:251], v[144:159]
	v_add_u32_e32 v160, s6, v194
	v_mad_i64_i32 v[180:181], s[10:11], v160, s68, v[176:177]
	global_load_dwordx4 v[160:163], v[180:181], off offset:1040
	s_add_i32 s6, s6, 32
	s_mul_i32 s1, s0, 0x2200
	s_mulk_i32 s0, 0x2400
	s_waitcnt lgkmcnt(0)
	v_mfma_f32_32x32x16_bf16 v[128:143], v[216:219], v[244:247], v[128:143]
	ds_read2_b64 v[198:201], v210 offset0:128 offset1:130
	s_cmpk_eq_i32 s6, 0x4100
	s_waitcnt lgkmcnt(1)
	v_mfma_f32_32x32x16_bf16 v[144:159], v[224:227], v[252:255], v[144:159]
	s_setprio 0
	s_nop 7
	v_fmamk_f32 v128, v128, 0x3e38aa3b, v175
	v_fmamk_f32 v129, v129, 0x3e38aa3b, v175
	v_fmamk_f32 v130, v130, 0x3e38aa3b, v175
	v_fmamk_f32 v131, v131, 0x3e38aa3b, v175
	v_fmamk_f32 v132, v132, 0x3e38aa3b, v175
	v_fmamk_f32 v133, v133, 0x3e38aa3b, v175
	v_fmamk_f32 v202, v134, 0x3e38aa3b, v175
	v_fmamk_f32 v135, v135, 0x3e38aa3b, v175
	v_fmamk_f32 v203, v144, 0x3e38aa3b, v173
	v_fmamk_f32 v145, v145, 0x3e38aa3b, v173
	v_fmamk_f32 v204, v146, 0x3e38aa3b, v173
	v_fmamk_f32 v205, v147, 0x3e38aa3b, v173
	v_fmamk_f32 v206, v148, 0x3e38aa3b, v173
	v_fmamk_f32 v207, v149, 0x3e38aa3b, v173
	v_fmamk_f32 v208, v150, 0x3e38aa3b, v173
	v_fmamk_f32 v209, v151, 0x3e38aa3b, v173
	v_exp_f32_e32 v150, v128
	v_exp_f32_e32 v148, v129
	v_exp_f32_e32 v146, v130
	v_exp_f32_e32 v144, v131
	v_exp_f32_e32 v134, v132
	v_exp_f32_e32 v130, v133
	v_exp_f32_e32 v132, v202
	v_exp_f32_e32 v128, v135
	v_exp_f32_e32 v151, v203
	v_exp_f32_e32 v149, v145
	v_exp_f32_e32 v147, v204
	v_exp_f32_e32 v145, v205
	v_exp_f32_e32 v135, v206
	v_exp_f32_e32 v131, v207
	v_exp_f32_e32 v133, v208
	v_exp_f32_e32 v129, v209
	v_cvt_pk_bf16_f32 v202, v150, v148
	v_cvt_pk_bf16_f32 v203, v146, v144
	v_cvt_pk_bf16_f32 v204, v134, v130
	v_cvt_pk_bf16_f32 v205, v132, v128
	v_cvt_pk_bf16_f32 v206, v151, v149
	v_cvt_pk_bf16_f32 v207, v147, v145
	v_cvt_pk_bf16_f32 v208, v135, v131
	v_cvt_pk_bf16_f32 v209, v133, v129
	s_setprio 1
	s_waitcnt lgkmcnt(0)
	v_mfma_f32_32x32x16_bf16 v[64:79], v[202:205], v[198:201], v[64:79]
	v_fmamk_f32 v152, v152, 0x3e38aa3b, v173
	v_fmamk_f32 v153, v153, 0x3e38aa3b, v173
	v_fmamk_f32 v154, v154, 0x3e38aa3b, v173
	v_fmamk_f32 v155, v155, 0x3e38aa3b, v173
	v_fmamk_f32 v156, v156, 0x3e38aa3b, v173
	v_fmamk_f32 v157, v157, 0x3e38aa3b, v173
	v_fmamk_f32 v158, v158, 0x3e38aa3b, v173
	v_mfma_f32_32x32x16_bf16 v[48:63], v[206:209], v[198:201], v[48:63]
	ds_read2_b64 v[198:201], v215 offset0:160 offset1:162
	ds_read2_b64 v[216:219], v210 offset0:132 offset1:134
	ds_read2_b64 v[220:223], v238 offset0:192 offset1:194
	ds_read2_b64 v[224:227], v197 offset0:224 offset1:226
	v_fmamk_f32 v159, v159, 0x3e38aa3b, v173
	v_exp_f32_e32 v213, v152
	v_exp_f32_e32 v229, v153
	v_exp_f32_e32 v231, v154
	v_exp_f32_e32 v233, v157
	s_waitcnt lgkmcnt(1)
; __device__ __forceinline__ void attn_item_A(const Params& p, int layer, int head, int q0u, char* lds) {
;     ...
;         float w[16];
; #pragma unroll
;         for (int e = 0; e < 16; ++e) { w[e] = __builtin_amdgcn_exp2f(fmaf(sx[e], CS, -bA)); lA += w[e]; }
;         const u32x4 p0 = {pk2(w[0], w[1]), pk2(w[2], w[3]), pk2(w[4], w[5]), pk2(w[6], w[7])};
;         const u32x4 p1 = {pk2(w[8], w[9]), pk2(w[10], w[11]), pk2(w[12], w[13]), pk2(w[14], w[15])};
;         a0 = __builtin_bit_cast(bf16x8, p0); a1 = __builtin_bit_cast(bf16x8, p1);
;       }
;       {
;         float w[16];
; #pragma unroll
;         for (int e = 0; e < 16; ++e) { w[e] = __builtin_amdgcn_exp2f(fmaf(sy[e], CS, -bB)); lB += w[e]; }
;         const u32x4 p0 = {pk2(w[0], w[1]), pk2(w[2], w[3]), pk2(w[4], w[5]), pk2(w[6], w[7])};
;         const u32x4 p1 = {pk2(w[8], w[9]), pk2(w[10], w[11]), pk2(w[12], w[13]), pk2(w[14], w[15])};
;         b0 = __builtin_bit_cast(bf16x8, p0); b1 = __builtin_bit_cast(bf16x8, p1);
;       }
;     }
;     const u16* vt = Vt + buf * 128 * VLD + r * VLD + 4 * h;
; #pragma unroll
;     for (int d = 0; d < 4; d += 2) {
;       const s16x4 l0 = *(const s16x4*)(vt + d * 32 * VLD), h0 = *(const s16x4*)(vt + d * 32 * VLD + 8);
;       const s16x4 l1 = *(const s16x4*)(vt + d * 32 * VLD + 16), h1 = *(const s16x4*)(vt + d * 32 * VLD + 24);
;       const s16x4 m0 = *(const s16x4*)(vt + (d + 1) * 32 * VLD), n0 = *(const s16x4*)(vt + (d + 1) * 32 * VLD + 8);
;       const s16x4 m1 = *(const s16x4*)(vt + (d + 1) * 32 * VLD + 16), n1 = *(const s16x4*)(vt + (d + 1) * 32 * VLD + 24);
;       const bf16x8 v0 = {l0[0], l0[1], l0[2], l0[3], h0[0], h0[1], h0[2], h0[3]};
;       const bf16x8 v1 = {l1[0], l1[1], l1[2], l1[3], h1[0], h1[1], h1[2], h1[3]};
;       const bf16x8 u0 = {m0[0], m0[1], m0[2], m0[3], n0[0], n0[1], n0[2], n0[3]};
;       const bf16x8 u1 = {m1[0], m1[1], m1[2], m1[3], n1[0], n1[1], n1[2], n1[3]};
;       o1[d] = MFMA32(a0, v0, o1[d]);
;       o2[d] = MFMA32(b0, v0, o2[d]);
;       o1[d + 1] = MFMA32(a0, u0, o1[d + 1]);
;       o2[d + 1] = MFMA32(b0, u0, o2[d + 1]);
;       o1[d] = MFMA32(a1, v1, o1[d]);
;       o2[d] = MFMA32(b1, v1, o2[d]);
;       o1[d + 1] = MFMA32(a1, u1, o1[d + 1]);
;       o2[d + 1] = MFMA32(b1, u1, o2[d + 1]);
;     }
;     if (more) { ATT_STOREK(buf ^ 1); ATT_STOREV(buf ^ 1); }
;     __syncthreads();
	v_mfma_f32_32x32x16_bf16 v[96:111], v[202:205], v[220:223], v[96:111]
	v_exp_f32_e32 v235, v158
	v_exp_f32_e32 v237, v159
	v_fmamk_f32 v136, v136, 0x3e38aa3b, v175
	v_fmamk_f32 v137, v137, 0x3e38aa3b, v175
	v_fmamk_f32 v138, v138, 0x3e38aa3b, v175
	v_fmamk_f32 v139, v139, 0x3e38aa3b, v175
	v_fmamk_f32 v140, v140, 0x3e38aa3b, v175
	v_mfma_f32_32x32x16_bf16 v[16:31], v[206:209], v[220:223], v[16:31]
	v_exp_f32_e32 v221, v155
	v_exp_f32_e32 v223, v156
	global_load_dwordx4 v[152:155], v[180:181], off offset:1024
	global_load_dwordx4 v[156:159], v[178:179], off
	v_fmamk_f32 v141, v141, 0x3e38aa3b, v175
	global_load_dwordx4 v[178:181], v[178:179], off offset:16
	v_fmamk_f32 v142, v142, 0x3e38aa3b, v175
	v_fmamk_f32 v143, v143, 0x3e38aa3b, v175
	v_exp_f32_e32 v212, v136
	v_exp_f32_e32 v228, v137
	v_exp_f32_e32 v230, v138
	v_exp_f32_e32 v220, v139
	v_exp_f32_e32 v222, v140
	v_exp_f32_e32 v232, v141
	v_exp_f32_e32 v234, v142
	v_exp_f32_e32 v236, v143
	v_mfma_f32_32x32x16_bf16 v[80:95], v[202:205], v[198:201], v[80:95]
	v_cvt_pk_bf16_f32 v136, v212, v228
	v_cvt_pk_bf16_f32 v137, v230, v220
	v_cvt_pk_bf16_f32 v138, v222, v232
	v_cvt_pk_bf16_f32 v139, v234, v236
	v_cvt_pk_bf16_f32 v140, v213, v229
	v_cvt_pk_bf16_f32 v141, v231, v221
	v_cvt_pk_bf16_f32 v142, v223, v233
	v_mfma_f32_32x32x16_bf16 v[32:47], v[206:209], v[198:201], v[32:47]
	v_cvt_pk_bf16_f32 v143, v235, v237
	ds_read2_b64 v[198:201], v215 offset0:164 offset1:166
	v_add_f32_e64 v150, v168, v150
	v_add_f32_e64 v151, v169, v151
	v_add_f32_e64 v148, v148, v150
	v_add_f32_e64 v149, v149, v151
	v_pk_add_f32 v[146:147], v[146:147], v[148:149]
	s_waitcnt lgkmcnt(1)
	v_mfma_f32_32x32x16_bf16 v[112:127], v[202:205], v[224:227], v[112:127]
	ds_read2_b64 v[202:205], v197 offset0:228 offset1:230
	v_add_f32_e64 v144, v144, v146
	v_add_f32_e64 v145, v145, v147
	v_add_f32_e64 v134, v134, v144
	v_add_f32_e64 v135, v135, v145
	v_pk_add_f32 v[130:131], v[130:131], v[134:135]
	v_mfma_f32_32x32x16_bf16 v[0:15], v[206:209], v[224:227], v[0:15]
	v_add_f32_e64 v130, v132, v130
	v_add_f32_e64 v131, v133, v131
	v_add_u32_e32 v206, s1, v172
	v_add_f32_e64 v128, v128, v130
	v_add_f32_e64 v129, v129, v131
	v_add_u32_e32 v207, s0, v174
	v_pk_add_f32 v[128:129], v[212:213], v[128:129]
	v_add_u32_e32 v197, 0x4400, v207
	v_pk_add_f32 v[128:129], v[228:229], v[128:129]
	s_waitcnt lgkmcnt(1)
	v_mfma_f32_32x32x16_bf16 v[80:95], v[136:139], v[198:201], v[80:95]
	v_add_f32_e64 v128, v230, v128
	v_add_f32_e64 v129, v231, v129
	v_add_u32_e32 v207, 0x4410, v207
	v_add_f32_e64 v128, v220, v128
	v_add_f32_e64 v129, v221, v129
	v_pk_add_f32 v[128:129], v[222:223], v[128:129]
	s_nop 0
	v_pk_add_f32 v[128:129], v[232:233], v[128:129]
	v_mfma_f32_32x32x16_bf16 v[32:47], v[140:143], v[198:201], v[32:47]
	ds_read2_b64 v[198:201], v238 offset0:196 offset1:198
	v_add_f32_e64 v128, v234, v128
	v_add_f32_e64 v129, v235, v129
	s_setprio 0
	s_waitcnt vmcnt(2)
	ds_write_b128 v206, v[152:155]
	ds_write_b128 v206, v[160:163] offset:16
	s_waitcnt vmcnt(1)
	ds_write2_b64 v197, v[156:157], v[158:159] offset1:1
	s_waitcnt vmcnt(0)
	ds_write2_b64 v207, v[178:179], v[180:181] offset1:1
	v_mfma_f32_32x32x16_bf16 v[64:79], v[136:139], v[216:219], v[64:79]
	v_add_f32_e64 v168, v236, v128
	v_add_f32_e64 v169, v237, v129
	v_add_u32_e32 v197, s1, v195
	s_waitcnt lgkmcnt(0)
	s_barrier
	ds_read_b128 v[128:131], v196 offset:37888
	ds_read_b128 v[160:163], v196 offset:38912
	ds_read_b128 v[144:147], v196 offset:41984
	ds_read_b128 v[178:181], v196 offset:43008
	ds_read_b128 v[132:135], v197
	ds_read_b128 v[148:151], v197 offset:128
	ds_read_b128 v[206:209], v197 offset:64
	ds_read_b128 v[220:223], v197 offset:192
	ds_read_b128 v[224:227], v197 offset:224
	v_mfma_f32_32x32x16_bf16 v[48:63], v[140:143], v[216:219], v[48:63]
	v_mfma_f32_32x32x16_bf16 v[96:111], v[136:139], v[198:201], v[96:111]
	v_mfma_f32_32x32x16_bf16 v[16:31], v[140:143], v[198:201], v[16:31]
	v_mfma_f32_32x32x16_bf16 v[112:127], v[136:139], v[202:205], v[112:127]
	v_mfma_f32_32x32x16_bf16 v[0:15], v[140:143], v[202:205], v[0:15]
	s_cbranch_scc0 .LBB0_2327
	ds_read_b128 v[128:131], v195 offset:8704
	ds_read_b128 v[132:135], v196 offset:37888
	ds_read_b128 v[136:139], v195 offset:8736
	ds_read_b128 v[140:143], v196 offset:38912
	s_waitcnt lgkmcnt(2)
	v_mfma_f32_32x32x16_bf16 v[144:159], v[128:131], v[132:135], 0
	ds_read_b128 v[128:131], v195 offset:8768
	ds_read_b128 v[132:135], v196 offset:39936
	ds_read_b128 v[160:163], v195 offset:8800
	ds_read_b128 v[176:179], v196 offset:40960
	s_waitcnt lgkmcnt(4)
	v_mfma_f32_32x32x16_bf16 v[144:159], v[136:139], v[140:143], v[144:159]
	s_waitcnt lgkmcnt(2)
	v_mfma_f32_32x32x16_bf16 v[144:159], v[128:131], v[132:135], v[144:159]
	ds_read_b128 v[128:131], v195 offset:8832
	ds_read_b128 v[132:135], v196 offset:41984
	ds_read_b128 v[198:201], v195 offset:8864
	ds_read_b128 v[202:205], v196 offset:43008
	ds_read_b128 v[206:209], v195 offset:8896
	ds_read_b128 v[192:195], v195 offset:8928
	ds_read_b128 v[216:219], v196 offset:44032
	ds_read_b128 v[220:223], v196 offset:45056
	s_waitcnt lgkmcnt(6)
	v_mfma_f32_32x32x16_bf16 v[128:143], v[128:131], v[132:135], 0
	s_waitcnt lgkmcnt(4)
	v_mfma_f32_32x32x16_bf16 v[128:143], v[198:201], v[202:205], v[128:143]
	s_waitcnt lgkmcnt(1)
	v_mfma_f32_32x32x16_bf16 v[128:143], v[206:209], v[216:219], v[128:143]
	s_waitcnt lgkmcnt(0)
; __device__ __forceinline__ void attn_item_A(const Params& p, int layer, int head, int q0u, char* lds) {
;     ...
;         float w[16];
; #pragma unroll
;         for (int e = 0; e < 16; ++e) { w[e] = __builtin_amdgcn_exp2f(fmaf(sx[e], CS, -bA)); lA += w[e]; }
;         const u32x4 p0 = {pk2(w[0], w[1]), pk2(w[2], w[3]), pk2(w[4], w[5]), pk2(w[6], w[7])};
;         const u32x4 p1 = {pk2(w[8], w[9]), pk2(w[10], w[11]), pk2(w[12], w[13]), pk2(w[14], w[15])};
;         a0 = __builtin_bit_cast(bf16x8, p0); a1 = __builtin_bit_cast(bf16x8, p1);
;       }
;       {
;         float w[16];
; #pragma unroll
;         for (int e = 0; e < 16; ++e) { w[e] = __builtin_amdgcn_exp2f(fmaf(sy[e], CS, -bB)); lB += w[e]; }
;         const u32x4 p0 = {pk2(w[0], w[1]), pk2(w[2], w[3]), pk2(w[4], w[5]), pk2(w[6], w[7])};
;         const u32x4 p1 = {pk2(w[8], w[9]), pk2(w[10], w[11]), pk2(w[12], w[13]), pk2(w[14], w[15])};
;         b0 = __builtin_bit_cast(bf16x8, p0); b1 = __builtin_bit_cast(bf16x8, p1);
;       }
;     }
;     const u16* vt = Vt + buf * 128 * VLD + r * VLD + 4 * h;
; #pragma unroll
;     for (int d = 0; d < 4; d += 2) {
;       const s16x4 l0 = *(const s16x4*)(vt + d * 32 * VLD), h0 = *(const s16x4*)(vt + d * 32 * VLD + 8);
;       const s16x4 l1 = *(const s16x4*)(vt + d * 32 * VLD + 16), h1 = *(const s16x4*)(vt + d * 32 * VLD + 24);
;       const s16x4 m0 = *(const s16x4*)(vt + (d + 1) * 32 * VLD), n0 = *(const s16x4*)(vt + (d + 1) * 32 * VLD + 8);
;       const s16x4 m1 = *(const s16x4*)(vt + (d + 1) * 32 * VLD + 16), n1 = *(const s16x4*)(vt + (d + 1) * 32 * VLD + 24);
;       const bf16x8 v0 = {l0[0], l0[1], l0[2], l0[3], h0[0], h0[1], h0[2], h0[3]};
;       const bf16x8 v1 = {l1[0], l1[1], l1[2], l1[3], h1[0], h1[1], h1[2], h1[3]};
;       const bf16x8 u0 = {m0[0], m0[1], m0[2], m0[3], n0[0], n0[1], n0[2], n0[3]};
;       const bf16x8 u1 = {m1[0], m1[1], m1[2], m1[3], n1[0], n1[1], n1[2], n1[3]};
;       o1[d] = MFMA32(a0, v0, o1[d]);
;       o2[d] = MFMA32(b0, v0, o2[d]);
;       o1[d + 1] = MFMA32(a0, u0, o1[d + 1]);
;       o2[d + 1] = MFMA32(b0, u0, o2[d + 1]);
;       o1[d] = MFMA32(a1, v1, o1[d]);
;       o2[d] = MFMA32(b1, v1, o2[d]);
;       o1[d + 1] = MFMA32(a1, u1, o1[d + 1]);
;       o2[d + 1] = MFMA32(b1, u1, o2[d + 1]);
;     }
;     if (more) { ATT_STOREK(buf ^ 1); ATT_STOREV(buf ^ 1); }
;     __syncthreads();
;   }
	v_mfma_f32_32x32x16_bf16 v[128:143], v[192:195], v[220:223], v[128:143]
	v_mfma_f32_32x32x16_bf16 v[144:159], v[160:163], v[176:179], v[144:159]
	s_nop 10
	v_fmamk_f32 v128, v128, 0x3e38aa3b, v173
	v_exp_f32_e32 v192, v128
	v_fmamk_f32 v128, v129, 0x3e38aa3b, v173
	v_exp_f32_e32 v193, v128
	v_fmamk_f32 v128, v130, 0x3e38aa3b, v173
	v_exp_f32_e32 v194, v128
	v_fmamk_f32 v128, v131, 0x3e38aa3b, v173
	v_exp_f32_e32 v195, v128
	v_fmamk_f32 v128, v132, 0x3e38aa3b, v173
	v_fmamk_f32 v132, v134, 0x3e38aa3b, v173
	v_fmamk_f32 v144, v144, 0x3e38aa3b, v175
	v_fmamk_f32 v145, v145, 0x3e38aa3b, v175
	v_fmamk_f32 v146, v146, 0x3e38aa3b, v175
	v_fmamk_f32 v147, v147, 0x3e38aa3b, v175
	v_fmamk_f32 v148, v148, 0x3e38aa3b, v175
	v_fmamk_f32 v149, v149, 0x3e38aa3b, v175
	v_fmamk_f32 v150, v150, 0x3e38aa3b, v175
	v_fmamk_f32 v151, v151, 0x3e38aa3b, v175
	v_exp_f32_e32 v201, v128
	v_fmamk_f32 v128, v133, 0x3e38aa3b, v173
	v_exp_f32_e32 v203, v132
	v_fmamk_f32 v132, v135, 0x3e38aa3b, v173
	v_exp_f32_e32 v170, v144
	v_exp_f32_e32 v171, v145
	v_exp_f32_e32 v172, v146
	v_exp_f32_e32 v174, v147
	v_exp_f32_e32 v176, v148
	v_exp_f32_e32 v177, v149
	v_exp_f32_e32 v178, v150
	v_exp_f32_e32 v179, v151
	v_fmamk_f32 v144, v155, 0x3e38aa3b, v175
	v_exp_f32_e32 v202, v128
	v_exp_f32_e32 v204, v132
	v_exp_f32_e32 v197, v144
	v_fmamk_f32 v144, v156, 0x3e38aa3b, v175
	v_fmamk_f32 v152, v152, 0x3e38aa3b, v175
	v_exp_f32_e32 v198, v144
	v_fmamk_f32 v144, v157, 0x3e38aa3b, v175
	v_exp_f32_e32 v180, v152
	v_exp_f32_e32 v199, v144
	v_fmamk_f32 v144, v158, 0x3e38aa3b, v175
	v_add_u32_e32 v152, 0x6800, v164
	v_fmamk_f32 v136, v136, 0x3e38aa3b, v173
	v_exp_f32_e32 v200, v144
	v_cvt_pk_bf16_f32 v144, v170, v171
	v_cvt_pk_bf16_f32 v145, v172, v174
	v_cvt_pk_bf16_f32 v146, v176, v177
	v_cvt_pk_bf16_f32 v147, v178, v179
	ds_read2_b64 v[128:131], v152 offset1:2
	v_cvt_pk_bf16_f32 v132, v192, v193
	v_cvt_pk_bf16_f32 v133, v194, v195
	v_cvt_pk_bf16_f32 v134, v201, v202
	v_cvt_pk_bf16_f32 v135, v203, v204
	v_exp_f32_e32 v205, v136
	v_fmamk_f32 v136, v137, 0x3e38aa3b, v173
	v_exp_f32_e32 v206, v136
	v_fmamk_f32 v136, v138, 0x3e38aa3b, v173
	v_exp_f32_e32 v207, v136
	v_fmamk_f32 v136, v139, 0x3e38aa3b, v173
	v_fmamk_f32 v153, v153, 0x3e38aa3b, v175
	v_exp_f32_e32 v208, v136
	v_fmamk_f32 v136, v140, 0x3e38aa3b, v173
	v_exp_f32_e32 v181, v153
	v_add_u32_e32 v153, 0x7000, v164
	v_exp_f32_e32 v209, v136
	v_fmamk_f32 v136, v141, 0x3e38aa3b, v173
	v_fmamk_f32 v154, v154, 0x3e38aa3b, v175
	v_fmac_f32_e32 v175, 0x3e38aa3b, v159
	s_waitcnt lgkmcnt(0)
	v_mfma_f32_32x32x16_bf16 v[64:79], v[144:147], v[128:131], v[64:79]
	v_exp_f32_e32 v210, v136
	v_fmamk_f32 v136, v142, 0x3e38aa3b, v173
	v_fmac_f32_e32 v173, 0x3e38aa3b, v143
	v_exp_f32_e32 v196, v154
	v_exp_f32_e32 v175, v175
	v_exp_f32_e32 v212, v136
	v_exp_f32_e32 v173, v173
	v_mfma_f32_32x32x16_bf16 v[48:63], v[132:135], v[128:131], v[48:63]
	ds_read2_b64 v[128:131], v153 offset0:32 offset1:34
	v_cvt_pk_bf16_f32 v148, v180, v181
	v_cvt_pk_bf16_f32 v149, v196, v197
	v_cvt_pk_bf16_f32 v150, v198, v199
	v_cvt_pk_bf16_f32 v151, v200, v175
	v_cvt_pk_bf16_f32 v136, v205, v206
	v_cvt_pk_bf16_f32 v137, v207, v208
	s_waitcnt lgkmcnt(0)
	v_mfma_f32_32x32x16_bf16 v[80:95], v[144:147], v[128:131], v[80:95]
	v_cvt_pk_bf16_f32 v138, v209, v210
	v_cvt_pk_bf16_f32 v139, v212, v173
	v_add_u32_e32 v160, 0x8000, v164
	v_mfma_f32_32x32x16_bf16 v[32:47], v[132:135], v[128:131], v[32:47]
	ds_read2_b64 v[128:131], v152 offset0:4 offset1:6
	v_add_u32_e32 v152, 0x7800, v164
	ds_read2_b64 v[140:143], v152 offset0:64 offset1:66
	s_waitcnt lgkmcnt(1)
	v_mfma_f32_32x32x16_bf16 v[64:79], v[148:151], v[128:131], v[64:79]
	v_mfma_f32_32x32x16_bf16 v[48:63], v[136:139], v[128:131], v[48:63]
	ds_read2_b64 v[128:131], v153 offset0:36 offset1:38
	ds_read2_b64 v[152:155], v152 offset0:68 offset1:70
	ds_read2_b64 v[156:159], v160 offset0:96 offset1:98
	ds_read2_b64 v[160:163], v160 offset0:100 offset1:102
	s_waitcnt lgkmcnt(0)
	s_barrier
	global_load_dword v164, v165, s[18:19]
	v_mfma_f32_32x32x16_bf16 v[96:111], v[144:147], v[140:143], v[96:111]
	v_and_b32_e32 v213, 31, v167
	v_mfma_f32_32x32x16_bf16 v[16:31], v[132:135], v[140:143], v[16:31]
	v_add_f32_e32 v140, v169, v192
	v_add_f32_e32 v140, v193, v140
	v_add_f32_e32 v140, v194, v140
	v_add_f32_e32 v140, v195, v140
	v_add_f32_e32 v140, v201, v140
	v_add_f32_e32 v140, v202, v140
	v_add_f32_e32 v140, v203, v140
	v_add_f32_e32 v140, v204, v140
	v_add_f32_e32 v140, v205, v140
	v_add_f32_e32 v140, v206, v140
	v_mfma_f32_32x32x16_bf16 v[0:15], v[132:135], v[156:159], v[0:15]
	v_add_f32_e32 v132, v207, v140
	v_add_f32_e32 v132, v208, v132
	v_add_f32_e32 v132, v209, v132
	v_add_f32_e32 v132, v210, v132
	v_add_f32_e32 v132, v212, v132
	v_add_f32_e32 v132, v173, v132
	ds_bpermute_b32 v133, v191, v132
	v_mfma_f32_32x32x16_bf16 v[80:95], v[148:151], v[128:131], v[80:95]
	s_waitcnt lgkmcnt(0)
	v_add_f32_e32 v132, v132, v133
	s_waitcnt vmcnt(0)
	v_div_scale_f32 v133, s[0:1], v132, v132, v164
	v_mfma_f32_32x32x16_bf16 v[32:47], v[136:139], v[128:131], v[32:47]
	v_add_f32_e32 v131, v168, v170
	v_add_f32_e32 v131, v171, v131
	v_add_f32_e32 v131, v172, v131
	v_add_f32_e32 v131, v174, v131
	v_add_f32_e32 v131, v176, v131
	v_add_f32_e32 v131, v177, v131
	v_add_f32_e32 v131, v178, v131
	v_add_f32_e32 v131, v179, v131
	v_add_f32_e32 v131, v180, v131
	v_add_f32_e32 v131, v181, v131
	v_lshlrev_b32_e32 v128, 2, v213
	v_add_f32_e32 v131, v196, v131
	v_rcp_f32_e32 v134, v133
	global_load_dword v129, v128, s[54:55] offset:512
	global_load_dword v130, v128, s[54:55] offset:640
	global_load_dword v215, v128, s[54:55] offset:768
	v_add_f32_e32 v131, v197, v131
	v_add_f32_e32 v131, v198, v131
	v_add_f32_e32 v131, v199, v131
	v_add_f32_e32 v131, v200, v131
	v_fma_f32 v140, -v133, v134, 1.0
	v_add_f32_e32 v131, v175, v131
	v_fmac_f32_e32 v134, v140, v134
	v_div_scale_f32 v140, vcc, v164, v132, v164
	ds_bpermute_b32 v135, v191, v131
	v_mul_f32_e32 v141, v140, v134
	v_fma_f32 v142, -v133, v141, v140
	v_fmac_f32_e32 v141, v142, v134
	v_fma_f32 v133, -v133, v141, v140
	v_div_fmas_f32 v133, v133, v134, v141
	v_div_fixup_f32 v132, v133, v132, v164
	s_waitcnt lgkmcnt(0)
; DI u16 f2bf(float a) { return (u16)(pk2(a, 0.f) & 0xffffu); }
; DI int crow(int i, int h) { return (i & 3) + 8 * (i >> 2) + 4 * h; }
; __device__ __forceinline__ void attn_item_A(const Params& p, int layer, int head, int q0u, char* lds) {
;     ...
;   int lane_e = lane; asm volatile("" : "+v"(lane_e));
;   const int r_e = lane_e & 31, h_e = lane_e >> 5;
;   lA += __shfl_xor(lA, 32); lB += __shfl_xor(lB, 32);
;   const float lam = ((const float*)(p.ws + OFF_LAM))[layer];
;   const float iA = 1.f / lA, iB = lam / lB;
;   u16* Mx = (u16*)(p.ws + OFF_M);
;   const int orow0 = q0u + wid * 32;
;   const float lam_init = 0.8f - 0.6f * expf(-0.3f * (float)layer);
;   float sw[4];
; #pragma unroll
;   for (int d = 0; d < 4; ++d) sw[d] = p.subln[layer * 128 + d * 32 + r_e] * (1.f - lam_init);
; #pragma unroll
;   for (int e = 0; e < 16; ++e) {
;     const int qq = crow(e, h_e);
;     const float ia = __shfl(iA, qq), ib = __shfl(iB, qq);
;     float ov[4];
;     float ss = 0.f;
; #pragma unroll
;     for (int d = 0; d < 4; ++d) { ov[d] = o1[d][e] * ia - o2[d][e] * ib; ss += ov[d] * ov[d]; }
; #pragma unroll
;     for (int x = 16; x >= 1; x >>= 1) ss += __shfl_xor(ss, x);
;     const float rs = rsqrtf(ss * (1.f / 128.f) + LN_EPS);
;     const size_t rowoff = (size_t)(orow0 + qq) * LDX + ocol + r_e;
; #pragma unroll
;     for (int d = 0; d < 4; ++d) Mx[rowoff + d * 32] = f2bf(ov[d] * rs * sw[d]);
;   }
	v_add_f32_e32 v133, v131, v135
	v_div_scale_f32 v134, s[0:1], v133, v133, 1.0
	v_rcp_f32_e32 v135, v134
	v_mfma_f32_32x32x16_bf16 v[0:15], v[136:139], v[160:163], v[0:15]
	v_mov_b32_e32 v143, v32
	v_mov_b32_e32 v140, v64
	v_mov_b32_e32 v142, v48
	v_mov_b32_e32 v141, v80
	v_mov_b32_e32 v80, v65
	s_add_u32 s0, s34, s4
	s_addc_u32 s1, s35, s5
	v_mfma_f32_32x32x16_bf16 v[112:127], v[144:147], v[156:159], v[112:127]
	s_nop 3
	v_mov_b32_e32 v146, v0
	v_xor_b32_e32 v0, 16, v214
	v_lshlrev_b32_e32 v164, 1, v213
	global_load_dword v128, v128, s[54:55] offset:896
	s_waitcnt vmcnt(3)
	v_mul_f32_e32 v131, 0x3f24fd5c, v129
	v_mfma_f32_32x32x16_bf16 v[16:31], v[136:139], v[152:155], v[16:31]
	v_fma_f32 v136, -v134, v135, 1.0
	v_fmac_f32_e32 v135, v136, v135
	v_div_scale_f32 v136, vcc, 1.0, v133, 1.0
	v_mul_f32_e32 v137, v136, v135
	v_fma_f32 v138, -v134, v137, v136
	v_fmac_f32_e32 v137, v138, v135
	v_fma_f32 v134, -v134, v137, v136
	v_div_fmas_f32 v134, v134, v135, v137
	v_ashrrev_i32_e32 v135, 3, v167
	v_div_fixup_f32 v133, v134, v133, 1.0
	v_and_b32_e32 v134, -4, v135
	v_mfma_f32_32x32x16_bf16 v[96:111], v[148:151], v[152:155], v[96:111]
	v_cmp_lt_i32_e32 vcc, v0, v187
	v_and_or_b32 v136, v135, 60, v186
	v_mov_b32_e32 v147, v16
	v_cndmask_b32_e32 v16, v214, v0, vcc
	v_lshlrev_b32_e32 v137, 2, v136
	ds_bpermute_b32 v138, v137, v132
	ds_bpermute_b32 v136, v137, v133
	v_mfma_f32_32x32x16_bf16 v[112:127], v[148:151], v[160:163], v[112:127]
	v_or_b32_e32 v150, 1, v134
	v_and_or_b32 v0, v150, 61, v186
	v_lshlrev_b32_e32 v32, 2, v0
	ds_bpermute_b32 v0, v32, v132
	ds_bpermute_b32 v64, v32, v133
	v_mov_b32_e32 v32, v49
	s_waitcnt lgkmcnt(3)
	v_pk_mul_f32 v[142:143], v[142:143], v[138:139] op_sel_hi:[1,0]
	s_nop 3
	v_mov_b32_e32 v144, v112
	v_mov_b32_e32 v145, v96
	v_pk_mul_f32 v[138:139], v[146:147], v[138:139] op_sel_hi:[1,0]
	v_lshlrev_b32_e32 v48, 2, v16
	s_waitcnt lgkmcnt(1)
	v_pk_mul_f32 v[32:33], v[32:33], v[0:1] op_sel_hi:[1,0]
	v_mov_b32_e32 v16, v1
	v_pk_fma_f32 v[140:141], v[140:141], v[136:137], v[142:143] op_sel_hi:[1,0,1] neg_lo:[0,0,1] neg_hi:[0,0,1]
	v_pk_fma_f32 v[136:137], v[144:145], v[136:137], v[138:139] op_sel_hi:[1,0,1] neg_lo:[0,0,1] neg_hi:[0,0,1]
	s_waitcnt lgkmcnt(0)
	v_pk_fma_f32 v[144:145], v[80:81], v[64:65], v[32:33] op_sel_hi:[1,0,1] neg_lo:[0,0,1] neg_hi:[0,0,1]
	v_mov_b32_e32 v96, v113
	v_pk_mul_f32 v[0:1], v[16:17], v[0:1] op_sel_hi:[1,0]
	v_pk_mul_f32 v[142:143], v[140:141], v[140:141]
	v_pk_mul_f32 v[32:33], v[144:145], v[144:145]
	v_pk_fma_f32 v[96:97], v[96:97], v[64:65], v[0:1] op_sel_hi:[1,0,1] neg_lo:[0,0,1] neg_hi:[0,0,1]
	v_pk_mul_f32 v[138:139], v[136:137], v[136:137]
	v_pk_mul_f32 v[0:1], v[96:97], v[96:97]
	v_mov_b32_e32 v16, v32
	v_mov_b32_e32 v17, v142
	v_mov_b32_e32 v142, v33
	v_pk_add_f32 v[16:17], v[16:17], v[142:143]
	v_mov_b32_e32 v32, v1
	v_mov_b32_e32 v33, v139
	v_pk_add_f32 v[16:17], v[32:33], v[16:17]
	v_mov_b32_e32 v1, v138
	v_pk_add_f32 v[0:1], v[0:1], v[16:17]
	ds_bpermute_b32 v17, v48, v1
	ds_bpermute_b32 v16, v48, v0
	v_xor_b32_e32 v32, 8, v214
	v_cmp_lt_i32_e32 vcc, v32, v187
	s_waitcnt vmcnt(2)
	v_mul_f32_e32 v130, 0x3f24fd5c, v130
	s_waitcnt vmcnt(1)
	v_mul_f32_e32 v129, 0x3f24fd5c, v215
	v_cndmask_b32_e32 v32, v214, v32, vcc
	v_lshlrev_b32_e32 v49, 2, v32
	s_waitcnt lgkmcnt(0)
	v_pk_add_f32 v[0:1], v[0:1], v[16:17]
	ds_bpermute_b32 v17, v49, v1
	ds_bpermute_b32 v16, v49, v0
	v_xor_b32_e32 v32, 4, v214
	v_cmp_lt_i32_e32 vcc, v32, v187
	v_or_b32_e32 v152, 2, v134
	v_or_b32_e32 v135, 3, v135
	v_cndmask_b32_e32 v32, v214, v32, vcc
	v_lshlrev_b32_e32 v64, 2, v32
	s_waitcnt lgkmcnt(0)
	v_pk_add_f32 v[0:1], v[0:1], v[16:17]
	ds_bpermute_b32 v17, v64, v1
	ds_bpermute_b32 v16, v64, v0
	v_xor_b32_e32 v32, 2, v214
	v_cmp_lt_i32_e32 vcc, v32, v187
	v_mov_b32_e32 v148, v2
	v_and_or_b32 v2, v135, 63, v186
	v_cndmask_b32_e32 v32, v214, v32, vcc
	v_lshlrev_b32_e32 v65, 2, v32
	s_waitcnt lgkmcnt(0)
	v_pk_add_f32 v[0:1], v[0:1], v[16:17]
	ds_bpermute_b32 v17, v65, v1
	ds_bpermute_b32 v16, v65, v0
	v_xor_b32_e32 v32, 1, v214
	v_cmp_lt_i32_e32 vcc, v32, v187
	v_mov_b32_e32 v149, v18
	v_lshlrev_b32_e32 v18, 2, v2
	v_cndmask_b32_e32 v32, v214, v32, vcc
	v_lshlrev_b32_e32 v80, 2, v32
	s_waitcnt lgkmcnt(0)
	v_pk_add_f32 v[0:1], v[0:1], v[16:17]
	ds_bpermute_b32 v33, v80, v1
	ds_bpermute_b32 v32, v80, v0
	v_lshl_add_u64 v[16:17], s[0:1], 0, v[164:165]
	ds_bpermute_b32 v2, v18, v132
	v_mov_b32_e32 v142, v50
	ds_bpermute_b32 v50, v18, v133
	s_waitcnt lgkmcnt(2)
	v_pk_add_f32 v[0:1], v[0:1], v[32:33]
	v_mov_b64_e32 v[32:33], s[36:37]
	v_pk_fma_f32 v[112:113], v[0:1], s[30:31], v[32:33] op_sel_hi:[1,0,0]
	v_mov_b32_e32 v143, v34
	v_mul_f32_e32 v0, 0x4b800000, v113
	v_cmp_gt_f32_e32 vcc, s81, v113
	v_mov_b32_e32 v34, v51
	s_waitcnt lgkmcnt(1)
	v_pk_mul_f32 v[34:35], v[34:35], v[2:3] op_sel_hi:[1,0]
	v_cndmask_b32_e32 v0, v113, v0, vcc
	v_rsq_f32_e32 v81, v0
	v_add_u32_e32 v0, v134, v190
	v_mad_i64_i32 v[0:1], s[0:1], v0, s78, v[16:17]
	v_mul_f32_e32 v113, 0x45800000, v81
	v_cndmask_b32_e32 v81, v81, v113, vcc
	v_mul_f32_e32 v113, v140, v81
	v_mul_f32_e32 v113, v131, v113
	v_cvt_pk_bf16_f32 v113, v113, s0
	global_store_short v[0:1], v113, off
	v_mul_f32_e32 v113, v141, v81
	v_mul_f32_e32 v113, v130, v113
	v_cvt_pk_bf16_f32 v113, v113, s0
	global_store_short v[0:1], v113, off offset:64
	v_mul_f32_e32 v113, v137, v81
	v_mul_f32_e32 v113, v129, v113
	v_cvt_pk_bf16_f32 v137, v113, s0
	v_mul_f32_e32 v113, 0x4b800000, v112
	v_cmp_gt_f32_e32 vcc, s81, v112
	v_mov_b32_e32 v140, v66
	v_mov_b32_e32 v141, v82
	v_cndmask_b32_e32 v112, v112, v113, vcc
	v_rsq_f32_e32 v151, v112
	v_and_or_b32 v112, v152, 62, v186
	v_lshlrev_b32_e32 v113, 2, v112
	ds_bpermute_b32 v138, v113, v132
	ds_bpermute_b32 v112, v113, v133
	v_mov_b32_e32 v82, v67
	v_mov_b32_e32 v18, v3
	v_mov_b32_e32 v146, v114
	s_waitcnt lgkmcnt(1)
; DI u16 f2bf(float a) { return (u16)(pk2(a, 0.f) & 0xffffu); }
; DI int crow(int i, int h) { return (i & 3) + 8 * (i >> 2) + 4 * h; }
; __device__ __forceinline__ void attn_item_A(const Params& p, int layer, int head, int q0u, char* lds) {
;     ...
; #pragma unroll
;   for (int e = 0; e < 16; ++e) {
;     const int qq = crow(e, h_e);
;     const float ia = __shfl(iA, qq), ib = __shfl(iB, qq);
;     float ov[4];
;     float ss = 0.f;
; #pragma unroll
;     for (int d = 0; d < 4; ++d) { ov[d] = o1[d][e] * ia - o2[d][e] * ib; ss += ov[d] * ov[d]; }
; #pragma unroll
;     for (int x = 16; x >= 1; x >>= 1) ss += __shfl_xor(ss, x);
;     const float rs = rsqrtf(ss * (1.f / 128.f) + LN_EPS);
;     const size_t rowoff = (size_t)(orow0 + qq) * LDX + ocol + r_e;
; #pragma unroll
;     for (int d = 0; d < 4; ++d) Mx[rowoff + d * 32] = f2bf(ov[d] * rs * sw[d]);
;   }
	v_pk_mul_f32 v[142:143], v[142:143], v[138:139] op_sel_hi:[1,0]
	v_mov_b32_e32 v147, v98
	s_waitcnt lgkmcnt(0)
	v_pk_fma_f32 v[140:141], v[140:141], v[112:113], v[142:143] op_sel_hi:[1,0,1] neg_lo:[0,0,1] neg_hi:[0,0,1]
	v_pk_mul_f32 v[138:139], v[148:149], v[138:139] op_sel_hi:[1,0]
	v_pk_fma_f32 v[66:67], v[82:83], v[50:51], v[34:35] op_sel_hi:[1,0,1] neg_lo:[0,0,1] neg_hi:[0,0,1]
	v_mov_b32_e32 v98, v115
	v_pk_mul_f32 v[2:3], v[18:19], v[2:3] op_sel_hi:[1,0]
	v_pk_mul_f32 v[142:143], v[140:141], v[140:141]
	v_pk_fma_f32 v[112:113], v[146:147], v[112:113], v[138:139] op_sel_hi:[1,0,1] neg_lo:[0,0,1] neg_hi:[0,0,1]
	v_pk_mul_f32 v[34:35], v[66:67], v[66:67]
	v_pk_fma_f32 v[50:51], v[98:99], v[50:51], v[2:3] op_sel_hi:[1,0,1] neg_lo:[0,0,1] neg_hi:[0,0,1]
	v_pk_mul_f32 v[138:139], v[112:113], v[112:113]
	v_pk_mul_f32 v[2:3], v[50:51], v[50:51]
	v_mov_b32_e32 v18, v34
	v_mov_b32_e32 v19, v142
	v_mov_b32_e32 v142, v35
	v_pk_add_f32 v[18:19], v[18:19], v[142:143]
	v_mov_b32_e32 v34, v3
	v_mov_b32_e32 v35, v139
	v_pk_add_f32 v[18:19], v[34:35], v[18:19]
	v_mov_b32_e32 v3, v138
	v_pk_add_f32 v[2:3], v[2:3], v[18:19]
	ds_bpermute_b32 v19, v48, v3
	ds_bpermute_b32 v18, v48, v2
	v_mul_f32_e32 v35, 0x45800000, v151
	v_cndmask_b32_e32 v35, v151, v35, vcc
	v_mul_f32_e32 v34, v136, v81
	v_mul_f32_e32 v81, v144, v35
	s_waitcnt lgkmcnt(0)
	v_pk_add_f32 v[18:19], v[2:3], v[18:19]
	ds_bpermute_b32 v83, v49, v19
	ds_bpermute_b32 v82, v49, v18
	v_add_u32_e32 v2, v150, v190
	v_mad_i64_i32 v[2:3], s[0:1], v2, s78, v[16:17]
	v_mul_f32_e32 v81, v131, v81
	s_waitcnt lgkmcnt(0)
	v_pk_add_f32 v[18:19], v[18:19], v[82:83]
	ds_bpermute_b32 v83, v64, v19
	ds_bpermute_b32 v82, v64, v18
	v_cvt_pk_bf16_f32 v81, v81, s0
	global_store_short v[2:3], v81, off
	v_mul_f32_e32 v81, v145, v35
	v_mul_f32_e32 v81, v130, v81
	s_waitcnt lgkmcnt(0)
	v_pk_add_f32 v[18:19], v[18:19], v[82:83]
	ds_bpermute_b32 v83, v65, v19
	ds_bpermute_b32 v82, v65, v18
	v_cvt_pk_bf16_f32 v81, v81, s0
	global_store_short v[2:3], v81, off offset:64
	v_mul_f32_e32 v81, v97, v35
	v_mul_f32_e32 v81, v129, v81
	s_waitcnt lgkmcnt(0)
	v_pk_add_f32 v[18:19], v[18:19], v[82:83]
	ds_bpermute_b32 v83, v80, v19
	ds_bpermute_b32 v82, v80, v18
	v_cvt_pk_bf16_f32 v81, v81, s0
	global_store_short v[2:3], v81, off offset:128
	v_mov_b32_e32 v136, v116
	v_add_u32_e32 v116, 9, v134
	s_waitcnt lgkmcnt(0)
	v_pk_add_f32 v[18:19], v[18:19], v[82:83]
	v_mov_b32_e32 v138, v4
	v_pk_fma_f32 v[82:83], v[18:19], s[30:31], v[32:33] op_sel_hi:[1,0,0]
	v_and_or_b32 v4, v116, 61, v186
	v_mul_f32_e32 v18, 0x4b800000, v83
	v_cmp_gt_f32_e32 vcc, s81, v83
	v_mov_b32_e32 v139, v20
	v_lshlrev_b32_e32 v20, 2, v4
	v_cndmask_b32_e32 v18, v83, v18, vcc
	v_rsq_f32_e32 v81, v18
	v_add_u32_e32 v18, v152, v190
	v_mad_i64_i32 v[18:19], s[0:1], v18, s78, v[16:17]
	v_mul_f32_e32 v83, 0x45800000, v81
	v_cndmask_b32_e32 v81, v81, v83, vcc
	v_mul_f32_e32 v83, v140, v81
	v_mul_f32_e32 v83, v131, v83
	v_cvt_pk_bf16_f32 v83, v83, s0
	global_store_short v[18:19], v83, off
	v_mul_f32_e32 v83, v141, v81
	v_mul_f32_e32 v83, v130, v83
	v_cvt_pk_bf16_f32 v83, v83, s0
	global_store_short v[18:19], v83, off offset:64
	v_mul_f32_e32 v83, v113, v81
	v_mul_f32_e32 v83, v129, v83
	v_cvt_pk_bf16_f32 v113, v83, s0
	v_mul_f32_e32 v83, 0x4b800000, v82
	v_cmp_gt_f32_e32 vcc, s81, v82
	v_add_u32_e32 v141, 8, v134
	v_mul_f32_e32 v35, v96, v35
	v_cndmask_b32_e32 v82, v82, v83, vcc
	v_rsq_f32_e32 v140, v82
	v_and_or_b32 v82, v141, 60, v186
	v_lshlrev_b32_e32 v83, 2, v82
	ds_bpermute_b32 v96, v83, v132
	ds_bpermute_b32 v4, v20, v132
	ds_bpermute_b32 v82, v83, v133
	v_mov_b32_e32 v114, v52
	ds_bpermute_b32 v52, v20, v133
	v_mov_b32_e32 v115, v36
	v_mov_b32_e32 v36, v53
	v_mov_b32_e32 v98, v68
	v_mov_b32_e32 v99, v84
	s_waitcnt lgkmcnt(3)
	v_pk_mul_f32 v[114:115], v[114:115], v[96:97] op_sel_hi:[1,0]
	v_mov_b32_e32 v84, v69
	s_waitcnt lgkmcnt(2)
	v_pk_mul_f32 v[36:37], v[36:37], v[4:5] op_sel_hi:[1,0]
	v_mov_b32_e32 v20, v5
	global_store_short v[0:1], v137, off offset:128
	s_waitcnt lgkmcnt(1)
	v_pk_fma_f32 v[98:99], v[98:99], v[82:83], v[114:115] op_sel_hi:[1,0,1] neg_lo:[0,0,1] neg_hi:[0,0,1]
	v_mov_b32_e32 v137, v100
	v_pk_mul_f32 v[96:97], v[138:139], v[96:97] op_sel_hi:[1,0]
	s_waitcnt lgkmcnt(0)
	v_pk_fma_f32 v[68:69], v[84:85], v[52:53], v[36:37] op_sel_hi:[1,0,1] neg_lo:[0,0,1] neg_hi:[0,0,1]
	v_mov_b32_e32 v100, v117
	v_pk_mul_f32 v[4:5], v[20:21], v[4:5] op_sel_hi:[1,0]
	v_pk_mul_f32 v[114:115], v[98:99], v[98:99]
	v_pk_fma_f32 v[82:83], v[136:137], v[82:83], v[96:97] op_sel_hi:[1,0,1] neg_lo:[0,0,1] neg_hi:[0,0,1]
	v_pk_mul_f32 v[36:37], v[68:69], v[68:69]
	v_pk_fma_f32 v[52:53], v[100:101], v[52:53], v[4:5] op_sel_hi:[1,0,1] neg_lo:[0,0,1] neg_hi:[0,0,1]
	v_pk_mul_f32 v[96:97], v[82:83], v[82:83]
	v_pk_mul_f32 v[4:5], v[52:53], v[52:53]
	v_mov_b32_e32 v20, v36
	v_mov_b32_e32 v21, v114
	v_mov_b32_e32 v114, v37
	v_pk_add_f32 v[20:21], v[20:21], v[114:115]
	v_mov_b32_e32 v36, v5
	v_mov_b32_e32 v37, v97
	v_pk_add_f32 v[20:21], v[36:37], v[20:21]
	v_mov_b32_e32 v5, v96
	v_pk_add_f32 v[4:5], v[4:5], v[20:21]
	ds_bpermute_b32 v21, v48, v5
	ds_bpermute_b32 v20, v48, v4
	v_mul_f32_e32 v37, 0x45800000, v140
	v_cndmask_b32_e32 v37, v140, v37, vcc
	v_mul_f32_e32 v66, v66, v37
	v_mul_f32_e32 v66, v131, v66
	s_waitcnt lgkmcnt(0)
	v_pk_add_f32 v[20:21], v[4:5], v[20:21]
	ds_bpermute_b32 v85, v49, v21
	ds_bpermute_b32 v84, v49, v20
	v_add_u32_e32 v4, v135, v190
	v_mad_i64_i32 v[4:5], s[0:1], v4, s78, v[16:17]
	v_mul_f32_e32 v36, v112, v81
	s_waitcnt lgkmcnt(0)
; DI u16 f2bf(float a) { return (u16)(pk2(a, 0.f) & 0xffffu); }
; DI int crow(int i, int h) { return (i & 3) + 8 * (i >> 2) + 4 * h; }
; __device__ __forceinline__ void attn_item_A(const Params& p, int layer, int head, int q0u, char* lds) {
;     ...
; #pragma unroll
;   for (int e = 0; e < 16; ++e) {
;     const int qq = crow(e, h_e);
;     const float ia = __shfl(iA, qq), ib = __shfl(iB, qq);
;     float ov[4];
;     float ss = 0.f;
; #pragma unroll
;     for (int d = 0; d < 4; ++d) { ov[d] = o1[d][e] * ia - o2[d][e] * ib; ss += ov[d] * ov[d]; }
; #pragma unroll
;     for (int x = 16; x >= 1; x >>= 1) ss += __shfl_xor(ss, x);
;     const float rs = rsqrtf(ss * (1.f / 128.f) + LN_EPS);
;     const size_t rowoff = (size_t)(orow0 + qq) * LDX + ocol + r_e;
; #pragma unroll
;     for (int d = 0; d < 4; ++d) Mx[rowoff + d * 32] = f2bf(ov[d] * rs * sw[d]);
;   }
	v_pk_add_f32 v[20:21], v[20:21], v[84:85]
	ds_bpermute_b32 v85, v64, v21
	ds_bpermute_b32 v84, v64, v20
	v_cvt_pk_bf16_f32 v66, v66, s0
	global_store_short v[4:5], v66, off
	v_mul_f32_e32 v81, v67, v37
	v_mul_f32_e32 v51, v51, v37
	s_waitcnt lgkmcnt(0)
	v_pk_add_f32 v[20:21], v[20:21], v[84:85]
	ds_bpermute_b32 v67, v65, v21
	ds_bpermute_b32 v66, v65, v20
	v_mul_f32_e32 v51, v129, v51
	v_cvt_pk_bf16_f32 v51, v51, s0
	global_store_short v[4:5], v51, off offset:128
	v_mul_f32_e32 v37, v50, v37
	s_waitcnt lgkmcnt(0)
	v_pk_add_f32 v[20:21], v[20:21], v[66:67]
	ds_bpermute_b32 v67, v80, v21
	ds_bpermute_b32 v66, v80, v20
	v_mul_f32_e32 v81, v130, v81
	v_cvt_pk_bf16_f32 v81, v81, s0
	global_store_short v[4:5], v81, off offset:64
	global_store_short v[18:19], v113, off offset:128
	s_waitcnt lgkmcnt(0)
	v_pk_add_f32 v[20:21], v[20:21], v[66:67]
	v_add_u32_e32 v113, 10, v134
	v_pk_fma_f32 v[50:51], v[20:21], s[30:31], v[32:33] op_sel_hi:[1,0,0]
	v_mov_b32_e32 v96, v54
	v_mul_f32_e32 v20, 0x4b800000, v51
	v_cmp_gt_f32_e32 vcc, s81, v51
	v_mov_b32_e32 v97, v38
	v_mov_b32_e32 v100, v6
	v_cndmask_b32_e32 v20, v51, v20, vcc
	v_rsq_f32_e32 v51, v20
	v_add_u32_e32 v20, v141, v190
	v_mad_i64_i32 v[20:21], s[0:1], v20, s78, v[16:17]
	v_mul_f32_e32 v66, 0x45800000, v51
	v_cndmask_b32_e32 v81, v51, v66, vcc
	v_mul_f32_e32 v51, v98, v81
	v_mul_f32_e32 v51, v131, v51
	v_cvt_pk_bf16_f32 v51, v51, s0
	global_store_short v[20:21], v51, off
	v_mul_f32_e32 v51, v99, v81
	v_mul_f32_e32 v51, v130, v51
	v_cvt_pk_bf16_f32 v51, v51, s0
	global_store_short v[20:21], v51, off offset:64
	v_mul_f32_e32 v51, v83, v81
	v_mul_f32_e32 v51, v129, v51
	v_cvt_pk_bf16_f32 v83, v51, s0
	v_mul_f32_e32 v51, 0x4b800000, v50
	v_cmp_gt_f32_e32 vcc, s81, v50
	v_mov_b32_e32 v101, v22
	v_mov_b32_e32 v84, v70
	v_cndmask_b32_e32 v50, v50, v51, vcc
	v_rsq_f32_e32 v112, v50
	v_and_or_b32 v50, v113, 62, v186
	v_lshlrev_b32_e32 v51, 2, v50
	ds_bpermute_b32 v66, v51, v132
	ds_bpermute_b32 v50, v51, v133
	v_mov_b32_e32 v85, v86
	v_mov_b32_e32 v98, v118
	v_mov_b32_e32 v99, v102
	s_waitcnt lgkmcnt(1)
	v_pk_mul_f32 v[96:97], v[96:97], v[66:67] op_sel_hi:[1,0]
	v_pk_mul_f32 v[66:67], v[100:101], v[66:67] op_sel_hi:[1,0]
	s_waitcnt lgkmcnt(0)
	v_pk_fma_f32 v[84:85], v[84:85], v[50:51], v[96:97] op_sel_hi:[1,0,1] neg_lo:[0,0,1] neg_hi:[0,0,1]
	v_pk_fma_f32 v[50:51], v[98:99], v[50:51], v[66:67] op_sel_hi:[1,0,1] neg_lo:[0,0,1] neg_hi:[0,0,1]
	v_add_u32_e32 v98, 11, v134
	v_and_or_b32 v6, v98, 63, v186
	v_lshlrev_b32_e32 v22, 2, v6
	ds_bpermute_b32 v6, v22, v132
	ds_bpermute_b32 v54, v22, v133
	v_mov_b32_e32 v38, v55
	v_mov_b32_e32 v86, v71
	v_mov_b32_e32 v22, v7
	s_waitcnt lgkmcnt(1)
	v_pk_mul_f32 v[38:39], v[38:39], v[6:7] op_sel_hi:[1,0]
	v_mov_b32_e32 v102, v119
	s_waitcnt lgkmcnt(0)
	v_pk_fma_f32 v[70:71], v[86:87], v[54:55], v[38:39] op_sel_hi:[1,0,1] neg_lo:[0,0,1] neg_hi:[0,0,1]
	v_pk_mul_f32 v[6:7], v[22:23], v[6:7] op_sel_hi:[1,0]
	v_pk_mul_f32 v[96:97], v[84:85], v[84:85]
	v_pk_mul_f32 v[38:39], v[70:71], v[70:71]
	v_pk_fma_f32 v[54:55], v[102:103], v[54:55], v[6:7] op_sel_hi:[1,0,1] neg_lo:[0,0,1] neg_hi:[0,0,1]
	v_pk_mul_f32 v[66:67], v[50:51], v[50:51]
	v_pk_mul_f32 v[6:7], v[54:55], v[54:55]
	v_mov_b32_e32 v22, v38
	v_mov_b32_e32 v23, v96
	v_mov_b32_e32 v96, v39
	v_pk_add_f32 v[22:23], v[22:23], v[96:97]
	v_mov_b32_e32 v38, v7
	v_mov_b32_e32 v39, v67
	v_pk_add_f32 v[22:23], v[38:39], v[22:23]
	v_mov_b32_e32 v7, v66
	v_pk_add_f32 v[6:7], v[6:7], v[22:23]
	ds_bpermute_b32 v23, v48, v7
	ds_bpermute_b32 v22, v48, v6
	v_mul_f32_e32 v39, 0x45800000, v112
	v_cndmask_b32_e32 v39, v112, v39, vcc
	v_mul_f32_e32 v68, v68, v39
	v_mul_f32_e32 v53, v53, v39
	s_waitcnt lgkmcnt(0)
	v_pk_add_f32 v[22:23], v[6:7], v[22:23]
	ds_bpermute_b32 v67, v49, v23
	ds_bpermute_b32 v66, v49, v22
	v_add_u32_e32 v6, v116, v190
	v_mad_i64_i32 v[6:7], s[0:1], v6, s78, v[16:17]
	v_mul_f32_e32 v68, v131, v68
	s_waitcnt lgkmcnt(0)
	v_pk_add_f32 v[22:23], v[22:23], v[66:67]
	ds_bpermute_b32 v67, v64, v23
	ds_bpermute_b32 v66, v64, v22
	v_mul_f32_e32 v53, v129, v53
	v_cvt_pk_bf16_f32 v68, v68, s0
	v_cvt_pk_bf16_f32 v53, v53, s0
	global_store_short v[6:7], v68, off
	s_waitcnt lgkmcnt(0)
	v_pk_add_f32 v[22:23], v[22:23], v[66:67]
	ds_bpermute_b32 v67, v65, v23
	ds_bpermute_b32 v66, v65, v22
	v_mul_f32_e32 v68, v69, v39
	global_store_short v[6:7], v53, off offset:128
	v_mul_f32_e32 v39, v52, v39
	v_mul_f32_e32 v38, v82, v81
	s_waitcnt lgkmcnt(0)
	v_pk_add_f32 v[22:23], v[22:23], v[66:67]
	ds_bpermute_b32 v67, v80, v23
	ds_bpermute_b32 v66, v80, v22
	v_mul_f32_e32 v68, v130, v68
	v_cvt_pk_bf16_f32 v68, v68, s0
	v_add_u32_e32 v97, 16, v134
	global_store_short v[20:21], v83, off offset:128
	s_waitcnt lgkmcnt(0)
	v_pk_add_f32 v[22:23], v[22:23], v[66:67]
	v_mov_b32_e32 v82, v56
	v_pk_fma_f32 v[52:53], v[22:23], s[30:31], v[32:33] op_sel_hi:[1,0,0]
	v_mov_b32_e32 v83, v40
	v_mul_f32_e32 v22, 0x4b800000, v53
	v_cmp_gt_f32_e32 vcc, s81, v53
	v_mov_b32_e32 v86, v8
	v_mov_b32_e32 v87, v24
	v_cndmask_b32_e32 v22, v53, v22, vcc
	v_rsq_f32_e32 v53, v22
	v_add_u32_e32 v22, v113, v190
	v_mad_i64_i32 v[22:23], s[0:1], v22, s78, v[16:17]
	v_mul_f32_e32 v66, 0x45800000, v53
	v_cndmask_b32_e32 v81, v53, v66, vcc
	v_mul_f32_e32 v53, v84, v81
	v_mul_f32_e32 v53, v131, v53
	v_cvt_pk_bf16_f32 v53, v53, s0
	global_store_short v[22:23], v53, off
	v_mul_f32_e32 v53, v85, v81
	v_mul_f32_e32 v53, v130, v53
	v_cvt_pk_bf16_f32 v53, v53, s0
	global_store_short v[22:23], v53, off offset:64
	v_mul_f32_e32 v53, 0x4b800000, v52
	v_cmp_gt_f32_e32 vcc, s81, v52
	global_store_short v[6:7], v68, off offset:64
	v_mov_b32_e32 v68, v72
	v_cndmask_b32_e32 v52, v52, v53, vcc
	v_rsq_f32_e32 v96, v52
	v_and_or_b32 v52, v97, 60, v186
	v_lshlrev_b32_e32 v53, 2, v52
	ds_bpermute_b32 v66, v53, v132
	ds_bpermute_b32 v52, v53, v133
	v_mov_b32_e32 v69, v88
	v_mov_b32_e32 v84, v120
	v_mov_b32_e32 v85, v104
	s_waitcnt lgkmcnt(1)
; DI u16 f2bf(float a) { return (u16)(pk2(a, 0.f) & 0xffffu); }
; DI int crow(int i, int h) { return (i & 3) + 8 * (i >> 2) + 4 * h; }
; __device__ __forceinline__ void attn_item_A(const Params& p, int layer, int head, int q0u, char* lds) {
;     ...
; #pragma unroll
;   for (int e = 0; e < 16; ++e) {
;     const int qq = crow(e, h_e);
;     const float ia = __shfl(iA, qq), ib = __shfl(iB, qq);
;     float ov[4];
;     float ss = 0.f;
; #pragma unroll
;     for (int d = 0; d < 4; ++d) { ov[d] = o1[d][e] * ia - o2[d][e] * ib; ss += ov[d] * ov[d]; }
; #pragma unroll
;     for (int x = 16; x >= 1; x >>= 1) ss += __shfl_xor(ss, x);
;     const float rs = rsqrtf(ss * (1.f / 128.f) + LN_EPS);
;     const size_t rowoff = (size_t)(orow0 + qq) * LDX + ocol + r_e;
; #pragma unroll
;     for (int d = 0; d < 4; ++d) Mx[rowoff + d * 32] = f2bf(ov[d] * rs * sw[d]);
;   }
	v_pk_mul_f32 v[82:83], v[82:83], v[66:67] op_sel_hi:[1,0]
	v_pk_mul_f32 v[66:67], v[86:87], v[66:67] op_sel_hi:[1,0]
	s_waitcnt lgkmcnt(0)
	v_pk_fma_f32 v[68:69], v[68:69], v[52:53], v[82:83] op_sel_hi:[1,0,1] neg_lo:[0,0,1] neg_hi:[0,0,1]
	v_pk_fma_f32 v[52:53], v[84:85], v[52:53], v[66:67] op_sel_hi:[1,0,1] neg_lo:[0,0,1] neg_hi:[0,0,1]
	v_add_u32_e32 v84, 17, v134
	v_and_or_b32 v8, v84, 61, v186
	v_lshlrev_b32_e32 v24, 2, v8
	ds_bpermute_b32 v8, v24, v132
	ds_bpermute_b32 v56, v24, v133
	v_mov_b32_e32 v40, v57
	v_mov_b32_e32 v88, v73
	v_mov_b32_e32 v24, v9
	s_waitcnt lgkmcnt(1)
	v_pk_mul_f32 v[40:41], v[40:41], v[8:9] op_sel_hi:[1,0]
	v_mov_b32_e32 v104, v121
	s_waitcnt lgkmcnt(0)
	v_pk_fma_f32 v[72:73], v[88:89], v[56:57], v[40:41] op_sel_hi:[1,0,1] neg_lo:[0,0,1] neg_hi:[0,0,1]
	v_pk_mul_f32 v[8:9], v[24:25], v[8:9] op_sel_hi:[1,0]
	v_pk_mul_f32 v[82:83], v[68:69], v[68:69]
	v_pk_mul_f32 v[40:41], v[72:73], v[72:73]
	v_pk_fma_f32 v[56:57], v[104:105], v[56:57], v[8:9] op_sel_hi:[1,0,1] neg_lo:[0,0,1] neg_hi:[0,0,1]
	v_pk_mul_f32 v[66:67], v[52:53], v[52:53]
	v_pk_mul_f32 v[8:9], v[56:57], v[56:57]
	v_mov_b32_e32 v24, v40
	v_mov_b32_e32 v25, v82
	v_mov_b32_e32 v82, v41
	v_pk_add_f32 v[24:25], v[24:25], v[82:83]
	v_mov_b32_e32 v40, v9
	v_mov_b32_e32 v41, v67
	v_pk_add_f32 v[24:25], v[40:41], v[24:25]
	v_mov_b32_e32 v9, v66
	v_pk_add_f32 v[8:9], v[8:9], v[24:25]
	ds_bpermute_b32 v25, v48, v9
	ds_bpermute_b32 v24, v48, v8
	v_mul_f32_e32 v51, v51, v81
	v_mul_f32_e32 v51, v129, v51
	v_cvt_pk_bf16_f32 v51, v51, s0
	global_store_short v[22:23], v51, off offset:128
	s_waitcnt lgkmcnt(0)
	v_pk_add_f32 v[24:25], v[8:9], v[24:25]
	v_mul_f32_e32 v40, v50, v81
	ds_bpermute_b32 v51, v49, v25
	ds_bpermute_b32 v50, v49, v24
	v_mul_f32_e32 v41, 0x45800000, v96
	v_cndmask_b32_e32 v41, v96, v41, vcc
	v_add_u32_e32 v8, v98, v190
	v_mul_f32_e32 v66, v70, v41
	s_waitcnt lgkmcnt(0)
	v_pk_add_f32 v[24:25], v[24:25], v[50:51]
	ds_bpermute_b32 v51, v64, v25
	ds_bpermute_b32 v50, v64, v24
	v_mad_i64_i32 v[8:9], s[0:1], v8, s78, v[16:17]
	v_mul_f32_e32 v66, v131, v66
	s_nop 0
	v_cvt_pk_bf16_f32 v66, v66, s0
	s_waitcnt lgkmcnt(0)
	v_pk_add_f32 v[24:25], v[24:25], v[50:51]
	ds_bpermute_b32 v51, v65, v25
	ds_bpermute_b32 v50, v65, v24
	global_store_short v[8:9], v66, off
	v_mul_f32_e32 v66, v71, v41
	v_mul_f32_e32 v55, v55, v41
	v_mul_f32_e32 v41, v54, v41
	s_waitcnt lgkmcnt(0)
	v_pk_add_f32 v[24:25], v[24:25], v[50:51]
	ds_bpermute_b32 v51, v80, v25
	ds_bpermute_b32 v50, v80, v24
	v_mul_f32_e32 v66, v130, v66
	v_mul_f32_e32 v55, v129, v55
	v_cvt_pk_bf16_f32 v66, v66, s0
	v_cvt_pk_bf16_f32 v55, v55, s0
	s_waitcnt lgkmcnt(0)
	v_pk_add_f32 v[24:25], v[24:25], v[50:51]
	v_add_u32_e32 v86, 18, v134
	v_pk_fma_f32 v[50:51], v[24:25], s[30:31], v[32:33] op_sel_hi:[1,0,0]
	global_store_short v[8:9], v66, off offset:64
	v_mul_f32_e32 v24, 0x4b800000, v51
	v_cmp_gt_f32_e32 vcc, s81, v51
	v_mov_b32_e32 v66, v74
	v_add_u32_e32 v74, 19, v134
	v_cndmask_b32_e32 v24, v51, v24, vcc
	v_rsq_f32_e32 v51, v24
	v_add_u32_e32 v24, v97, v190
	v_mad_i64_i32 v[24:25], s[0:1], v24, s78, v[16:17]
	v_mul_f32_e32 v54, 0x45800000, v51
	v_cndmask_b32_e32 v81, v51, v54, vcc
	v_mul_f32_e32 v51, v68, v81
	v_mul_f32_e32 v51, v131, v51
	v_cvt_pk_bf16_f32 v51, v51, s0
	global_store_short v[24:25], v51, off
	v_mul_f32_e32 v51, v69, v81
	v_mul_f32_e32 v51, v130, v51
	v_cvt_pk_bf16_f32 v51, v51, s0
	global_store_short v[24:25], v51, off offset:64
	v_mul_f32_e32 v51, v53, v81
	v_mul_f32_e32 v51, v129, v51
	v_cvt_pk_bf16_f32 v53, v51, s0
	v_mul_f32_e32 v51, 0x4b800000, v50
	v_cmp_gt_f32_e32 vcc, s81, v50
	v_mov_b32_e32 v82, v10
	v_and_or_b32 v10, v74, 63, v186
	v_cndmask_b32_e32 v50, v50, v51, vcc
	v_rsq_f32_e32 v85, v50
	v_and_or_b32 v50, v86, 62, v186
	v_lshlrev_b32_e32 v51, 2, v50
	ds_bpermute_b32 v54, v51, v132
	ds_bpermute_b32 v50, v51, v133
	v_mov_b32_e32 v68, v58
	v_mov_b32_e32 v69, v42
	v_mov_b32_e32 v83, v26
	v_lshlrev_b32_e32 v26, 2, v10
	global_store_short v[8:9], v55, off offset:128
	v_mov_b32_e32 v67, v90
	s_waitcnt lgkmcnt(1)
	v_pk_mul_f32 v[68:69], v[68:69], v[54:55] op_sel_hi:[1,0]
	v_mov_b32_e32 v70, v122
	v_mov_b32_e32 v71, v106
	v_pk_mul_f32 v[54:55], v[82:83], v[54:55] op_sel_hi:[1,0]
	ds_bpermute_b32 v10, v26, v132
	s_waitcnt lgkmcnt(1)
	v_pk_fma_f32 v[66:67], v[66:67], v[50:51], v[68:69] op_sel_hi:[1,0,1] neg_lo:[0,0,1] neg_hi:[0,0,1]
	v_pk_fma_f32 v[50:51], v[70:71], v[50:51], v[54:55] op_sel_hi:[1,0,1] neg_lo:[0,0,1] neg_hi:[0,0,1]
	ds_bpermute_b32 v54, v26, v133
	v_mov_b32_e32 v42, v59
	v_mov_b32_e32 v90, v75
	s_waitcnt lgkmcnt(1)
	v_pk_mul_f32 v[42:43], v[42:43], v[10:11] op_sel_hi:[1,0]
	v_mov_b32_e32 v26, v11
	s_waitcnt lgkmcnt(0)
	v_pk_fma_f32 v[42:43], v[90:91], v[54:55], v[42:43] op_sel_hi:[1,0,1] neg_lo:[0,0,1] neg_hi:[0,0,1]
	v_mov_b32_e32 v106, v123
	v_pk_mul_f32 v[10:11], v[26:27], v[10:11] op_sel_hi:[1,0]
	v_pk_mul_f32 v[68:69], v[66:67], v[66:67]
	v_pk_mul_f32 v[58:59], v[42:43], v[42:43]
	v_pk_fma_f32 v[54:55], v[106:107], v[54:55], v[10:11] op_sel_hi:[1,0,1] neg_lo:[0,0,1] neg_hi:[0,0,1]
	v_pk_mul_f32 v[70:71], v[50:51], v[50:51]
	v_pk_mul_f32 v[10:11], v[54:55], v[54:55]
	v_mov_b32_e32 v26, v58
	v_mov_b32_e32 v27, v68
	v_mov_b32_e32 v68, v59
	v_pk_add_f32 v[26:27], v[26:27], v[68:69]
	v_mov_b32_e32 v58, v11
	v_mov_b32_e32 v59, v71
	v_pk_add_f32 v[26:27], v[58:59], v[26:27]
	v_mov_b32_e32 v11, v70
	v_pk_add_f32 v[10:11], v[10:11], v[26:27]
	ds_bpermute_b32 v27, v48, v11
	ds_bpermute_b32 v26, v48, v10
	v_mul_f32_e32 v75, v52, v81
	v_mul_f32_e32 v52, 0x45800000, v85
	global_store_short v[24:25], v53, off offset:128
	v_cndmask_b32_e32 v58, v85, v52, vcc
	s_waitcnt lgkmcnt(0)
; DI u16 f2bf(float a) { return (u16)(pk2(a, 0.f) & 0xffffu); }
; DI int crow(int i, int h) { return (i & 3) + 8 * (i >> 2) + 4 * h; }
; __device__ __forceinline__ void attn_item_A(const Params& p, int layer, int head, int q0u, char* lds) {
;     ...
; #pragma unroll
;   for (int e = 0; e < 16; ++e) {
;     const int qq = crow(e, h_e);
;     const float ia = __shfl(iA, qq), ib = __shfl(iB, qq);
;     float ov[4];
;     float ss = 0.f;
; #pragma unroll
;     for (int d = 0; d < 4; ++d) { ov[d] = o1[d][e] * ia - o2[d][e] * ib; ss += ov[d] * ov[d]; }
; #pragma unroll
;     for (int x = 16; x >= 1; x >>= 1) ss += __shfl_xor(ss, x);
;     const float rs = rsqrtf(ss * (1.f / 128.f) + LN_EPS);
;     const size_t rowoff = (size_t)(orow0 + qq) * LDX + ocol + r_e;
; #pragma unroll
;     for (int d = 0; d < 4; ++d) Mx[rowoff + d * 32] = f2bf(ov[d] * rs * sw[d]);
;   }
	v_pk_add_f32 v[26:27], v[10:11], v[26:27]
	ds_bpermute_b32 v53, v49, v27
	ds_bpermute_b32 v52, v49, v26
	v_add_u32_e32 v10, v84, v190
	v_mul_f32_e32 v59, v72, v58
	v_mad_i64_i32 v[10:11], s[0:1], v10, s78, v[16:17]
	s_waitcnt lgkmcnt(0)
	v_pk_add_f32 v[26:27], v[26:27], v[52:53]
	ds_bpermute_b32 v53, v64, v27
	ds_bpermute_b32 v52, v64, v26
	v_mul_f32_e32 v59, v131, v59
	v_cvt_pk_bf16_f32 v59, v59, s0
	v_mul_f32_e32 v72, v56, v58
	global_store_short v[10:11], v59, off
	s_waitcnt lgkmcnt(0)
	v_pk_add_f32 v[26:27], v[26:27], v[52:53]
	ds_bpermute_b32 v53, v65, v27
	ds_bpermute_b32 v52, v65, v26
	v_mul_f32_e32 v59, v73, v58
	v_mul_f32_e32 v57, v57, v58
	v_mul_f32_e32 v59, v130, v59
	v_mul_f32_e32 v57, v129, v57
	s_waitcnt lgkmcnt(0)
	v_pk_add_f32 v[26:27], v[26:27], v[52:53]
	ds_bpermute_b32 v53, v80, v27
	ds_bpermute_b32 v52, v80, v26
	v_cvt_pk_bf16_f32 v59, v59, s0
	v_cvt_pk_bf16_f32 v57, v57, s0
	v_add_u32_e32 v82, 24, v134
	v_mov_b32_e32 v70, v12
	s_waitcnt lgkmcnt(0)
	v_pk_add_f32 v[26:27], v[26:27], v[52:53]
	v_mov_b32_e32 v71, v28
	v_pk_fma_f32 v[52:53], v[26:27], s[30:31], v[32:33] op_sel_hi:[1,0,0]
	global_store_short v[10:11], v57, off offset:128
	v_mul_f32_e32 v26, 0x4b800000, v53
	v_cmp_gt_f32_e32 vcc, s81, v53
	global_store_short v[10:11], v59, off offset:64
	v_mov_b32_e32 v58, v76
	v_cndmask_b32_e32 v26, v53, v26, vcc
	v_rsq_f32_e32 v53, v26
	v_add_u32_e32 v26, v86, v190
	v_mad_i64_i32 v[26:27], s[0:1], v26, s78, v[16:17]
	v_mul_f32_e32 v56, 0x45800000, v53
	v_cndmask_b32_e32 v73, v53, v56, vcc
	v_mul_f32_e32 v53, v66, v73
	v_mul_f32_e32 v53, v131, v53
	v_cvt_pk_bf16_f32 v53, v53, s0
	global_store_short v[26:27], v53, off
	v_mul_f32_e32 v53, v67, v73
	v_mul_f32_e32 v53, v130, v53
	v_cvt_pk_bf16_f32 v53, v53, s0
	global_store_short v[26:27], v53, off offset:64
	v_mul_f32_e32 v53, 0x4b800000, v52
	v_cmp_gt_f32_e32 vcc, s81, v52
	v_mov_b32_e32 v66, v60
	v_mov_b32_e32 v67, v44
	v_cndmask_b32_e32 v52, v52, v53, vcc
	v_rsq_f32_e32 v81, v52
	v_and_or_b32 v52, v82, 60, v186
	v_lshlrev_b32_e32 v53, 2, v52
	ds_bpermute_b32 v56, v53, v132
	ds_bpermute_b32 v52, v53, v133
	v_mov_b32_e32 v59, v92
	v_mov_b32_e32 v68, v124
	v_mov_b32_e32 v69, v108
	s_waitcnt lgkmcnt(1)
	v_pk_mul_f32 v[66:67], v[66:67], v[56:57] op_sel_hi:[1,0]
	v_pk_mul_f32 v[56:57], v[70:71], v[56:57] op_sel_hi:[1,0]
	v_add_u32_e32 v70, 25, v134
	v_and_or_b32 v12, v70, 61, v186
	v_lshlrev_b32_e32 v28, 2, v12
	ds_bpermute_b32 v12, v28, v132
	s_waitcnt lgkmcnt(1)
	v_pk_fma_f32 v[58:59], v[58:59], v[52:53], v[66:67] op_sel_hi:[1,0,1] neg_lo:[0,0,1] neg_hi:[0,0,1]
	v_pk_fma_f32 v[52:53], v[68:69], v[52:53], v[56:57] op_sel_hi:[1,0,1] neg_lo:[0,0,1] neg_hi:[0,0,1]
	ds_bpermute_b32 v56, v28, v133
	v_mov_b32_e32 v44, v61
	v_mov_b32_e32 v92, v77
	s_waitcnt lgkmcnt(1)
	v_pk_mul_f32 v[44:45], v[44:45], v[12:13] op_sel_hi:[1,0]
	v_mov_b32_e32 v28, v13
	s_waitcnt lgkmcnt(0)
	v_pk_fma_f32 v[44:45], v[92:93], v[56:57], v[44:45] op_sel_hi:[1,0,1] neg_lo:[0,0,1] neg_hi:[0,0,1]
	v_mov_b32_e32 v108, v125
	v_pk_mul_f32 v[12:13], v[28:29], v[12:13] op_sel_hi:[1,0]
	v_pk_mul_f32 v[66:67], v[58:59], v[58:59]
	v_pk_mul_f32 v[60:61], v[44:45], v[44:45]
	v_pk_fma_f32 v[28:29], v[108:109], v[56:57], v[12:13] op_sel_hi:[1,0,1] neg_lo:[0,0,1] neg_hi:[0,0,1]
	v_pk_mul_f32 v[68:69], v[52:53], v[52:53]
	v_pk_mul_f32 v[12:13], v[28:29], v[28:29]
	v_mov_b32_e32 v56, v60
	v_mov_b32_e32 v57, v66
	v_mov_b32_e32 v66, v61
	v_pk_add_f32 v[56:57], v[56:57], v[66:67]
	v_mov_b32_e32 v60, v13
	v_mov_b32_e32 v61, v69
	v_pk_add_f32 v[56:57], v[60:61], v[56:57]
	v_mov_b32_e32 v13, v68
	v_pk_add_f32 v[12:13], v[12:13], v[56:57]
	ds_bpermute_b32 v57, v48, v13
	ds_bpermute_b32 v56, v48, v12
	v_mul_f32_e32 v51, v51, v73
	v_mul_f32_e32 v51, v129, v51
	v_cvt_pk_bf16_f32 v51, v51, s0
	v_mul_f32_e32 v68, v50, v73
	v_mul_f32_e32 v50, 0x45800000, v81
	global_store_short v[26:27], v51, off offset:128
	v_cndmask_b32_e32 v60, v81, v50, vcc
	s_waitcnt lgkmcnt(0)
	v_pk_add_f32 v[50:51], v[12:13], v[56:57]
	ds_bpermute_b32 v57, v49, v51
	ds_bpermute_b32 v56, v49, v50
	v_add_u32_e32 v12, v74, v190
	v_mul_f32_e32 v42, v42, v60
	v_mad_i64_i32 v[12:13], s[0:1], v12, s78, v[16:17]
	s_waitcnt lgkmcnt(0)
	v_pk_add_f32 v[50:51], v[50:51], v[56:57]
	ds_bpermute_b32 v57, v64, v51
	ds_bpermute_b32 v56, v64, v50
	v_mul_f32_e32 v42, v131, v42
	v_cvt_pk_bf16_f32 v42, v42, s0
	global_store_short v[12:13], v42, off
	v_mul_f32_e32 v61, v43, v60
	s_waitcnt lgkmcnt(0)
	v_pk_add_f32 v[42:43], v[50:51], v[56:57]
	ds_bpermute_b32 v51, v65, v43
	ds_bpermute_b32 v50, v65, v42
	v_mul_f32_e32 v69, v54, v60
	v_mul_f32_e32 v55, v55, v60
	v_mul_f32_e32 v56, v130, v61
	v_mul_f32_e32 v55, v129, v55
	s_waitcnt lgkmcnt(0)
	v_pk_add_f32 v[42:43], v[42:43], v[50:51]
	ds_bpermute_b32 v51, v80, v43
	ds_bpermute_b32 v50, v80, v42
	v_cvt_pk_bf16_f32 v56, v56, s0
	v_cvt_pk_bf16_f32 v55, v55, s0
	v_add_u32_e32 v74, 26, v134
	v_add_u32_e32 v76, 27, v134
	s_waitcnt lgkmcnt(0)
	v_pk_add_f32 v[42:43], v[42:43], v[50:51]
	v_mov_b32_e32 v66, v14
	v_pk_fma_f32 v[42:43], v[42:43], s[30:31], v[32:33] op_sel_hi:[1,0,0]
	v_mov_b32_e32 v67, v30
	v_mul_f32_e32 v50, 0x4b800000, v43
	v_cmp_gt_f32_e32 vcc, s81, v43
	v_and_or_b32 v14, v76, 63, v186
	global_store_short v[12:13], v56, off offset:64
	v_cndmask_b32_e32 v43, v43, v50, vcc
	v_rsq_f32_e32 v43, v43
	v_add_u32_e32 v50, v82, v190
	v_mad_i64_i32 v[50:51], s[0:1], v50, s78, v[16:17]
	v_mul_f32_e32 v54, 0x45800000, v43
	v_cndmask_b32_e32 v71, v43, v54, vcc
	v_mul_f32_e32 v43, v58, v71
	v_mul_f32_e32 v43, v131, v43
	v_cvt_pk_bf16_f32 v43, v43, s0
	global_store_short v[50:51], v43, off
	v_mul_f32_e32 v43, v59, v71
	v_mul_f32_e32 v43, v130, v43
	v_cvt_pk_bf16_f32 v43, v43, s0
	global_store_short v[50:51], v43, off offset:64
	v_mul_f32_e32 v43, v53, v71
	v_mul_f32_e32 v43, v129, v43
	v_cvt_pk_bf16_f32 v53, v43, s0
	v_mul_f32_e32 v43, 0x4b800000, v42
	v_cmp_gt_f32_e32 vcc, s81, v42
	v_mov_b32_e32 v58, v62
	v_mov_b32_e32 v59, v46
	v_cndmask_b32_e32 v42, v42, v43, vcc
	v_rsq_f32_e32 v73, v42
	v_and_or_b32 v42, v74, 62, v186
	v_lshlrev_b32_e32 v43, 2, v42
	ds_bpermute_b32 v54, v43, v132
	ds_bpermute_b32 v42, v43, v133
	global_store_short v[12:13], v55, off offset:128
	v_mov_b32_e32 v56, v78
	v_mov_b32_e32 v57, v94
	s_waitcnt lgkmcnt(1)
; DI u16 f2bf(float a) { return (u16)(pk2(a, 0.f) & 0xffffu); }
; DI int crow(int i, int h) { return (i & 3) + 8 * (i >> 2) + 4 * h; }
; __device__ __forceinline__ void attn_item_A(const Params& p, int layer, int head, int q0u, char* lds) {
;     ...
; #pragma unroll
;   for (int e = 0; e < 16; ++e) {
;     const int qq = crow(e, h_e);
;     const float ia = __shfl(iA, qq), ib = __shfl(iB, qq);
;     float ov[4];
;     float ss = 0.f;
; #pragma unroll
;     for (int d = 0; d < 4; ++d) { ov[d] = o1[d][e] * ia - o2[d][e] * ib; ss += ov[d] * ov[d]; }
; #pragma unroll
;     for (int x = 16; x >= 1; x >>= 1) ss += __shfl_xor(ss, x);
;     const float rs = rsqrtf(ss * (1.f / 128.f) + LN_EPS);
;     const size_t rowoff = (size_t)(orow0 + qq) * LDX + ocol + r_e;
; #pragma unroll
;     for (int d = 0; d < 4; ++d) Mx[rowoff + d * 32] = f2bf(ov[d] * rs * sw[d]);
;   }
	v_pk_mul_f32 v[58:59], v[58:59], v[54:55] op_sel_hi:[1,0]
	v_mov_b32_e32 v60, v126
	v_mov_b32_e32 v61, v110
	v_pk_mul_f32 v[54:55], v[66:67], v[54:55] op_sel_hi:[1,0]
	v_lshlrev_b32_e32 v14, 2, v14
	s_waitcnt lgkmcnt(0)
	v_pk_fma_f32 v[56:57], v[56:57], v[42:43], v[58:59] op_sel_hi:[1,0,1] neg_lo:[0,0,1] neg_hi:[0,0,1]
	v_pk_fma_f32 v[42:43], v[60:61], v[42:43], v[54:55] op_sel_hi:[1,0,1] neg_lo:[0,0,1] neg_hi:[0,0,1]
	ds_bpermute_b32 v55, v14, v132
	ds_bpermute_b32 v54, v14, v133
	v_mov_b32_e32 v46, v63
	v_mov_b32_e32 v94, v79
	v_pk_mul_f32 v[58:59], v[56:57], v[56:57]
	s_waitcnt lgkmcnt(1)
	v_mov_b32_e32 v14, v55
	v_pk_mul_f32 v[46:47], v[46:47], v[14:15] op_sel_hi:[1,0]
	v_mov_b32_e32 v14, v127
	s_waitcnt lgkmcnt(0)
	v_pk_mul_f32 v[14:15], v[14:15], v[54:55]
	v_pk_fma_f32 v[46:47], v[94:95], v[54:55], v[46:47] op_sel_hi:[1,0,1] neg_lo:[0,0,1] neg_hi:[0,0,1]
	v_mul_f32_e32 v67, v111, v54
	v_mul_f32_e32 v31, v31, v55
	v_mov_b32_e32 v66, v14
	v_mov_b32_e32 v30, v15
	v_pk_mul_f32 v[62:63], v[46:47], v[46:47]
	v_pk_add_f32 v[14:15], v[66:67], v[30:31] neg_lo:[0,1] neg_hi:[0,1]
	v_pk_mul_f32 v[60:61], v[42:43], v[42:43]
	v_pk_mul_f32 v[30:31], v[14:15], v[14:15]
	v_mov_b32_e32 v54, v62
	v_mov_b32_e32 v55, v58
	v_mov_b32_e32 v58, v63
	v_pk_add_f32 v[54:55], v[54:55], v[58:59]
	v_mov_b32_e32 v58, v31
	v_mov_b32_e32 v59, v61
	v_pk_add_f32 v[54:55], v[58:59], v[54:55]
	v_mov_b32_e32 v31, v60
	v_pk_add_f32 v[30:31], v[30:31], v[54:55]
	ds_bpermute_b32 v55, v48, v31
	ds_bpermute_b32 v54, v48, v30
	global_store_short v[50:51], v53, off offset:128
	v_mul_f32_e32 v58, v52, v71
	v_mul_f32_e32 v48, 0x45800000, v73
	v_cndmask_b32_e32 v59, v73, v48, vcc
	s_waitcnt lgkmcnt(0)
	v_pk_add_f32 v[30:31], v[30:31], v[54:55]
	ds_bpermute_b32 v53, v49, v31
	ds_bpermute_b32 v52, v49, v30
	v_add_u32_e32 v48, v70, v190
	v_mul_f32_e32 v44, v44, v59
	v_mad_i64_i32 v[48:49], s[0:1], v48, s78, v[16:17]
	s_waitcnt lgkmcnt(0)
	v_pk_add_f32 v[30:31], v[30:31], v[52:53]
	ds_bpermute_b32 v53, v64, v31
	ds_bpermute_b32 v52, v64, v30
	v_mul_f32_e32 v44, v131, v44
	v_cvt_pk_bf16_f32 v44, v44, s0
	global_store_short v[48:49], v44, off
	v_mul_f32_e32 v54, v45, v59
	s_waitcnt lgkmcnt(0)
	v_pk_add_f32 v[30:31], v[30:31], v[52:53]
	ds_bpermute_b32 v45, v65, v31
	ds_bpermute_b32 v44, v65, v30
	v_mul_f32_e32 v29, v29, v59
	v_mul_f32_e32 v52, v130, v54
	v_mul_f32_e32 v29, v129, v29
	v_cvt_pk_bf16_f32 v52, v52, s0
	s_waitcnt lgkmcnt(0)
	v_pk_add_f32 v[30:31], v[30:31], v[44:45]
	ds_bpermute_b32 v45, v80, v31
	ds_bpermute_b32 v44, v80, v30
	v_cvt_pk_bf16_f32 v29, v29, s0
	global_store_short v[48:49], v52, off offset:64
	global_store_short v[48:49], v29, off offset:128
	v_mul_f32_e32 v52, v28, v59
	s_waitcnt lgkmcnt(0)
	v_pk_add_f32 v[28:29], v[30:31], v[44:45]
	s_nop 0
	v_pk_fma_f32 v[28:29], v[28:29], s[30:31], v[32:33] op_sel_hi:[1,0,0]
	s_nop 0
	v_mul_f32_e32 v30, 0x4b800000, v29
	v_cmp_gt_f32_e32 vcc, s81, v29
	v_mul_f32_e32 v33, 0x4b800000, v28
	s_nop 0
	v_cndmask_b32_e32 v29, v29, v30, vcc
	v_rsq_f32_e32 v29, v29
	v_add_u32_e32 v30, v74, v190
	v_mad_i64_i32 v[30:31], s[0:1], v30, s78, v[16:17]
	v_mul_f32_e32 v32, 0x45800000, v29
	v_cndmask_b32_e32 v29, v29, v32, vcc
	v_mul_f32_e32 v32, v56, v29
	v_mul_f32_e32 v32, v131, v32
	v_cvt_pk_bf16_f32 v32, v32, s0
	global_store_short v[30:31], v32, off
	v_mul_f32_e32 v32, v57, v29
	v_cmp_gt_f32_e32 vcc, s81, v28
	v_mul_f32_e32 v32, v130, v32
	v_cvt_pk_bf16_f32 v32, v32, s0
	v_cndmask_b32_e32 v28, v28, v33, vcc
	v_rsq_f32_e32 v28, v28
	global_store_short v[30:31], v32, off offset:64
	v_mul_f32_e32 v32, v43, v29
	v_mul_f32_e32 v32, v129, v32
	v_cvt_pk_bf16_f32 v32, v32, s0
	global_store_short v[30:31], v32, off offset:128
	v_mul_f32_e32 v32, 0x45800000, v28
	v_cndmask_b32_e32 v167, v28, v32, vcc
	v_add_u32_e32 v28, v76, v190
	v_mad_i64_i32 v[16:17], s[0:1], v28, s78, v[16:17]
	v_mul_f32_e32 v28, v46, v167
	v_mul_f32_e32 v28, v131, v28
	v_cvt_pk_bf16_f32 v28, v28, s0
	v_mul_f32_e32 v15, v15, v167
	global_store_short v[16:17], v28, off
	v_mul_f32_e32 v28, v47, v167
	v_mul_f32_e32 v15, v129, v15
	v_mul_f32_e32 v28, v130, v28
	v_cvt_pk_bf16_f32 v15, v15, s0
	v_mov_b32_e32 v129, v14
	v_cvt_pk_bf16_f32 v28, v28, s0
	global_store_short v[16:17], v15, off offset:128
	s_waitcnt vmcnt(47)
	v_pk_mul_f32 v[14:15], v[128:129], v[166:167]
	global_store_short v[16:17], v28, off offset:64
	v_mul_f32_e32 v28, v14, v34
	v_cvt_pk_bf16_f32 v28, v28, s0
	global_store_short v[0:1], v28, off offset:192
	v_mul_f32_e32 v0, v14, v35
	v_cvt_pk_bf16_f32 v0, v0, s0
	global_store_short v[2:3], v0, off offset:192
	v_mul_f32_e32 v0, v14, v36
	v_cvt_pk_bf16_f32 v0, v0, s0
	global_store_short v[18:19], v0, off offset:192
	v_mul_f32_e32 v0, v14, v37
	v_cvt_pk_bf16_f32 v0, v0, s0
	global_store_short v[4:5], v0, off offset:192
	v_mul_f32_e32 v0, v14, v38
	v_cvt_pk_bf16_f32 v0, v0, s0
	global_store_short v[20:21], v0, off offset:192
	v_mul_f32_e32 v0, v14, v39
	v_cvt_pk_bf16_f32 v0, v0, s0
	global_store_short v[6:7], v0, off offset:192
	v_mul_f32_e32 v0, v14, v40
	v_cvt_pk_bf16_f32 v0, v0, s0
	global_store_short v[22:23], v0, off offset:192
	v_mul_f32_e32 v0, v14, v41
	v_cvt_pk_bf16_f32 v0, v0, s0
	global_store_short v[8:9], v0, off offset:192
	v_mul_f32_e32 v0, v14, v75
	v_cvt_pk_bf16_f32 v0, v0, s0
	global_store_short v[24:25], v0, off offset:192
	v_mul_f32_e32 v0, v14, v72
	v_cvt_pk_bf16_f32 v0, v0, s0
	global_store_short v[10:11], v0, off offset:192
	v_mul_f32_e32 v0, v14, v68
	v_cvt_pk_bf16_f32 v0, v0, s0
	global_store_short v[26:27], v0, off offset:192
	v_mul_f32_e32 v0, v14, v69
	v_cvt_pk_bf16_f32 v0, v0, s0
	global_store_short v[12:13], v0, off offset:192
	v_mul_f32_e32 v0, v14, v58
	v_cvt_pk_bf16_f32 v0, v0, s0
	global_store_short v[50:51], v0, off offset:192
	v_mul_f32_e32 v0, v14, v52
	v_mul_f32_e32 v29, v42, v29
	v_cvt_pk_bf16_f32 v0, v0, s0
	global_store_short v[48:49], v0, off offset:192
	v_mul_f32_e32 v0, v14, v29
	v_cvt_pk_bf16_f32 v0, v0, s0
	global_store_short v[30:31], v0, off offset:192
	v_mul_f32_e32 v0, v14, v15
	s_branch .LBB0_2240
